# GEMM units: acc zero-init removed, first K-iteration peeled with C=0 MFMAs
# speedup vs baseline: 1.0171x; 1.0069x over previous
.LBB0_353:
	s_lshl_b64 s[2:3], s[14:15], 1
	v_readlane_b32 s20, v253, 52
	v_readlane_b32 s21, v253, 53
	s_add_u32 s20, s20, s2
	s_addc_u32 s21, s21, s3
	s_and_b64 s[2:3], s[18:19], exec
	s_cselect_b32 s11, s21, s27
	s_cselect_b32 s13, s20, s26
	s_lshl_b64 s[2:3], s[16:17], 1
	s_add_u32 s22, s48, s2
	s_addc_u32 s23, s49, s3
	s_and_b64 s[2:3], s[18:19], exec
	s_cselect_b32 s44, s23, s29
	s_cselect_b32 s45, s22, s28
	s_add_u32 s26, s26, 0x40080
	s_addc_u32 s27, s27, 0
	s_add_u32 s46, s28, 0x100
	s_addc_u32 s47, s29, 0
	s_mov_b32 s52, -2
.Lpk354_peel:
	ds_read_b128 v[166:169], v139
	ds_read_b128 v[170:173], v139 offset:1024
	ds_read_b128 v[178:181], v139 offset:2048
	ds_read_b128 v[182:185], v139 offset:3072
	ds_read_b128 v[186:189], v164
	ds_read_b128 v[190:193], v164 offset:1024
	ds_read_b128 v[194:197], v164 offset:2048
	ds_read_b128 v[198:201], v164 offset:3072
	s_add_u32 s2, s26, 0xfffc0080
	s_addc_u32 s3, s27, -1
	s_cmp_eq_u32 s52, 12
	s_cselect_b32 s3, s11, s3
	s_cselect_b32 s2, s13, s2
	s_cselect_b32 s29, s44, s47
	s_cselect_b32 s28, s45, s46
	v_lshl_add_u64 v[148:149], s[26:27], 0, v[142:143]
	s_add_i32 m0, s34, 0xc000
	ds_read_b128 v[202:205], v165
	ds_read_b128 v[206:209], v165 offset:1024
	ds_read_b128 v[210:213], v165 offset:2048
	ds_read_b128 v[214:217], v165 offset:3072
	ds_read_b128 v[218:221], v165 offset:4096
	ds_read_b128 v[222:225], v165 offset:5120
	ds_read_b128 v[226:229], v165 offset:6144
	ds_read_b128 v[230:233], v165 offset:7168
	global_load_lds_dwordx4 v[148:149], off
	v_lshl_add_u64 v[148:149], s[26:27], 0, v[144:145]
	s_add_i32 m0, s34, 0xe000
	s_nop 0
	global_load_lds_dwordx4 v[148:149], off
	s_waitcnt vmcnt(8)
	s_waitcnt lgkmcnt(0)
	s_barrier
	s_setprio 1
	s_waitcnt lgkmcnt(0)
	v_mfma_f32_16x16x32_bf16 v[126:129], v[166:169], v[202:205], 0
	v_mfma_f32_16x16x32_bf16 v[122:125], v[178:181], v[202:205], 0
	v_mfma_f32_16x16x32_bf16 v[110:113], v[166:169], v[210:213], 0
	v_mfma_f32_16x16x32_bf16 v[106:109], v[178:181], v[210:213], 0
	v_mfma_f32_16x16x32_bf16 v[94:97], v[166:169], v[218:221], 0
	v_mfma_f32_16x16x32_bf16 v[90:93], v[178:181], v[218:221], 0
	v_mfma_f32_16x16x32_bf16 v[78:81], v[166:169], v[226:229], 0
	v_mfma_f32_16x16x32_bf16 v[74:77], v[178:181], v[226:229], 0
	v_mfma_f32_16x16x32_bf16 v[126:129], v[170:173], v[206:209], v[126:129]
	v_mfma_f32_16x16x32_bf16 v[122:125], v[182:185], v[206:209], v[122:125]
	v_mfma_f32_16x16x32_bf16 v[110:113], v[170:173], v[214:217], v[110:113]
	v_mfma_f32_16x16x32_bf16 v[106:109], v[182:185], v[214:217], v[106:109]
	v_mfma_f32_16x16x32_bf16 v[94:97], v[170:173], v[222:225], v[94:97]
	v_mfma_f32_16x16x32_bf16 v[90:93], v[182:185], v[222:225], v[90:93]
	v_mfma_f32_16x16x32_bf16 v[78:81], v[170:173], v[230:233], v[78:81]
	v_mfma_f32_16x16x32_bf16 v[74:77], v[182:185], v[230:233], v[74:77]
	s_setprio 0
	s_setprio 1
	v_mfma_f32_16x16x32_bf16 v[118:121], v[186:189], v[202:205], 0
	v_mfma_f32_16x16x32_bf16 v[114:117], v[194:197], v[202:205], 0
	v_mfma_f32_16x16x32_bf16 v[102:105], v[186:189], v[210:213], 0
	v_mfma_f32_16x16x32_bf16 v[98:101], v[194:197], v[210:213], 0
	v_mfma_f32_16x16x32_bf16 v[86:89], v[186:189], v[218:221], 0
	v_mfma_f32_16x16x32_bf16 v[82:85], v[194:197], v[218:221], 0
	v_mfma_f32_16x16x32_bf16 v[70:73], v[186:189], v[226:229], 0
	v_mfma_f32_16x16x32_bf16 v[66:69], v[194:197], v[226:229], 0
	v_mfma_f32_16x16x32_bf16 v[118:121], v[190:193], v[206:209], v[118:121]
	v_mfma_f32_16x16x32_bf16 v[114:117], v[198:201], v[206:209], v[114:117]
	v_mfma_f32_16x16x32_bf16 v[102:105], v[190:193], v[214:217], v[102:105]
	v_mfma_f32_16x16x32_bf16 v[98:101], v[198:201], v[214:217], v[98:101]
	v_mfma_f32_16x16x32_bf16 v[86:89], v[190:193], v[222:225], v[86:89]
	v_mfma_f32_16x16x32_bf16 v[82:85], v[198:201], v[222:225], v[82:85]
	v_mfma_f32_16x16x32_bf16 v[70:73], v[190:193], v[230:233], v[70:73]
	v_mfma_f32_16x16x32_bf16 v[66:69], v[198:201], v[230:233], v[66:69]
	s_setprio 0
	s_barrier
	s_add_i32 s53, s41, s30
	v_lshl_add_u64 v[148:149], s[28:29], 0, v[132:133]
	s_mov_b32 m0, s53
	ds_read_b128 v[202:205], v165 offset:16384
	ds_read_b128 v[206:209], v165 offset:17408
	ds_read_b128 v[210:213], v165 offset:18432
	ds_read_b128 v[214:217], v165 offset:19456
	ds_read_b128 v[218:221], v165 offset:20480
	ds_read_b128 v[222:225], v165 offset:21504
	ds_read_b128 v[226:229], v165 offset:22528
	ds_read_b128 v[230:233], v165 offset:23552
	global_load_lds_dwordx4 v[148:149], off
	s_add_i32 m0, s53, 0x2000
	s_add_u32 s54, s28, 0x40000
	v_lshl_add_u64 v[174:175], s[28:29], 0, v[136:137]
	s_addc_u32 s55, s29, 0
	s_add_i32 s53, s42, s30
	global_load_lds_dwordx4 v[174:175], off
	v_lshl_add_u64 v[234:235], s[54:55], 0, v[132:133]
	s_mov_b32 m0, s53
	v_lshl_add_u64 v[236:237], s[2:3], 0, v[134:135]
	global_load_lds_dwordx4 v[234:235], off
	v_lshl_add_u64 v[234:235], s[54:55], 0, v[136:137]
	s_add_i32 m0, s53, 0x2000
	s_nop 0
	global_load_lds_dwordx4 v[234:235], off
	v_lshl_add_u64 v[234:235], s[2:3], 0, v[130:131]
	s_mov_b32 m0, s34
	s_nop 0
	global_load_lds_dwordx4 v[234:235], off
	s_mov_b32 m0, s25
	s_nop 0
	global_load_lds_dwordx4 v[236:237], off
	s_waitcnt vmcnt(8)
	s_waitcnt lgkmcnt(0)
	s_barrier
	s_setprio 1
	s_waitcnt lgkmcnt(0)
	v_mfma_f32_16x16x32_bf16 v[62:65], v[166:169], v[202:205], 0
	v_mfma_f32_16x16x32_bf16 v[58:61], v[178:181], v[202:205], 0
	v_mfma_f32_16x16x32_bf16 v[46:49], v[166:169], v[210:213], 0
	v_mfma_f32_16x16x32_bf16 v[42:45], v[178:181], v[210:213], 0
	v_mfma_f32_16x16x32_bf16 v[30:33], v[166:169], v[218:221], 0
	v_mfma_f32_16x16x32_bf16 v[26:29], v[178:181], v[218:221], 0
	v_mfma_f32_16x16x32_bf16 v[14:17], v[166:169], v[226:229], 0
	v_mfma_f32_16x16x32_bf16 v[10:13], v[178:181], v[226:229], 0
	v_mfma_f32_16x16x32_bf16 v[62:65], v[170:173], v[206:209], v[62:65]
	v_mfma_f32_16x16x32_bf16 v[58:61], v[182:185], v[206:209], v[58:61]
	v_mfma_f32_16x16x32_bf16 v[46:49], v[170:173], v[214:217], v[46:49]
	v_mfma_f32_16x16x32_bf16 v[42:45], v[182:185], v[214:217], v[42:45]
	v_mfma_f32_16x16x32_bf16 v[30:33], v[170:173], v[222:225], v[30:33]
	v_mfma_f32_16x16x32_bf16 v[26:29], v[182:185], v[222:225], v[26:29]
	v_mfma_f32_16x16x32_bf16 v[14:17], v[170:173], v[230:233], v[14:17]
	v_mfma_f32_16x16x32_bf16 v[10:13], v[182:185], v[230:233], v[10:13]
	s_setprio 0
	s_setprio 1
	v_mfma_f32_16x16x32_bf16 v[54:57], v[186:189], v[202:205], 0
	v_mfma_f32_16x16x32_bf16 v[50:53], v[194:197], v[202:205], 0
	v_mfma_f32_16x16x32_bf16 v[38:41], v[186:189], v[210:213], 0
	v_mfma_f32_16x16x32_bf16 v[34:37], v[194:197], v[210:213], 0
	v_mfma_f32_16x16x32_bf16 v[22:25], v[186:189], v[218:221], 0
	v_mfma_f32_16x16x32_bf16 v[18:21], v[194:197], v[218:221], 0
	v_mfma_f32_16x16x32_bf16 v[6:9], v[186:189], v[226:229], 0
	v_mfma_f32_16x16x32_bf16 v[2:5], v[194:197], v[226:229], 0
	v_mfma_f32_16x16x32_bf16 v[54:57], v[190:193], v[206:209], v[54:57]
	v_mfma_f32_16x16x32_bf16 v[50:53], v[198:201], v[206:209], v[50:53]
	v_mfma_f32_16x16x32_bf16 v[38:41], v[190:193], v[214:217], v[38:41]
	v_mfma_f32_16x16x32_bf16 v[34:37], v[198:201], v[214:217], v[34:37]
	v_mfma_f32_16x16x32_bf16 v[22:25], v[190:193], v[222:225], v[22:25]
	v_mfma_f32_16x16x32_bf16 v[18:21], v[198:201], v[222:225], v[18:21]
	v_mfma_f32_16x16x32_bf16 v[6:9], v[190:193], v[230:233], v[6:9]
	v_mfma_f32_16x16x32_bf16 v[2:5], v[198:201], v[230:233], v[2:5]
	s_setprio 0
	s_barrier
	s_add_i32 s53, 0, 0x18000
	v_add_u32_e32 v176, s53, v163
	s_add_i32 s54, 0, 0x1c000
	ds_read_b128 v[166:169], v176
	ds_read_b128 v[170:173], v176 offset:1024
	ds_read_b128 v[178:181], v176 offset:2048
	ds_read_b128 v[182:185], v176 offset:3072
	v_add_u32_e32 v176, s54, v163
	ds_read_b128 v[186:189], v176
	ds_read_b128 v[190:193], v176 offset:1024
	ds_read_b128 v[194:197], v176 offset:2048
	ds_read_b128 v[198:201], v176 offset:3072
	s_add_u32 s2, s2, 0x40000
	s_addc_u32 s3, s3, 0
	s_mov_b32 m0, s35
	v_lshl_add_u64 v[238:239], s[2:3], 0, v[130:131]
	ds_read_b128 v[202:205], v165 offset:32768
	ds_read_b128 v[206:209], v165 offset:33792
	ds_read_b128 v[210:213], v165 offset:34816
	ds_read_b128 v[214:217], v165 offset:35840
	ds_read_b128 v[218:221], v165 offset:36864
	ds_read_b128 v[222:225], v165 offset:37888
	ds_read_b128 v[226:229], v165 offset:38912
	ds_read_b128 v[230:233], v165 offset:39936
	global_load_lds_dwordx4 v[238:239], off
	v_lshl_add_u64 v[238:239], s[2:3], 0, v[134:135]
	s_mov_b32 m0, s36
	s_nop 0
	global_load_lds_dwordx4 v[238:239], off
	s_waitcnt vmcnt(8)
	s_waitcnt lgkmcnt(0)
	s_barrier
	s_setprio 1
	s_waitcnt lgkmcnt(0)
	v_mfma_f32_16x16x32_bf16 v[126:129], v[166:169], v[202:205], v[126:129]
	v_mfma_f32_16x16x32_bf16 v[122:125], v[178:181], v[202:205], v[122:125]
	v_mfma_f32_16x16x32_bf16 v[110:113], v[166:169], v[210:213], v[110:113]
	v_mfma_f32_16x16x32_bf16 v[106:109], v[178:181], v[210:213], v[106:109]
	v_mfma_f32_16x16x32_bf16 v[94:97], v[166:169], v[218:221], v[94:97]
	v_mfma_f32_16x16x32_bf16 v[90:93], v[178:181], v[218:221], v[90:93]
	v_mfma_f32_16x16x32_bf16 v[78:81], v[166:169], v[226:229], v[78:81]
	v_mfma_f32_16x16x32_bf16 v[74:77], v[178:181], v[226:229], v[74:77]
	v_mfma_f32_16x16x32_bf16 v[126:129], v[170:173], v[206:209], v[126:129]
	v_mfma_f32_16x16x32_bf16 v[122:125], v[182:185], v[206:209], v[122:125]
	v_mfma_f32_16x16x32_bf16 v[110:113], v[170:173], v[214:217], v[110:113]
	v_mfma_f32_16x16x32_bf16 v[106:109], v[182:185], v[214:217], v[106:109]
	v_mfma_f32_16x16x32_bf16 v[94:97], v[170:173], v[222:225], v[94:97]
	v_mfma_f32_16x16x32_bf16 v[90:93], v[182:185], v[222:225], v[90:93]
	v_mfma_f32_16x16x32_bf16 v[78:81], v[170:173], v[230:233], v[78:81]
	v_mfma_f32_16x16x32_bf16 v[74:77], v[182:185], v[230:233], v[74:77]
	s_setprio 0
	s_setprio 1
	v_mfma_f32_16x16x32_bf16 v[118:121], v[186:189], v[202:205], v[118:121]
	v_mfma_f32_16x16x32_bf16 v[114:117], v[194:197], v[202:205], v[114:117]
	v_mfma_f32_16x16x32_bf16 v[102:105], v[186:189], v[210:213], v[102:105]
	v_mfma_f32_16x16x32_bf16 v[98:101], v[194:197], v[210:213], v[98:101]
	v_mfma_f32_16x16x32_bf16 v[86:89], v[186:189], v[218:221], v[86:89]
	v_mfma_f32_16x16x32_bf16 v[82:85], v[194:197], v[218:221], v[82:85]
	v_mfma_f32_16x16x32_bf16 v[70:73], v[186:189], v[226:229], v[70:73]
	v_mfma_f32_16x16x32_bf16 v[66:69], v[194:197], v[226:229], v[66:69]
	v_mfma_f32_16x16x32_bf16 v[118:121], v[190:193], v[206:209], v[118:121]
	v_mfma_f32_16x16x32_bf16 v[114:117], v[198:201], v[206:209], v[114:117]
	v_mfma_f32_16x16x32_bf16 v[102:105], v[190:193], v[214:217], v[102:105]
	v_mfma_f32_16x16x32_bf16 v[98:101], v[198:201], v[214:217], v[98:101]
	v_mfma_f32_16x16x32_bf16 v[86:89], v[190:193], v[222:225], v[86:89]
	v_mfma_f32_16x16x32_bf16 v[82:85], v[198:201], v[222:225], v[82:85]
	v_mfma_f32_16x16x32_bf16 v[70:73], v[190:193], v[230:233], v[70:73]
	v_mfma_f32_16x16x32_bf16 v[66:69], v[198:201], v[230:233], v[66:69]
	s_setprio 0
	s_barrier
	s_add_i32 s2, s53, s30
	v_lshl_add_u64 v[148:149], v[148:149], 0, s[6:7]
	s_mov_b32 m0, s2
	ds_read_b128 v[202:205], v165 offset:49152
	ds_read_b128 v[206:209], v165 offset:50176
	ds_read_b128 v[210:213], v165 offset:51200
	ds_read_b128 v[214:217], v165 offset:52224
	ds_read_b128 v[218:221], v165 offset:53248
	ds_read_b128 v[222:225], v165 offset:54272
	ds_read_b128 v[226:229], v165 offset:55296
	ds_read_b128 v[230:233], v165 offset:56320
	global_load_lds_dwordx4 v[148:149], off
	s_add_i32 m0, s2, 0x2000
	s_add_u32 s2, s28, 0x40080
	v_lshl_add_u64 v[148:149], v[174:175], 0, s[6:7]
	s_addc_u32 s3, s29, 0
	s_add_i32 s28, s54, s30
	global_load_lds_dwordx4 v[148:149], off
	v_lshl_add_u64 v[148:149], s[2:3], 0, v[132:133]
	s_mov_b32 m0, s28
	s_nop 0
	global_load_lds_dwordx4 v[148:149], off
	v_lshl_add_u64 v[148:149], s[2:3], 0, v[136:137]
	s_add_i32 m0, s28, 0x2000
	s_nop 0
	global_load_lds_dwordx4 v[148:149], off
	v_lshl_add_u64 v[148:149], v[234:235], 0, s[6:7]
	s_mov_b32 m0, s38
	s_nop 0
	global_load_lds_dwordx4 v[148:149], off
	v_lshl_add_u64 v[148:149], v[236:237], 0, s[6:7]
	s_mov_b32 m0, s39
	s_nop 0
	global_load_lds_dwordx4 v[148:149], off
	s_waitcnt vmcnt(8)
	s_waitcnt lgkmcnt(0)
	s_barrier
	s_setprio 1
	s_waitcnt lgkmcnt(0)
	v_mfma_f32_16x16x32_bf16 v[62:65], v[166:169], v[202:205], v[62:65]
	v_mfma_f32_16x16x32_bf16 v[58:61], v[178:181], v[202:205], v[58:61]
	v_mfma_f32_16x16x32_bf16 v[46:49], v[166:169], v[210:213], v[46:49]
	v_mfma_f32_16x16x32_bf16 v[42:45], v[178:181], v[210:213], v[42:45]
	v_mfma_f32_16x16x32_bf16 v[30:33], v[166:169], v[218:221], v[30:33]
	v_mfma_f32_16x16x32_bf16 v[26:29], v[178:181], v[218:221], v[26:29]
	v_mfma_f32_16x16x32_bf16 v[14:17], v[166:169], v[226:229], v[14:17]
	v_mfma_f32_16x16x32_bf16 v[10:13], v[178:181], v[226:229], v[10:13]
	v_mfma_f32_16x16x32_bf16 v[62:65], v[170:173], v[206:209], v[62:65]
	v_mfma_f32_16x16x32_bf16 v[58:61], v[182:185], v[206:209], v[58:61]
	v_mfma_f32_16x16x32_bf16 v[46:49], v[170:173], v[214:217], v[46:49]
	v_mfma_f32_16x16x32_bf16 v[42:45], v[182:185], v[214:217], v[42:45]
	v_mfma_f32_16x16x32_bf16 v[30:33], v[170:173], v[222:225], v[30:33]
	v_mfma_f32_16x16x32_bf16 v[26:29], v[182:185], v[222:225], v[26:29]
	v_mfma_f32_16x16x32_bf16 v[14:17], v[170:173], v[230:233], v[14:17]
	v_mfma_f32_16x16x32_bf16 v[10:13], v[182:185], v[230:233], v[10:13]
	s_setprio 0
	s_setprio 1
	v_mfma_f32_16x16x32_bf16 v[54:57], v[186:189], v[202:205], v[54:57]
	v_mfma_f32_16x16x32_bf16 v[50:53], v[194:197], v[202:205], v[50:53]
	v_mfma_f32_16x16x32_bf16 v[38:41], v[186:189], v[210:213], v[38:41]
	v_mfma_f32_16x16x32_bf16 v[34:37], v[194:197], v[210:213], v[34:37]
	v_mfma_f32_16x16x32_bf16 v[22:25], v[186:189], v[218:221], v[22:25]
	v_mfma_f32_16x16x32_bf16 v[18:21], v[194:197], v[218:221], v[18:21]
	v_mfma_f32_16x16x32_bf16 v[6:9], v[186:189], v[226:229], v[6:9]
	v_mfma_f32_16x16x32_bf16 v[2:5], v[194:197], v[226:229], v[2:5]
	v_mfma_f32_16x16x32_bf16 v[54:57], v[190:193], v[206:209], v[54:57]
	v_mfma_f32_16x16x32_bf16 v[50:53], v[198:201], v[206:209], v[50:53]
	v_mfma_f32_16x16x32_bf16 v[38:41], v[190:193], v[214:217], v[38:41]
	v_mfma_f32_16x16x32_bf16 v[34:37], v[198:201], v[214:217], v[34:37]
	v_mfma_f32_16x16x32_bf16 v[22:25], v[190:193], v[222:225], v[22:25]
	v_mfma_f32_16x16x32_bf16 v[18:21], v[198:201], v[222:225], v[18:21]
	v_mfma_f32_16x16x32_bf16 v[6:9], v[190:193], v[230:233], v[6:9]
	v_mfma_f32_16x16x32_bf16 v[2:5], v[198:201], v[230:233], v[2:5]
	s_setprio 0
	s_barrier
	s_add_i32 s52, s52, 2
	s_add_u32 s26, s26, 0x100
	s_addc_u32 s27, s27, 0
	s_add_u32 s46, s46, 0x100
	s_addc_u32 s47, s47, 0
	s_cmp_gt_u32 s52, 13
	s_cbranch_scc0 .LBB0_354
	s_branch .Lpk354_exit

.Lpk354_exit:
	s_and_b64 vcc, exec, s[8:9]
	s_cbranch_vccz .LBB0_357
	s_barrier

.LBB0_450:
	s_lshl_b64 s[2:3], s[14:15], 1
	v_readlane_b32 s20, v253, 52
	v_readlane_b32 s21, v253, 53
	s_add_u32 s20, s20, s2
	s_addc_u32 s21, s21, s3
	s_and_b64 s[2:3], s[18:19], exec
	s_cselect_b32 s11, s21, s29
	s_cselect_b32 s13, s20, s28
	s_lshl_b64 s[2:3], s[16:17], 1
	s_add_u32 s22, s48, s2
	s_addc_u32 s23, s49, s3
	s_and_b64 s[2:3], s[18:19], exec
	s_cselect_b32 s44, s23, s31
	s_cselect_b32 s45, s22, s30
	s_add_u32 s28, s28, 0x40080
	s_addc_u32 s29, s29, 0
	s_add_u32 s46, s30, 0x100
	s_addc_u32 s47, s31, 0
	s_mov_b32 s52, -2
.Lpk451_peel:
	ds_read_b128 v[152:155], v149
	ds_read_b128 v[156:159], v149 offset:1024
	ds_read_b128 v[160:163], v149 offset:2048
	ds_read_b128 v[164:167], v149 offset:3072
	ds_read_b128 v[168:171], v150
	ds_read_b128 v[172:175], v150 offset:1024
	ds_read_b128 v[178:181], v150 offset:2048
	ds_read_b128 v[182:185], v150 offset:3072
	s_add_u32 s2, s28, 0xfffc0080
	s_addc_u32 s3, s29, -1
	s_cmp_eq_u32 s52, 12
	s_cselect_b32 s3, s11, s3
	s_cselect_b32 s2, s13, s2
	s_cselect_b32 s31, s44, s47
	s_cselect_b32 s30, s45, s46
	v_lshl_add_u64 v[146:147], s[28:29], 0, v[140:141]
	s_add_i32 m0, s25, 0xc000
	ds_read_b128 v[186:189], v151
	ds_read_b128 v[190:193], v151 offset:1024
	ds_read_b128 v[194:197], v151 offset:2048
	ds_read_b128 v[198:201], v151 offset:3072
	ds_read_b128 v[202:205], v151 offset:4096
	ds_read_b128 v[206:209], v151 offset:5120
	ds_read_b128 v[210:213], v151 offset:6144
	ds_read_b128 v[214:217], v151 offset:7168
	global_load_lds_dwordx4 v[146:147], off
	v_lshl_add_u64 v[146:147], s[28:29], 0, v[142:143]
	s_add_i32 m0, s25, 0xe000
	s_nop 0
	global_load_lds_dwordx4 v[146:147], off
	s_waitcnt vmcnt(8)
	s_waitcnt lgkmcnt(0)
	s_barrier
	s_setprio 1
	s_waitcnt lgkmcnt(0)
	v_mfma_f32_16x16x32_bf16 v[126:129], v[152:155], v[186:189], 0
	v_mfma_f32_16x16x32_bf16 v[122:125], v[160:163], v[186:189], 0
	v_mfma_f32_16x16x32_bf16 v[110:113], v[152:155], v[194:197], 0
	v_mfma_f32_16x16x32_bf16 v[106:109], v[160:163], v[194:197], 0
	v_mfma_f32_16x16x32_bf16 v[94:97], v[152:155], v[202:205], 0
	v_mfma_f32_16x16x32_bf16 v[90:93], v[160:163], v[202:205], 0
	v_mfma_f32_16x16x32_bf16 v[78:81], v[152:155], v[210:213], 0
	v_mfma_f32_16x16x32_bf16 v[74:77], v[160:163], v[210:213], 0
	v_mfma_f32_16x16x32_bf16 v[126:129], v[156:159], v[190:193], v[126:129]
	v_mfma_f32_16x16x32_bf16 v[122:125], v[164:167], v[190:193], v[122:125]
	v_mfma_f32_16x16x32_bf16 v[110:113], v[156:159], v[198:201], v[110:113]
	v_mfma_f32_16x16x32_bf16 v[106:109], v[164:167], v[198:201], v[106:109]
	v_mfma_f32_16x16x32_bf16 v[94:97], v[156:159], v[206:209], v[94:97]
	v_mfma_f32_16x16x32_bf16 v[90:93], v[164:167], v[206:209], v[90:93]
	v_mfma_f32_16x16x32_bf16 v[78:81], v[156:159], v[214:217], v[78:81]
	v_mfma_f32_16x16x32_bf16 v[74:77], v[164:167], v[214:217], v[74:77]
	s_setprio 0
	s_setprio 1
	v_mfma_f32_16x16x32_bf16 v[118:121], v[168:171], v[186:189], 0
	v_mfma_f32_16x16x32_bf16 v[114:117], v[178:181], v[186:189], 0
	v_mfma_f32_16x16x32_bf16 v[102:105], v[168:171], v[194:197], 0
	v_mfma_f32_16x16x32_bf16 v[98:101], v[178:181], v[194:197], 0
	v_mfma_f32_16x16x32_bf16 v[86:89], v[168:171], v[202:205], 0
	v_mfma_f32_16x16x32_bf16 v[82:85], v[178:181], v[202:205], 0
	v_mfma_f32_16x16x32_bf16 v[70:73], v[168:171], v[210:213], 0
	v_mfma_f32_16x16x32_bf16 v[66:69], v[178:181], v[210:213], 0
	v_mfma_f32_16x16x32_bf16 v[118:121], v[172:175], v[190:193], v[118:121]
	v_mfma_f32_16x16x32_bf16 v[114:117], v[182:185], v[190:193], v[114:117]
	v_mfma_f32_16x16x32_bf16 v[102:105], v[172:175], v[198:201], v[102:105]
	v_mfma_f32_16x16x32_bf16 v[98:101], v[182:185], v[198:201], v[98:101]
	v_mfma_f32_16x16x32_bf16 v[86:89], v[172:175], v[206:209], v[86:89]
	v_mfma_f32_16x16x32_bf16 v[82:85], v[182:185], v[206:209], v[82:85]
	v_mfma_f32_16x16x32_bf16 v[70:73], v[172:175], v[214:217], v[70:73]
	v_mfma_f32_16x16x32_bf16 v[66:69], v[182:185], v[214:217], v[66:69]
	s_setprio 0
	s_barrier
	s_add_i32 s53, s42, s34
	v_lshl_add_u64 v[146:147], s[30:31], 0, v[132:133]
	s_mov_b32 m0, s53
	ds_read_b128 v[186:189], v151 offset:16384
	ds_read_b128 v[190:193], v151 offset:17408
	ds_read_b128 v[194:197], v151 offset:18432
	ds_read_b128 v[198:201], v151 offset:19456
	ds_read_b128 v[202:205], v151 offset:20480
	ds_read_b128 v[206:209], v151 offset:21504
	ds_read_b128 v[210:213], v151 offset:22528
	ds_read_b128 v[214:217], v151 offset:23552
	global_load_lds_dwordx4 v[146:147], off
	s_add_i32 m0, s53, 0x2000
	s_add_u32 s54, s30, 0x40000
	v_lshl_add_u64 v[218:219], s[30:31], 0, v[136:137]
	s_addc_u32 s55, s31, 0
	s_add_i32 s53, s43, s34
	global_load_lds_dwordx4 v[218:219], off
	v_lshl_add_u64 v[220:221], s[54:55], 0, v[132:133]
	s_mov_b32 m0, s53
	v_lshl_add_u64 v[222:223], s[2:3], 0, v[134:135]
	global_load_lds_dwordx4 v[220:221], off
	v_lshl_add_u64 v[220:221], s[54:55], 0, v[136:137]
	s_add_i32 m0, s53, 0x2000
	s_nop 0
	global_load_lds_dwordx4 v[220:221], off
	v_lshl_add_u64 v[220:221], s[2:3], 0, v[130:131]
	s_mov_b32 m0, s25
	s_nop 0
	global_load_lds_dwordx4 v[220:221], off
	s_mov_b32 m0, s27
	s_nop 0
	global_load_lds_dwordx4 v[222:223], off
	s_waitcnt vmcnt(8)
	s_waitcnt lgkmcnt(0)
	s_barrier
	s_setprio 1
	s_waitcnt lgkmcnt(0)
	v_mfma_f32_16x16x32_bf16 v[62:65], v[152:155], v[186:189], 0
	v_mfma_f32_16x16x32_bf16 v[58:61], v[160:163], v[186:189], 0
	v_mfma_f32_16x16x32_bf16 v[46:49], v[152:155], v[194:197], 0
	v_mfma_f32_16x16x32_bf16 v[42:45], v[160:163], v[194:197], 0
	v_mfma_f32_16x16x32_bf16 v[30:33], v[152:155], v[202:205], 0
	v_mfma_f32_16x16x32_bf16 v[26:29], v[160:163], v[202:205], 0
	v_mfma_f32_16x16x32_bf16 v[14:17], v[152:155], v[210:213], 0
	v_mfma_f32_16x16x32_bf16 v[10:13], v[160:163], v[210:213], 0
	v_mfma_f32_16x16x32_bf16 v[62:65], v[156:159], v[190:193], v[62:65]
	v_mfma_f32_16x16x32_bf16 v[58:61], v[164:167], v[190:193], v[58:61]
	v_mfma_f32_16x16x32_bf16 v[46:49], v[156:159], v[198:201], v[46:49]
	v_mfma_f32_16x16x32_bf16 v[42:45], v[164:167], v[198:201], v[42:45]
	v_mfma_f32_16x16x32_bf16 v[30:33], v[156:159], v[206:209], v[30:33]
	v_mfma_f32_16x16x32_bf16 v[26:29], v[164:167], v[206:209], v[26:29]
	v_mfma_f32_16x16x32_bf16 v[14:17], v[156:159], v[214:217], v[14:17]
	v_mfma_f32_16x16x32_bf16 v[10:13], v[164:167], v[214:217], v[10:13]
	s_setprio 0
	s_setprio 1
	v_mfma_f32_16x16x32_bf16 v[54:57], v[168:171], v[186:189], 0
	v_mfma_f32_16x16x32_bf16 v[50:53], v[178:181], v[186:189], 0
	v_mfma_f32_16x16x32_bf16 v[38:41], v[168:171], v[194:197], 0
	v_mfma_f32_16x16x32_bf16 v[34:37], v[178:181], v[194:197], 0
	v_mfma_f32_16x16x32_bf16 v[22:25], v[168:171], v[202:205], 0
	v_mfma_f32_16x16x32_bf16 v[18:21], v[178:181], v[202:205], 0
	v_mfma_f32_16x16x32_bf16 v[6:9], v[168:171], v[210:213], 0
	v_mfma_f32_16x16x32_bf16 v[2:5], v[178:181], v[210:213], 0
	v_mfma_f32_16x16x32_bf16 v[54:57], v[172:175], v[190:193], v[54:57]
	v_mfma_f32_16x16x32_bf16 v[50:53], v[182:185], v[190:193], v[50:53]
	v_mfma_f32_16x16x32_bf16 v[38:41], v[172:175], v[198:201], v[38:41]
	v_mfma_f32_16x16x32_bf16 v[34:37], v[182:185], v[198:201], v[34:37]
	v_mfma_f32_16x16x32_bf16 v[22:25], v[172:175], v[206:209], v[22:25]
	v_mfma_f32_16x16x32_bf16 v[18:21], v[182:185], v[206:209], v[18:21]
	v_mfma_f32_16x16x32_bf16 v[6:9], v[172:175], v[214:217], v[6:9]
	v_mfma_f32_16x16x32_bf16 v[2:5], v[182:185], v[214:217], v[2:5]
	s_setprio 0
	s_barrier
	s_add_i32 s53, 0, 0x18000
	s_add_i32 s54, 0, 0x1c000
	v_add_u32_e32 v164, s53, v148
	v_add_u32_e32 v176, s54, v148
	ds_read_b128 v[152:155], v164
	ds_read_b128 v[156:159], v164 offset:1024
	ds_read_b128 v[160:163], v164 offset:2048
	ds_read_b128 v[164:167], v164 offset:3072
	ds_read_b128 v[168:171], v176
	ds_read_b128 v[172:175], v176 offset:1024
	ds_read_b128 v[178:181], v176 offset:2048
	ds_read_b128 v[182:185], v176 offset:3072
	s_add_u32 s2, s2, 0x40000
	s_addc_u32 s3, s3, 0
	s_mov_b32 m0, s36
	v_lshl_add_u64 v[224:225], s[2:3], 0, v[130:131]
	ds_read_b128 v[186:189], v151 offset:32768
	ds_read_b128 v[190:193], v151 offset:33792
	ds_read_b128 v[194:197], v151 offset:34816
	ds_read_b128 v[198:201], v151 offset:35840
	ds_read_b128 v[202:205], v151 offset:36864
	ds_read_b128 v[206:209], v151 offset:37888
	ds_read_b128 v[210:213], v151 offset:38912
	ds_read_b128 v[214:217], v151 offset:39936
	global_load_lds_dwordx4 v[224:225], off
	v_lshl_add_u64 v[224:225], s[2:3], 0, v[134:135]
	s_mov_b32 m0, s37
	s_nop 0
	global_load_lds_dwordx4 v[224:225], off
	s_waitcnt vmcnt(8)
	s_waitcnt lgkmcnt(0)
	s_barrier
	s_setprio 1
	s_waitcnt lgkmcnt(0)
	v_mfma_f32_16x16x32_bf16 v[126:129], v[152:155], v[186:189], v[126:129]
	v_mfma_f32_16x16x32_bf16 v[122:125], v[160:163], v[186:189], v[122:125]
	v_mfma_f32_16x16x32_bf16 v[110:113], v[152:155], v[194:197], v[110:113]
	v_mfma_f32_16x16x32_bf16 v[106:109], v[160:163], v[194:197], v[106:109]
	v_mfma_f32_16x16x32_bf16 v[94:97], v[152:155], v[202:205], v[94:97]
	v_mfma_f32_16x16x32_bf16 v[90:93], v[160:163], v[202:205], v[90:93]
	v_mfma_f32_16x16x32_bf16 v[78:81], v[152:155], v[210:213], v[78:81]
	v_mfma_f32_16x16x32_bf16 v[74:77], v[160:163], v[210:213], v[74:77]
	v_mfma_f32_16x16x32_bf16 v[126:129], v[156:159], v[190:193], v[126:129]
	v_mfma_f32_16x16x32_bf16 v[122:125], v[164:167], v[190:193], v[122:125]
	v_mfma_f32_16x16x32_bf16 v[110:113], v[156:159], v[198:201], v[110:113]
	v_mfma_f32_16x16x32_bf16 v[106:109], v[164:167], v[198:201], v[106:109]
	v_mfma_f32_16x16x32_bf16 v[94:97], v[156:159], v[206:209], v[94:97]
	v_mfma_f32_16x16x32_bf16 v[90:93], v[164:167], v[206:209], v[90:93]
	v_mfma_f32_16x16x32_bf16 v[78:81], v[156:159], v[214:217], v[78:81]
	v_mfma_f32_16x16x32_bf16 v[74:77], v[164:167], v[214:217], v[74:77]
	s_setprio 0
	s_setprio 1
	v_mfma_f32_16x16x32_bf16 v[118:121], v[168:171], v[186:189], v[118:121]
	v_mfma_f32_16x16x32_bf16 v[114:117], v[178:181], v[186:189], v[114:117]
	v_mfma_f32_16x16x32_bf16 v[102:105], v[168:171], v[194:197], v[102:105]
	v_mfma_f32_16x16x32_bf16 v[98:101], v[178:181], v[194:197], v[98:101]
	v_mfma_f32_16x16x32_bf16 v[86:89], v[168:171], v[202:205], v[86:89]
	v_mfma_f32_16x16x32_bf16 v[82:85], v[178:181], v[202:205], v[82:85]
	v_mfma_f32_16x16x32_bf16 v[70:73], v[168:171], v[210:213], v[70:73]
	v_mfma_f32_16x16x32_bf16 v[66:69], v[178:181], v[210:213], v[66:69]
	v_mfma_f32_16x16x32_bf16 v[118:121], v[172:175], v[190:193], v[118:121]
	v_mfma_f32_16x16x32_bf16 v[114:117], v[182:185], v[190:193], v[114:117]
	v_mfma_f32_16x16x32_bf16 v[102:105], v[172:175], v[198:201], v[102:105]
	v_mfma_f32_16x16x32_bf16 v[98:101], v[182:185], v[198:201], v[98:101]
	v_mfma_f32_16x16x32_bf16 v[86:89], v[172:175], v[206:209], v[86:89]
	v_mfma_f32_16x16x32_bf16 v[82:85], v[182:185], v[206:209], v[82:85]
	v_mfma_f32_16x16x32_bf16 v[70:73], v[172:175], v[214:217], v[70:73]
	v_mfma_f32_16x16x32_bf16 v[66:69], v[182:185], v[214:217], v[66:69]
	s_setprio 0
	s_barrier
	s_add_i32 s2, s53, s34
	v_lshl_add_u64 v[146:147], v[146:147], 0, s[6:7]
	s_mov_b32 m0, s2
	ds_read_b128 v[186:189], v151 offset:49152
	ds_read_b128 v[190:193], v151 offset:50176
	ds_read_b128 v[194:197], v151 offset:51200
	ds_read_b128 v[198:201], v151 offset:52224
	ds_read_b128 v[202:205], v151 offset:53248
	ds_read_b128 v[206:209], v151 offset:54272
	ds_read_b128 v[210:213], v151 offset:55296
	ds_read_b128 v[214:217], v151 offset:56320
	global_load_lds_dwordx4 v[146:147], off
	s_add_i32 m0, s2, 0x2000
	s_add_u32 s2, s30, 0x40080
	v_lshl_add_u64 v[146:147], v[218:219], 0, s[6:7]
	s_addc_u32 s3, s31, 0
	s_add_i32 s30, s54, s34
	global_load_lds_dwordx4 v[146:147], off
	v_lshl_add_u64 v[146:147], s[2:3], 0, v[132:133]
	s_mov_b32 m0, s30
	s_nop 0
	global_load_lds_dwordx4 v[146:147], off
	v_lshl_add_u64 v[146:147], s[2:3], 0, v[136:137]
	s_add_i32 m0, s30, 0x2000
	s_nop 0
	global_load_lds_dwordx4 v[146:147], off
	v_lshl_add_u64 v[146:147], v[220:221], 0, s[6:7]
	s_mov_b32 m0, s39
	s_nop 0
	global_load_lds_dwordx4 v[146:147], off
	v_lshl_add_u64 v[146:147], v[222:223], 0, s[6:7]
	s_mov_b32 m0, s40
	s_nop 0
	global_load_lds_dwordx4 v[146:147], off
	s_waitcnt vmcnt(8)
	s_waitcnt lgkmcnt(0)
	s_barrier
	s_setprio 1
	s_waitcnt lgkmcnt(0)
	v_mfma_f32_16x16x32_bf16 v[62:65], v[152:155], v[186:189], v[62:65]
	v_mfma_f32_16x16x32_bf16 v[58:61], v[160:163], v[186:189], v[58:61]
	v_mfma_f32_16x16x32_bf16 v[46:49], v[152:155], v[194:197], v[46:49]
	v_mfma_f32_16x16x32_bf16 v[42:45], v[160:163], v[194:197], v[42:45]
	v_mfma_f32_16x16x32_bf16 v[30:33], v[152:155], v[202:205], v[30:33]
	v_mfma_f32_16x16x32_bf16 v[26:29], v[160:163], v[202:205], v[26:29]
	v_mfma_f32_16x16x32_bf16 v[14:17], v[152:155], v[210:213], v[14:17]
	v_mfma_f32_16x16x32_bf16 v[10:13], v[160:163], v[210:213], v[10:13]
	v_mfma_f32_16x16x32_bf16 v[62:65], v[156:159], v[190:193], v[62:65]
	v_mfma_f32_16x16x32_bf16 v[58:61], v[164:167], v[190:193], v[58:61]
	v_mfma_f32_16x16x32_bf16 v[46:49], v[156:159], v[198:201], v[46:49]
	v_mfma_f32_16x16x32_bf16 v[42:45], v[164:167], v[198:201], v[42:45]
	v_mfma_f32_16x16x32_bf16 v[30:33], v[156:159], v[206:209], v[30:33]
	v_mfma_f32_16x16x32_bf16 v[26:29], v[164:167], v[206:209], v[26:29]
	v_mfma_f32_16x16x32_bf16 v[14:17], v[156:159], v[214:217], v[14:17]
	v_mfma_f32_16x16x32_bf16 v[10:13], v[164:167], v[214:217], v[10:13]
	s_setprio 0
	s_setprio 1
	v_mfma_f32_16x16x32_bf16 v[54:57], v[168:171], v[186:189], v[54:57]
	v_mfma_f32_16x16x32_bf16 v[50:53], v[178:181], v[186:189], v[50:53]
	v_mfma_f32_16x16x32_bf16 v[38:41], v[168:171], v[194:197], v[38:41]
	v_mfma_f32_16x16x32_bf16 v[34:37], v[178:181], v[194:197], v[34:37]
	v_mfma_f32_16x16x32_bf16 v[22:25], v[168:171], v[202:205], v[22:25]
	v_mfma_f32_16x16x32_bf16 v[18:21], v[178:181], v[202:205], v[18:21]
	v_mfma_f32_16x16x32_bf16 v[6:9], v[168:171], v[210:213], v[6:9]
	v_mfma_f32_16x16x32_bf16 v[2:5], v[178:181], v[210:213], v[2:5]
	v_mfma_f32_16x16x32_bf16 v[54:57], v[172:175], v[190:193], v[54:57]
	v_mfma_f32_16x16x32_bf16 v[50:53], v[182:185], v[190:193], v[50:53]
	v_mfma_f32_16x16x32_bf16 v[38:41], v[172:175], v[198:201], v[38:41]
	v_mfma_f32_16x16x32_bf16 v[34:37], v[182:185], v[198:201], v[34:37]
	v_mfma_f32_16x16x32_bf16 v[22:25], v[172:175], v[206:209], v[22:25]
	v_mfma_f32_16x16x32_bf16 v[18:21], v[182:185], v[206:209], v[18:21]
	v_mfma_f32_16x16x32_bf16 v[6:9], v[172:175], v[214:217], v[6:9]
	v_mfma_f32_16x16x32_bf16 v[2:5], v[182:185], v[214:217], v[2:5]
	s_setprio 0
	s_barrier
	s_add_i32 s52, s52, 2
	s_add_u32 s28, s28, 0x100
	s_addc_u32 s29, s29, 0
	s_add_u32 s46, s46, 0x100
	s_addc_u32 s47, s47, 0
	s_cmp_gt_u32 s52, 13
	s_cbranch_scc0 .LBB0_451
	s_branch .Lpk451_exit

.LBB0_494:
	s_lshl_b64 s[2:3], s[8:9], 1
	v_readlane_b32 s14, v253, 54
	s_add_u32 s14, s14, s2
	v_readlane_b32 s2, v253, 7
	s_addc_u32 s15, s2, s3
	s_and_b64 s[2:3], s[12:13], exec
	s_cselect_b32 s44, s15, s19
	s_cselect_b32 s45, s14, s18
	s_lshl_b64 s[2:3], s[10:11], 1
	s_add_u32 s16, s26, s2
	s_addc_u32 s17, s27, s3
	s_and_b64 s[2:3], s[12:13], exec
	s_cselect_b32 s46, s17, s21
	s_cselect_b32 s47, s16, s20
	s_add_u32 s18, s18, 0xc000
	s_addc_u32 s19, s19, 0
	s_add_u32 s48, s20, 0x10000
	s_addc_u32 s49, s21, 0
	s_mov_b32 s50, -2
.Lpk495_peel:
	ds_read_b128 v[152:155], v149
	ds_read_b128 v[156:159], v149 offset:1024
	ds_read_b128 v[160:163], v149 offset:2048
	ds_read_b128 v[164:167], v149 offset:3072
	ds_read_b128 v[168:171], v150
	ds_read_b128 v[172:175], v150 offset:1024
	ds_read_b128 v[178:181], v150 offset:2048
	ds_read_b128 v[182:185], v150 offset:3072
	s_add_u32 s2, s18, 0x4000
	s_addc_u32 s3, s19, 0
	s_cmp_eq_u32 s50, 40
	s_cselect_b32 s2, s45, s2
	s_cselect_b32 s3, s44, s3
	s_cselect_b32 s23, s46, s49
	s_cselect_b32 s22, s47, s48
	s_add_u32 s20, s2, 0x8000
	s_addc_u32 s21, s3, 0
	v_lshl_add_u64 v[144:145], s[18:19], 0, v[138:139]
	s_add_i32 m0, s29, 0xc000
	ds_read_b128 v[186:189], v151
	ds_read_b128 v[190:193], v151 offset:1024
	ds_read_b128 v[194:197], v151 offset:2048
	ds_read_b128 v[198:201], v151 offset:3072
	ds_read_b128 v[202:205], v151 offset:4096
	ds_read_b128 v[206:209], v151 offset:5120
	ds_read_b128 v[210:213], v151 offset:6144
	ds_read_b128 v[214:217], v151 offset:7168
	global_load_lds_dwordx4 v[144:145], off
	v_lshl_add_u64 v[144:145], s[18:19], 0, v[140:141]
	s_add_i32 m0, s29, 0xe000
	s_nop 0
	global_load_lds_dwordx4 v[144:145], off
	s_waitcnt vmcnt(8)
	s_waitcnt lgkmcnt(0)
	s_barrier
	s_setprio 1
	s_waitcnt lgkmcnt(0)
	v_mfma_f32_16x16x32_bf16 v[126:129], v[152:155], v[186:189], 0
	v_mfma_f32_16x16x32_bf16 v[122:125], v[160:163], v[186:189], 0
	v_mfma_f32_16x16x32_bf16 v[114:117], v[152:155], v[194:197], 0
	v_mfma_f32_16x16x32_bf16 v[106:109], v[160:163], v[194:197], 0
	v_mfma_f32_16x16x32_bf16 v[98:101], v[152:155], v[202:205], 0
	v_mfma_f32_16x16x32_bf16 v[90:93], v[160:163], v[202:205], 0
	v_mfma_f32_16x16x32_bf16 v[82:85], v[152:155], v[210:213], 0
	v_mfma_f32_16x16x32_bf16 v[74:77], v[160:163], v[210:213], 0
	v_mfma_f32_16x16x32_bf16 v[126:129], v[156:159], v[190:193], v[126:129]
	v_mfma_f32_16x16x32_bf16 v[122:125], v[164:167], v[190:193], v[122:125]
	v_mfma_f32_16x16x32_bf16 v[114:117], v[156:159], v[198:201], v[114:117]
	v_mfma_f32_16x16x32_bf16 v[106:109], v[164:167], v[198:201], v[106:109]
	v_mfma_f32_16x16x32_bf16 v[98:101], v[156:159], v[206:209], v[98:101]
	v_mfma_f32_16x16x32_bf16 v[90:93], v[164:167], v[206:209], v[90:93]
	v_mfma_f32_16x16x32_bf16 v[82:85], v[156:159], v[214:217], v[82:85]
	v_mfma_f32_16x16x32_bf16 v[74:77], v[164:167], v[214:217], v[74:77]
	s_setprio 0
	s_setprio 1
	v_mfma_f32_16x16x32_bf16 v[118:121], v[168:171], v[186:189], 0
	v_mfma_f32_16x16x32_bf16 v[110:113], v[178:181], v[186:189], 0
	v_mfma_f32_16x16x32_bf16 v[102:105], v[168:171], v[194:197], 0
	v_mfma_f32_16x16x32_bf16 v[94:97], v[178:181], v[194:197], 0
	v_mfma_f32_16x16x32_bf16 v[86:89], v[168:171], v[202:205], 0
	v_mfma_f32_16x16x32_bf16 v[78:81], v[178:181], v[202:205], 0
	v_mfma_f32_16x16x32_bf16 v[70:73], v[168:171], v[210:213], 0
	v_mfma_f32_16x16x32_bf16 v[66:69], v[178:181], v[210:213], 0
	v_mfma_f32_16x16x32_bf16 v[118:121], v[172:175], v[190:193], v[118:121]
	v_mfma_f32_16x16x32_bf16 v[110:113], v[182:185], v[190:193], v[110:113]
	v_mfma_f32_16x16x32_bf16 v[102:105], v[172:175], v[198:201], v[102:105]
	v_mfma_f32_16x16x32_bf16 v[94:97], v[182:185], v[198:201], v[94:97]
	v_mfma_f32_16x16x32_bf16 v[86:89], v[172:175], v[206:209], v[86:89]
	v_mfma_f32_16x16x32_bf16 v[78:81], v[182:185], v[206:209], v[78:81]
	v_mfma_f32_16x16x32_bf16 v[70:73], v[172:175], v[214:217], v[70:73]
	v_mfma_f32_16x16x32_bf16 v[66:69], v[182:185], v[214:217], v[66:69]
	s_setprio 0
	s_barrier
	s_add_i32 s51, s38, s28
	v_lshl_add_u64 v[144:145], s[22:23], 0, v[132:133]
	s_mov_b32 m0, s51
	ds_read_b128 v[186:189], v151 offset:16384
	ds_read_b128 v[190:193], v151 offset:17408
	ds_read_b128 v[194:197], v151 offset:18432
	ds_read_b128 v[198:201], v151 offset:19456
	ds_read_b128 v[202:205], v151 offset:20480
	ds_read_b128 v[206:209], v151 offset:21504
	ds_read_b128 v[210:213], v151 offset:22528
	ds_read_b128 v[214:217], v151 offset:23552
	global_load_lds_dwordx4 v[144:145], off
	s_add_i32 m0, s51, 0x2000
	s_add_u32 s52, s22, 0x4000
	v_lshl_add_u64 v[144:145], s[22:23], 0, v[136:137]
	s_addc_u32 s53, s23, 0
	s_add_i32 s51, s39, s28
	global_load_lds_dwordx4 v[144:145], off
	v_lshl_add_u64 v[144:145], s[52:53], 0, v[132:133]
	s_mov_b32 m0, s51
	s_nop 0
	global_load_lds_dwordx4 v[144:145], off
	v_lshl_add_u64 v[144:145], s[52:53], 0, v[136:137]
	s_add_i32 m0, s51, 0x2000
	s_nop 0
	global_load_lds_dwordx4 v[144:145], off
	v_lshl_add_u64 v[144:145], s[2:3], 0, v[130:131]
	s_mov_b32 m0, s29
	s_nop 0
	global_load_lds_dwordx4 v[144:145], off
	v_lshl_add_u64 v[144:145], s[2:3], 0, v[134:135]
	s_mov_b32 m0, s30
	s_nop 0
	global_load_lds_dwordx4 v[144:145], off
	s_waitcnt vmcnt(8)
	s_waitcnt lgkmcnt(0)
	s_barrier
	s_setprio 1
	s_waitcnt lgkmcnt(0)
	v_mfma_f32_16x16x32_bf16 v[62:65], v[152:155], v[186:189], 0
	v_mfma_f32_16x16x32_bf16 v[58:61], v[160:163], v[186:189], 0
	v_mfma_f32_16x16x32_bf16 v[50:53], v[152:155], v[194:197], 0
	v_mfma_f32_16x16x32_bf16 v[42:45], v[160:163], v[194:197], 0
	v_mfma_f32_16x16x32_bf16 v[34:37], v[152:155], v[202:205], 0
	v_mfma_f32_16x16x32_bf16 v[26:29], v[160:163], v[202:205], 0
	v_mfma_f32_16x16x32_bf16 v[18:21], v[152:155], v[210:213], 0
	v_mfma_f32_16x16x32_bf16 v[10:13], v[160:163], v[210:213], 0
	v_mfma_f32_16x16x32_bf16 v[62:65], v[156:159], v[190:193], v[62:65]
	v_mfma_f32_16x16x32_bf16 v[58:61], v[164:167], v[190:193], v[58:61]
	v_mfma_f32_16x16x32_bf16 v[50:53], v[156:159], v[198:201], v[50:53]
	v_mfma_f32_16x16x32_bf16 v[42:45], v[164:167], v[198:201], v[42:45]
	v_mfma_f32_16x16x32_bf16 v[34:37], v[156:159], v[206:209], v[34:37]
	v_mfma_f32_16x16x32_bf16 v[26:29], v[164:167], v[206:209], v[26:29]
	v_mfma_f32_16x16x32_bf16 v[18:21], v[156:159], v[214:217], v[18:21]
	v_mfma_f32_16x16x32_bf16 v[10:13], v[164:167], v[214:217], v[10:13]
	s_setprio 0
	s_setprio 1
	v_mfma_f32_16x16x32_bf16 v[54:57], v[168:171], v[186:189], 0
	v_mfma_f32_16x16x32_bf16 v[46:49], v[178:181], v[186:189], 0
	v_mfma_f32_16x16x32_bf16 v[38:41], v[168:171], v[194:197], 0
	v_mfma_f32_16x16x32_bf16 v[30:33], v[178:181], v[194:197], 0
	v_mfma_f32_16x16x32_bf16 v[22:25], v[168:171], v[202:205], 0
	v_mfma_f32_16x16x32_bf16 v[14:17], v[178:181], v[202:205], 0
	v_mfma_f32_16x16x32_bf16 v[6:9], v[168:171], v[210:213], 0
	v_mfma_f32_16x16x32_bf16 v[2:5], v[178:181], v[210:213], 0
	v_mfma_f32_16x16x32_bf16 v[54:57], v[172:175], v[190:193], v[54:57]
	v_mfma_f32_16x16x32_bf16 v[46:49], v[182:185], v[190:193], v[46:49]
	v_mfma_f32_16x16x32_bf16 v[38:41], v[172:175], v[198:201], v[38:41]
	v_mfma_f32_16x16x32_bf16 v[30:33], v[182:185], v[198:201], v[30:33]
	v_mfma_f32_16x16x32_bf16 v[22:25], v[172:175], v[206:209], v[22:25]
	v_mfma_f32_16x16x32_bf16 v[14:17], v[182:185], v[206:209], v[14:17]
	v_mfma_f32_16x16x32_bf16 v[6:9], v[172:175], v[214:217], v[6:9]
	v_mfma_f32_16x16x32_bf16 v[2:5], v[182:185], v[214:217], v[2:5]
	s_setprio 0
	s_barrier
	s_add_i32 s51, 0, 0x18000
	v_add_u32_e32 v144, s51, v147
	s_add_i32 s52, 0, 0x1c000
	ds_read_b128 v[152:155], v144
	ds_read_b128 v[156:159], v144 offset:1024
	ds_read_b128 v[160:163], v144 offset:2048
	ds_read_b128 v[164:167], v144 offset:3072
	v_add_u32_e32 v144, s52, v147
	ds_read_b128 v[168:171], v144
	ds_read_b128 v[172:175], v144 offset:1024
	ds_read_b128 v[178:181], v144 offset:2048
	ds_read_b128 v[182:185], v144 offset:3072
	s_add_u32 s2, s2, 0x4000
	s_addc_u32 s3, s3, 0
	s_mov_b32 m0, s31
	v_lshl_add_u64 v[144:145], s[2:3], 0, v[130:131]
	ds_read_b128 v[186:189], v151 offset:32768
	ds_read_b128 v[190:193], v151 offset:33792
	ds_read_b128 v[194:197], v151 offset:34816
	ds_read_b128 v[198:201], v151 offset:35840
	ds_read_b128 v[202:205], v151 offset:36864
	ds_read_b128 v[206:209], v151 offset:37888
	ds_read_b128 v[210:213], v151 offset:38912
	ds_read_b128 v[214:217], v151 offset:39936
	global_load_lds_dwordx4 v[144:145], off
	v_lshl_add_u64 v[144:145], s[2:3], 0, v[134:135]
	s_mov_b32 m0, s34
	s_nop 0
	global_load_lds_dwordx4 v[144:145], off
	s_waitcnt vmcnt(8)
	s_waitcnt lgkmcnt(0)
	s_barrier
	s_setprio 1
	s_waitcnt lgkmcnt(0)
	v_mfma_f32_16x16x32_bf16 v[126:129], v[152:155], v[186:189], v[126:129]
	v_mfma_f32_16x16x32_bf16 v[122:125], v[160:163], v[186:189], v[122:125]
	v_mfma_f32_16x16x32_bf16 v[114:117], v[152:155], v[194:197], v[114:117]
	v_mfma_f32_16x16x32_bf16 v[106:109], v[160:163], v[194:197], v[106:109]
	v_mfma_f32_16x16x32_bf16 v[98:101], v[152:155], v[202:205], v[98:101]
	v_mfma_f32_16x16x32_bf16 v[90:93], v[160:163], v[202:205], v[90:93]
	v_mfma_f32_16x16x32_bf16 v[82:85], v[152:155], v[210:213], v[82:85]
	v_mfma_f32_16x16x32_bf16 v[74:77], v[160:163], v[210:213], v[74:77]
	v_mfma_f32_16x16x32_bf16 v[126:129], v[156:159], v[190:193], v[126:129]
	v_mfma_f32_16x16x32_bf16 v[122:125], v[164:167], v[190:193], v[122:125]
	v_mfma_f32_16x16x32_bf16 v[114:117], v[156:159], v[198:201], v[114:117]
	v_mfma_f32_16x16x32_bf16 v[106:109], v[164:167], v[198:201], v[106:109]
	v_mfma_f32_16x16x32_bf16 v[98:101], v[156:159], v[206:209], v[98:101]
	v_mfma_f32_16x16x32_bf16 v[90:93], v[164:167], v[206:209], v[90:93]
	v_mfma_f32_16x16x32_bf16 v[82:85], v[156:159], v[214:217], v[82:85]
	v_mfma_f32_16x16x32_bf16 v[74:77], v[164:167], v[214:217], v[74:77]
	s_setprio 0
	s_setprio 1
	v_mfma_f32_16x16x32_bf16 v[118:121], v[168:171], v[186:189], v[118:121]
	v_mfma_f32_16x16x32_bf16 v[110:113], v[178:181], v[186:189], v[110:113]
	v_mfma_f32_16x16x32_bf16 v[102:105], v[168:171], v[194:197], v[102:105]
	v_mfma_f32_16x16x32_bf16 v[94:97], v[178:181], v[194:197], v[94:97]
	v_mfma_f32_16x16x32_bf16 v[86:89], v[168:171], v[202:205], v[86:89]
	v_mfma_f32_16x16x32_bf16 v[78:81], v[178:181], v[202:205], v[78:81]
	v_mfma_f32_16x16x32_bf16 v[70:73], v[168:171], v[210:213], v[70:73]
	v_mfma_f32_16x16x32_bf16 v[66:69], v[178:181], v[210:213], v[66:69]
	v_mfma_f32_16x16x32_bf16 v[118:121], v[172:175], v[190:193], v[118:121]
	v_mfma_f32_16x16x32_bf16 v[110:113], v[182:185], v[190:193], v[110:113]
	v_mfma_f32_16x16x32_bf16 v[102:105], v[172:175], v[198:201], v[102:105]
	v_mfma_f32_16x16x32_bf16 v[94:97], v[182:185], v[198:201], v[94:97]
	v_mfma_f32_16x16x32_bf16 v[86:89], v[172:175], v[206:209], v[86:89]
	v_mfma_f32_16x16x32_bf16 v[78:81], v[182:185], v[206:209], v[78:81]
	v_mfma_f32_16x16x32_bf16 v[70:73], v[172:175], v[214:217], v[70:73]
	v_mfma_f32_16x16x32_bf16 v[66:69], v[182:185], v[214:217], v[66:69]
	s_setprio 0
	s_barrier
	s_add_u32 s2, s22, 0x8000
	s_addc_u32 s3, s23, 0
	s_add_i32 s51, s51, s28
	v_lshl_add_u64 v[144:145], s[2:3], 0, v[132:133]
	s_mov_b32 m0, s51
	ds_read_b128 v[186:189], v151 offset:49152
	ds_read_b128 v[190:193], v151 offset:50176
	ds_read_b128 v[194:197], v151 offset:51200
	ds_read_b128 v[198:201], v151 offset:52224
	ds_read_b128 v[202:205], v151 offset:53248
	ds_read_b128 v[206:209], v151 offset:54272
	ds_read_b128 v[210:213], v151 offset:55296
	ds_read_b128 v[214:217], v151 offset:56320
	global_load_lds_dwordx4 v[144:145], off
	s_add_i32 m0, s51, 0x2000
	v_lshl_add_u64 v[144:145], s[2:3], 0, v[136:137]
	s_add_u32 s2, s22, 0xc000
	s_addc_u32 s3, s23, 0
	s_add_i32 s22, s52, s28
	global_load_lds_dwordx4 v[144:145], off
	v_lshl_add_u64 v[144:145], s[2:3], 0, v[132:133]
	s_mov_b32 m0, s22
	s_nop 0
	global_load_lds_dwordx4 v[144:145], off
	v_lshl_add_u64 v[144:145], s[2:3], 0, v[136:137]
	s_add_i32 m0, s22, 0x2000
	s_nop 0
	global_load_lds_dwordx4 v[144:145], off
	v_lshl_add_u64 v[144:145], s[20:21], 0, v[130:131]
	s_mov_b32 m0, s36
	s_nop 0
	global_load_lds_dwordx4 v[144:145], off
	v_lshl_add_u64 v[144:145], s[20:21], 0, v[134:135]
	s_mov_b32 m0, s37
	s_nop 0
	global_load_lds_dwordx4 v[144:145], off
	s_waitcnt vmcnt(8)
	s_waitcnt lgkmcnt(0)
	s_barrier
	s_setprio 1
	s_waitcnt lgkmcnt(0)
	v_mfma_f32_16x16x32_bf16 v[62:65], v[152:155], v[186:189], v[62:65]
	v_mfma_f32_16x16x32_bf16 v[58:61], v[160:163], v[186:189], v[58:61]
	v_mfma_f32_16x16x32_bf16 v[50:53], v[152:155], v[194:197], v[50:53]
	v_mfma_f32_16x16x32_bf16 v[42:45], v[160:163], v[194:197], v[42:45]
	v_mfma_f32_16x16x32_bf16 v[34:37], v[152:155], v[202:205], v[34:37]
	v_mfma_f32_16x16x32_bf16 v[26:29], v[160:163], v[202:205], v[26:29]
	v_mfma_f32_16x16x32_bf16 v[18:21], v[152:155], v[210:213], v[18:21]
	v_mfma_f32_16x16x32_bf16 v[10:13], v[160:163], v[210:213], v[10:13]
	v_mfma_f32_16x16x32_bf16 v[62:65], v[156:159], v[190:193], v[62:65]
	v_mfma_f32_16x16x32_bf16 v[58:61], v[164:167], v[190:193], v[58:61]
	v_mfma_f32_16x16x32_bf16 v[50:53], v[156:159], v[198:201], v[50:53]
	v_mfma_f32_16x16x32_bf16 v[42:45], v[164:167], v[198:201], v[42:45]
	v_mfma_f32_16x16x32_bf16 v[34:37], v[156:159], v[206:209], v[34:37]
	v_mfma_f32_16x16x32_bf16 v[26:29], v[164:167], v[206:209], v[26:29]
	v_mfma_f32_16x16x32_bf16 v[18:21], v[156:159], v[214:217], v[18:21]
	v_mfma_f32_16x16x32_bf16 v[10:13], v[164:167], v[214:217], v[10:13]
	s_setprio 0
	s_setprio 1
	v_mfma_f32_16x16x32_bf16 v[54:57], v[168:171], v[186:189], v[54:57]
	v_mfma_f32_16x16x32_bf16 v[46:49], v[178:181], v[186:189], v[46:49]
	v_mfma_f32_16x16x32_bf16 v[38:41], v[168:171], v[194:197], v[38:41]
	v_mfma_f32_16x16x32_bf16 v[30:33], v[178:181], v[194:197], v[30:33]
	v_mfma_f32_16x16x32_bf16 v[22:25], v[168:171], v[202:205], v[22:25]
	v_mfma_f32_16x16x32_bf16 v[14:17], v[178:181], v[202:205], v[14:17]
	v_mfma_f32_16x16x32_bf16 v[6:9], v[168:171], v[210:213], v[6:9]
	v_mfma_f32_16x16x32_bf16 v[2:5], v[178:181], v[210:213], v[2:5]
	v_mfma_f32_16x16x32_bf16 v[54:57], v[172:175], v[190:193], v[54:57]
	v_mfma_f32_16x16x32_bf16 v[46:49], v[182:185], v[190:193], v[46:49]
	v_mfma_f32_16x16x32_bf16 v[38:41], v[172:175], v[198:201], v[38:41]
	v_mfma_f32_16x16x32_bf16 v[30:33], v[182:185], v[198:201], v[30:33]
	v_mfma_f32_16x16x32_bf16 v[22:25], v[172:175], v[206:209], v[22:25]
	v_mfma_f32_16x16x32_bf16 v[14:17], v[182:185], v[206:209], v[14:17]
	v_mfma_f32_16x16x32_bf16 v[6:9], v[172:175], v[214:217], v[6:9]
	v_mfma_f32_16x16x32_bf16 v[2:5], v[182:185], v[214:217], v[2:5]
	s_setprio 0
	s_barrier
	s_add_i32 s50, s50, 2
	s_add_u32 s18, s18, 0x10000
	s_addc_u32 s19, s19, 0
	s_add_u32 s48, s48, 0x10000
	s_addc_u32 s49, s49, 0
	s_cmp_gt_u32 s50, 41
	s_cbranch_scc0 .LBB0_495
	s_branch .Lpk495_exit

.Lpk495_exit:
	s_and_b64 vcc, exec, s[6:7]
	s_cbranch_vccz .LBB0_498
	s_barrier

.LBB0_554:
	s_lshl_b64 s[2:3], s[14:15], 1
	v_readlane_b32 s20, v253, 52
	v_readlane_b32 s21, v253, 53
	s_add_u32 s20, s20, s2
	s_addc_u32 s21, s21, s3
	s_and_b64 s[2:3], s[18:19], exec
	s_cselect_b32 s11, s21, s27
	s_cselect_b32 s13, s20, s26
	s_lshl_b64 s[2:3], s[16:17], 1
	s_add_u32 s22, s30, s2
	s_addc_u32 s23, s31, s3
	s_and_b64 s[2:3], s[18:19], exec
	s_cselect_b32 s48, s23, s29
	s_cselect_b32 s49, s22, s28
	s_add_u32 s26, s26, 0x40080
	s_addc_u32 s27, s27, 0
	s_add_u32 s50, s28, 0x100
	s_addc_u32 s51, s29, 0
	s_mov_b32 s52, -2
.Lpk555_peel:
	ds_read_b128 v[154:157], v151
	ds_read_b128 v[158:161], v151 offset:1024
	ds_read_b128 v[162:165], v151 offset:2048
	ds_read_b128 v[166:169], v151 offset:3072
	ds_read_b128 v[170:173], v152
	ds_read_b128 v[178:181], v152 offset:1024
	ds_read_b128 v[182:185], v152 offset:2048
	ds_read_b128 v[186:189], v152 offset:3072
	s_add_u32 s2, s26, 0xfffc0080
	s_addc_u32 s3, s27, -1
	s_cmp_eq_u32 s52, 12
	s_cselect_b32 s3, s11, s3
	s_cselect_b32 s2, s13, s2
	s_cselect_b32 s29, s48, s51
	s_cselect_b32 s28, s49, s50
	v_lshl_add_u64 v[144:145], s[26:27], 0, v[138:139]
	s_add_i32 m0, s37, 0xc000
	ds_read_b128 v[190:193], v153
	ds_read_b128 v[194:197], v153 offset:1024
	ds_read_b128 v[198:201], v153 offset:2048
	ds_read_b128 v[202:205], v153 offset:3072
	ds_read_b128 v[206:209], v153 offset:4096
	ds_read_b128 v[210:213], v153 offset:5120
	ds_read_b128 v[214:217], v153 offset:6144
	ds_read_b128 v[218:221], v153 offset:7168
	global_load_lds_dwordx4 v[144:145], off
	v_lshl_add_u64 v[144:145], s[26:27], 0, v[140:141]
	s_add_i32 m0, s37, 0xe000
	s_nop 0
	global_load_lds_dwordx4 v[144:145], off
	s_waitcnt vmcnt(8)
	s_waitcnt lgkmcnt(0)
	s_barrier
	s_setprio 1
	s_waitcnt lgkmcnt(0)
	v_mfma_f32_16x16x32_bf16 v[126:129], v[154:157], v[190:193], 0
	v_mfma_f32_16x16x32_bf16 v[122:125], v[162:165], v[190:193], 0
	v_mfma_f32_16x16x32_bf16 v[114:117], v[154:157], v[198:201], 0
	v_mfma_f32_16x16x32_bf16 v[106:109], v[162:165], v[198:201], 0
	v_mfma_f32_16x16x32_bf16 v[98:101], v[154:157], v[206:209], 0
	v_mfma_f32_16x16x32_bf16 v[90:93], v[162:165], v[206:209], 0
	v_mfma_f32_16x16x32_bf16 v[82:85], v[154:157], v[214:217], 0
	v_mfma_f32_16x16x32_bf16 v[74:77], v[162:165], v[214:217], 0
	v_mfma_f32_16x16x32_bf16 v[126:129], v[158:161], v[194:197], v[126:129]
	v_mfma_f32_16x16x32_bf16 v[122:125], v[166:169], v[194:197], v[122:125]
	v_mfma_f32_16x16x32_bf16 v[114:117], v[158:161], v[202:205], v[114:117]
	v_mfma_f32_16x16x32_bf16 v[106:109], v[166:169], v[202:205], v[106:109]
	v_mfma_f32_16x16x32_bf16 v[98:101], v[158:161], v[210:213], v[98:101]
	v_mfma_f32_16x16x32_bf16 v[90:93], v[166:169], v[210:213], v[90:93]
	v_mfma_f32_16x16x32_bf16 v[82:85], v[158:161], v[218:221], v[82:85]
	v_mfma_f32_16x16x32_bf16 v[74:77], v[166:169], v[218:221], v[74:77]
	s_setprio 0
	s_setprio 1
	v_mfma_f32_16x16x32_bf16 v[118:121], v[170:173], v[190:193], 0
	v_mfma_f32_16x16x32_bf16 v[110:113], v[182:185], v[190:193], 0
	v_mfma_f32_16x16x32_bf16 v[102:105], v[170:173], v[198:201], 0
	v_mfma_f32_16x16x32_bf16 v[94:97], v[182:185], v[198:201], 0
	v_mfma_f32_16x16x32_bf16 v[86:89], v[170:173], v[206:209], 0
	v_mfma_f32_16x16x32_bf16 v[78:81], v[182:185], v[206:209], 0
	v_mfma_f32_16x16x32_bf16 v[70:73], v[170:173], v[214:217], 0
	v_mfma_f32_16x16x32_bf16 v[66:69], v[182:185], v[214:217], 0
	v_mfma_f32_16x16x32_bf16 v[118:121], v[178:181], v[194:197], v[118:121]
	v_mfma_f32_16x16x32_bf16 v[110:113], v[186:189], v[194:197], v[110:113]
	v_mfma_f32_16x16x32_bf16 v[102:105], v[178:181], v[202:205], v[102:105]
	v_mfma_f32_16x16x32_bf16 v[94:97], v[186:189], v[202:205], v[94:97]
	v_mfma_f32_16x16x32_bf16 v[86:89], v[178:181], v[210:213], v[86:89]
	v_mfma_f32_16x16x32_bf16 v[78:81], v[186:189], v[210:213], v[78:81]
	v_mfma_f32_16x16x32_bf16 v[70:73], v[178:181], v[218:221], v[70:73]
	v_mfma_f32_16x16x32_bf16 v[66:69], v[186:189], v[218:221], v[66:69]
	s_setprio 0
	s_barrier
	s_add_i32 s53, s44, s34
	v_lshl_add_u64 v[144:145], s[28:29], 0, v[134:135]
	s_mov_b32 m0, s53
	ds_read_b128 v[190:193], v153 offset:16384
	ds_read_b128 v[194:197], v153 offset:17408
	ds_read_b128 v[198:201], v153 offset:18432
	ds_read_b128 v[202:205], v153 offset:19456
	ds_read_b128 v[206:209], v153 offset:20480
	ds_read_b128 v[210:213], v153 offset:21504
	ds_read_b128 v[214:217], v153 offset:22528
	ds_read_b128 v[218:221], v153 offset:23552
	global_load_lds_dwordx4 v[144:145], off
	s_add_i32 m0, s53, 0x2000
	s_add_u32 s54, s28, 0x40000
	v_lshl_add_u64 v[174:175], s[28:29], 0, v[130:131]
	s_addc_u32 s55, s29, 0
	s_add_i32 s53, s45, s34
	global_load_lds_dwordx4 v[174:175], off
	v_lshl_add_u64 v[222:223], s[54:55], 0, v[134:135]
	s_mov_b32 m0, s53
	v_lshl_add_u64 v[224:225], s[2:3], 0, v[132:133]
	global_load_lds_dwordx4 v[222:223], off
	v_lshl_add_u64 v[222:223], s[54:55], 0, v[130:131]
	s_add_i32 m0, s53, 0x2000
	s_nop 0
	global_load_lds_dwordx4 v[222:223], off
	v_lshl_add_u64 v[222:223], s[2:3], 0, v[136:137]
	s_mov_b32 m0, s37
	s_nop 0
	global_load_lds_dwordx4 v[222:223], off
	s_mov_b32 m0, s25
	s_nop 0
	global_load_lds_dwordx4 v[224:225], off
	s_waitcnt vmcnt(8)
	s_waitcnt lgkmcnt(0)
	s_barrier
	s_setprio 1
	s_waitcnt lgkmcnt(0)
	v_mfma_f32_16x16x32_bf16 v[62:65], v[154:157], v[190:193], 0
	v_mfma_f32_16x16x32_bf16 v[58:61], v[162:165], v[190:193], 0
	v_mfma_f32_16x16x32_bf16 v[50:53], v[154:157], v[198:201], 0
	v_mfma_f32_16x16x32_bf16 v[42:45], v[162:165], v[198:201], 0
	v_mfma_f32_16x16x32_bf16 v[34:37], v[154:157], v[206:209], 0
	v_mfma_f32_16x16x32_bf16 v[26:29], v[162:165], v[206:209], 0
	v_mfma_f32_16x16x32_bf16 v[18:21], v[154:157], v[214:217], 0
	v_mfma_f32_16x16x32_bf16 v[10:13], v[162:165], v[214:217], 0
	v_mfma_f32_16x16x32_bf16 v[62:65], v[158:161], v[194:197], v[62:65]
	v_mfma_f32_16x16x32_bf16 v[58:61], v[166:169], v[194:197], v[58:61]
	v_mfma_f32_16x16x32_bf16 v[50:53], v[158:161], v[202:205], v[50:53]
	v_mfma_f32_16x16x32_bf16 v[42:45], v[166:169], v[202:205], v[42:45]
	v_mfma_f32_16x16x32_bf16 v[34:37], v[158:161], v[210:213], v[34:37]
	v_mfma_f32_16x16x32_bf16 v[26:29], v[166:169], v[210:213], v[26:29]
	v_mfma_f32_16x16x32_bf16 v[18:21], v[158:161], v[218:221], v[18:21]
	v_mfma_f32_16x16x32_bf16 v[10:13], v[166:169], v[218:221], v[10:13]
	s_setprio 0
	s_setprio 1
	v_mfma_f32_16x16x32_bf16 v[54:57], v[170:173], v[190:193], 0
	v_mfma_f32_16x16x32_bf16 v[46:49], v[182:185], v[190:193], 0
	v_mfma_f32_16x16x32_bf16 v[38:41], v[170:173], v[198:201], 0
	v_mfma_f32_16x16x32_bf16 v[30:33], v[182:185], v[198:201], 0
	v_mfma_f32_16x16x32_bf16 v[22:25], v[170:173], v[206:209], 0
	v_mfma_f32_16x16x32_bf16 v[14:17], v[182:185], v[206:209], 0
	v_mfma_f32_16x16x32_bf16 v[6:9], v[170:173], v[214:217], 0
	v_mfma_f32_16x16x32_bf16 v[2:5], v[182:185], v[214:217], 0
	v_mfma_f32_16x16x32_bf16 v[54:57], v[178:181], v[194:197], v[54:57]
	v_mfma_f32_16x16x32_bf16 v[46:49], v[186:189], v[194:197], v[46:49]
	v_mfma_f32_16x16x32_bf16 v[38:41], v[178:181], v[202:205], v[38:41]
	v_mfma_f32_16x16x32_bf16 v[30:33], v[186:189], v[202:205], v[30:33]
	v_mfma_f32_16x16x32_bf16 v[22:25], v[178:181], v[210:213], v[22:25]
	v_mfma_f32_16x16x32_bf16 v[14:17], v[186:189], v[210:213], v[14:17]
	v_mfma_f32_16x16x32_bf16 v[6:9], v[178:181], v[218:221], v[6:9]
	v_mfma_f32_16x16x32_bf16 v[2:5], v[186:189], v[218:221], v[2:5]
	s_setprio 0
	s_barrier
	s_add_i32 s53, 0, 0x18000
	s_add_i32 s54, 0, 0x1c000
	v_add_u32_e32 v166, s53, v149
	v_add_u32_e32 v176, s54, v149
	ds_read_b128 v[154:157], v166
	ds_read_b128 v[158:161], v166 offset:1024
	ds_read_b128 v[162:165], v166 offset:2048
	ds_read_b128 v[166:169], v166 offset:3072
	ds_read_b128 v[170:173], v176
	ds_read_b128 v[178:181], v176 offset:1024
	ds_read_b128 v[182:185], v176 offset:2048
	ds_read_b128 v[186:189], v176 offset:3072
	s_add_u32 s2, s2, 0x40000
	s_addc_u32 s3, s3, 0
	s_mov_b32 m0, s38
	v_lshl_add_u64 v[226:227], s[2:3], 0, v[136:137]
	ds_read_b128 v[190:193], v153 offset:32768
	ds_read_b128 v[194:197], v153 offset:33792
	ds_read_b128 v[198:201], v153 offset:34816
	ds_read_b128 v[202:205], v153 offset:35840
	ds_read_b128 v[206:209], v153 offset:36864
	ds_read_b128 v[210:213], v153 offset:37888
	ds_read_b128 v[214:217], v153 offset:38912
	ds_read_b128 v[218:221], v153 offset:39936
	global_load_lds_dwordx4 v[226:227], off
	v_lshl_add_u64 v[226:227], s[2:3], 0, v[132:133]
	s_mov_b32 m0, s39
	s_nop 0
	global_load_lds_dwordx4 v[226:227], off
	s_waitcnt vmcnt(8)
	s_waitcnt lgkmcnt(0)
	s_barrier
	s_setprio 1
	s_waitcnt lgkmcnt(0)
	v_mfma_f32_16x16x32_bf16 v[126:129], v[154:157], v[190:193], v[126:129]
	v_mfma_f32_16x16x32_bf16 v[122:125], v[162:165], v[190:193], v[122:125]
	v_mfma_f32_16x16x32_bf16 v[114:117], v[154:157], v[198:201], v[114:117]
	v_mfma_f32_16x16x32_bf16 v[106:109], v[162:165], v[198:201], v[106:109]
	v_mfma_f32_16x16x32_bf16 v[98:101], v[154:157], v[206:209], v[98:101]
	v_mfma_f32_16x16x32_bf16 v[90:93], v[162:165], v[206:209], v[90:93]
	v_mfma_f32_16x16x32_bf16 v[82:85], v[154:157], v[214:217], v[82:85]
	v_mfma_f32_16x16x32_bf16 v[74:77], v[162:165], v[214:217], v[74:77]
	v_mfma_f32_16x16x32_bf16 v[126:129], v[158:161], v[194:197], v[126:129]
	v_mfma_f32_16x16x32_bf16 v[122:125], v[166:169], v[194:197], v[122:125]
	v_mfma_f32_16x16x32_bf16 v[114:117], v[158:161], v[202:205], v[114:117]
	v_mfma_f32_16x16x32_bf16 v[106:109], v[166:169], v[202:205], v[106:109]
	v_mfma_f32_16x16x32_bf16 v[98:101], v[158:161], v[210:213], v[98:101]
	v_mfma_f32_16x16x32_bf16 v[90:93], v[166:169], v[210:213], v[90:93]
	v_mfma_f32_16x16x32_bf16 v[82:85], v[158:161], v[218:221], v[82:85]
	v_mfma_f32_16x16x32_bf16 v[74:77], v[166:169], v[218:221], v[74:77]
	s_setprio 0
	s_setprio 1
	v_mfma_f32_16x16x32_bf16 v[118:121], v[170:173], v[190:193], v[118:121]
	v_mfma_f32_16x16x32_bf16 v[110:113], v[182:185], v[190:193], v[110:113]
	v_mfma_f32_16x16x32_bf16 v[102:105], v[170:173], v[198:201], v[102:105]
	v_mfma_f32_16x16x32_bf16 v[94:97], v[182:185], v[198:201], v[94:97]
	v_mfma_f32_16x16x32_bf16 v[86:89], v[170:173], v[206:209], v[86:89]
	v_mfma_f32_16x16x32_bf16 v[78:81], v[182:185], v[206:209], v[78:81]
	v_mfma_f32_16x16x32_bf16 v[70:73], v[170:173], v[214:217], v[70:73]
	v_mfma_f32_16x16x32_bf16 v[66:69], v[182:185], v[214:217], v[66:69]
	v_mfma_f32_16x16x32_bf16 v[118:121], v[178:181], v[194:197], v[118:121]
	v_mfma_f32_16x16x32_bf16 v[110:113], v[186:189], v[194:197], v[110:113]
	v_mfma_f32_16x16x32_bf16 v[102:105], v[178:181], v[202:205], v[102:105]
	v_mfma_f32_16x16x32_bf16 v[94:97], v[186:189], v[202:205], v[94:97]
	v_mfma_f32_16x16x32_bf16 v[86:89], v[178:181], v[210:213], v[86:89]
	v_mfma_f32_16x16x32_bf16 v[78:81], v[186:189], v[210:213], v[78:81]
	v_mfma_f32_16x16x32_bf16 v[70:73], v[178:181], v[218:221], v[70:73]
	v_mfma_f32_16x16x32_bf16 v[66:69], v[186:189], v[218:221], v[66:69]
	s_setprio 0
	s_barrier
	s_add_i32 s2, s53, s34
	v_lshl_add_u64 v[144:145], v[144:145], 0, s[6:7]
	s_mov_b32 m0, s2
	ds_read_b128 v[190:193], v153 offset:49152
	ds_read_b128 v[194:197], v153 offset:50176
	ds_read_b128 v[198:201], v153 offset:51200
	ds_read_b128 v[202:205], v153 offset:52224
	ds_read_b128 v[206:209], v153 offset:53248
	ds_read_b128 v[210:213], v153 offset:54272
	ds_read_b128 v[214:217], v153 offset:55296
	ds_read_b128 v[218:221], v153 offset:56320
	global_load_lds_dwordx4 v[144:145], off
	s_add_i32 m0, s2, 0x2000
	s_add_u32 s2, s28, 0x40080
	v_lshl_add_u64 v[144:145], v[174:175], 0, s[6:7]
	s_addc_u32 s3, s29, 0
	s_add_i32 s28, s54, s34
	global_load_lds_dwordx4 v[144:145], off
	v_lshl_add_u64 v[144:145], s[2:3], 0, v[134:135]
	s_mov_b32 m0, s28
	s_nop 0
	global_load_lds_dwordx4 v[144:145], off
	v_lshl_add_u64 v[144:145], s[2:3], 0, v[130:131]
	s_add_i32 m0, s28, 0x2000
	s_nop 0
	global_load_lds_dwordx4 v[144:145], off
	v_lshl_add_u64 v[144:145], v[222:223], 0, s[6:7]
	s_mov_b32 m0, s41
	s_nop 0
	global_load_lds_dwordx4 v[144:145], off
	v_lshl_add_u64 v[144:145], v[224:225], 0, s[6:7]
	s_mov_b32 m0, s42
	s_nop 0
	global_load_lds_dwordx4 v[144:145], off
	s_waitcnt vmcnt(8)
	s_waitcnt lgkmcnt(0)
	s_barrier
	s_setprio 1
	s_waitcnt lgkmcnt(0)
	v_mfma_f32_16x16x32_bf16 v[62:65], v[154:157], v[190:193], v[62:65]
	v_mfma_f32_16x16x32_bf16 v[58:61], v[162:165], v[190:193], v[58:61]
	v_mfma_f32_16x16x32_bf16 v[50:53], v[154:157], v[198:201], v[50:53]
	v_mfma_f32_16x16x32_bf16 v[42:45], v[162:165], v[198:201], v[42:45]
	v_mfma_f32_16x16x32_bf16 v[34:37], v[154:157], v[206:209], v[34:37]
	v_mfma_f32_16x16x32_bf16 v[26:29], v[162:165], v[206:209], v[26:29]
	v_mfma_f32_16x16x32_bf16 v[18:21], v[154:157], v[214:217], v[18:21]
	v_mfma_f32_16x16x32_bf16 v[10:13], v[162:165], v[214:217], v[10:13]
	v_mfma_f32_16x16x32_bf16 v[62:65], v[158:161], v[194:197], v[62:65]
	v_mfma_f32_16x16x32_bf16 v[58:61], v[166:169], v[194:197], v[58:61]
	v_mfma_f32_16x16x32_bf16 v[50:53], v[158:161], v[202:205], v[50:53]
	v_mfma_f32_16x16x32_bf16 v[42:45], v[166:169], v[202:205], v[42:45]
	v_mfma_f32_16x16x32_bf16 v[34:37], v[158:161], v[210:213], v[34:37]
	v_mfma_f32_16x16x32_bf16 v[26:29], v[166:169], v[210:213], v[26:29]
	v_mfma_f32_16x16x32_bf16 v[18:21], v[158:161], v[218:221], v[18:21]
	v_mfma_f32_16x16x32_bf16 v[10:13], v[166:169], v[218:221], v[10:13]
	s_setprio 0
	s_setprio 1
	v_mfma_f32_16x16x32_bf16 v[54:57], v[170:173], v[190:193], v[54:57]
	v_mfma_f32_16x16x32_bf16 v[46:49], v[182:185], v[190:193], v[46:49]
	v_mfma_f32_16x16x32_bf16 v[38:41], v[170:173], v[198:201], v[38:41]
	v_mfma_f32_16x16x32_bf16 v[30:33], v[182:185], v[198:201], v[30:33]
	v_mfma_f32_16x16x32_bf16 v[22:25], v[170:173], v[206:209], v[22:25]
	v_mfma_f32_16x16x32_bf16 v[14:17], v[182:185], v[206:209], v[14:17]
	v_mfma_f32_16x16x32_bf16 v[6:9], v[170:173], v[214:217], v[6:9]
	v_mfma_f32_16x16x32_bf16 v[2:5], v[182:185], v[214:217], v[2:5]
	v_mfma_f32_16x16x32_bf16 v[54:57], v[178:181], v[194:197], v[54:57]
	v_mfma_f32_16x16x32_bf16 v[46:49], v[186:189], v[194:197], v[46:49]
	v_mfma_f32_16x16x32_bf16 v[38:41], v[178:181], v[202:205], v[38:41]
	v_mfma_f32_16x16x32_bf16 v[30:33], v[186:189], v[202:205], v[30:33]
	v_mfma_f32_16x16x32_bf16 v[22:25], v[178:181], v[210:213], v[22:25]
	v_mfma_f32_16x16x32_bf16 v[14:17], v[186:189], v[210:213], v[14:17]
	v_mfma_f32_16x16x32_bf16 v[6:9], v[178:181], v[218:221], v[6:9]
	v_mfma_f32_16x16x32_bf16 v[2:5], v[186:189], v[218:221], v[2:5]
	s_setprio 0
	s_barrier
	s_add_i32 s52, s52, 2
	s_add_u32 s26, s26, 0x100
	s_addc_u32 s27, s27, 0
	s_add_u32 s50, s50, 0x100
	s_addc_u32 s51, s51, 0
	s_cmp_gt_u32 s52, 13
	s_cbranch_scc0 .LBB0_555
	s_branch .Lpk555_exit

.LBB0_1097:
	s_lshl_b64 s[2:3], s[18:19], 1
	s_add_u32 s24, s90, s2
	s_addc_u32 s25, s91, s3
	s_and_b64 s[2:3], s[22:23], exec
	s_cselect_b32 s15, s25, s31
	s_cselect_b32 s17, s24, s30
	s_lshl_b64 s[2:3], s[20:21], 1
	s_add_u32 s26, s37, s2
	s_addc_u32 s27, s38, s3
	s_and_b64 s[2:3], s[22:23], exec
	s_cselect_b32 s52, s27, s35
	s_cselect_b32 s53, s26, s34
	s_add_u32 s30, s30, 0x40080
	s_addc_u32 s31, s31, 0
	s_add_u32 s54, s34, 0x100
	s_addc_u32 s55, s35, 0
	s_mov_b32 s56, -2
.Lpk1098_peel:
	ds_read_b128 v[152:155], v148
	ds_read_b128 v[156:159], v148 offset:1024
	ds_read_b128 v[160:163], v148 offset:2048
	ds_read_b128 v[164:167], v148 offset:3072
	ds_read_b128 v[168:171], v149
	ds_read_b128 v[172:175], v149 offset:1024
	ds_read_b128 v[178:181], v149 offset:2048
	ds_read_b128 v[182:185], v149 offset:3072
	s_add_u32 s2, s30, 0xfffc0080
	s_addc_u32 s3, s31, -1
	s_cmp_eq_u32 s56, 12
	s_cselect_b32 s3, s15, s3
	s_cselect_b32 s2, s17, s2
	s_cselect_b32 s35, s52, s55
	s_cselect_b32 s34, s53, s54
	v_lshl_add_u64 v[144:145], s[30:31], 0, v[138:139]
	s_add_i32 m0, s40, 0xc000
	ds_read_b128 v[186:189], v150
	ds_read_b128 v[190:193], v150 offset:1024
	ds_read_b128 v[194:197], v150 offset:2048
	ds_read_b128 v[198:201], v150 offset:3072
	ds_read_b128 v[202:205], v150 offset:4096
	ds_read_b128 v[206:209], v150 offset:5120
	ds_read_b128 v[210:213], v150 offset:6144
	ds_read_b128 v[214:217], v150 offset:7168
	global_load_lds_dwordx4 v[144:145], off
	v_lshl_add_u64 v[144:145], s[30:31], 0, v[140:141]
	s_add_i32 m0, s40, 0xe000
	s_nop 0
	global_load_lds_dwordx4 v[144:145], off
	s_waitcnt vmcnt(8)
	s_waitcnt lgkmcnt(0)
	s_barrier
	s_setprio 1
	s_waitcnt lgkmcnt(0)
	v_mfma_f32_16x16x32_bf16 v[126:129], v[152:155], v[186:189], 0
	v_mfma_f32_16x16x32_bf16 v[122:125], v[160:163], v[186:189], 0
	v_mfma_f32_16x16x32_bf16 v[114:117], v[152:155], v[194:197], 0
	v_mfma_f32_16x16x32_bf16 v[106:109], v[160:163], v[194:197], 0
	v_mfma_f32_16x16x32_bf16 v[98:101], v[152:155], v[202:205], 0
	v_mfma_f32_16x16x32_bf16 v[90:93], v[160:163], v[202:205], 0
	v_mfma_f32_16x16x32_bf16 v[82:85], v[152:155], v[210:213], 0
	v_mfma_f32_16x16x32_bf16 v[74:77], v[160:163], v[210:213], 0
	v_mfma_f32_16x16x32_bf16 v[126:129], v[156:159], v[190:193], v[126:129]
	v_mfma_f32_16x16x32_bf16 v[122:125], v[164:167], v[190:193], v[122:125]
	v_mfma_f32_16x16x32_bf16 v[114:117], v[156:159], v[198:201], v[114:117]
	v_mfma_f32_16x16x32_bf16 v[106:109], v[164:167], v[198:201], v[106:109]
	v_mfma_f32_16x16x32_bf16 v[98:101], v[156:159], v[206:209], v[98:101]
	v_mfma_f32_16x16x32_bf16 v[90:93], v[164:167], v[206:209], v[90:93]
	v_mfma_f32_16x16x32_bf16 v[82:85], v[156:159], v[214:217], v[82:85]
	v_mfma_f32_16x16x32_bf16 v[74:77], v[164:167], v[214:217], v[74:77]
	s_setprio 0
	s_setprio 1
	v_mfma_f32_16x16x32_bf16 v[118:121], v[168:171], v[186:189], 0
	v_mfma_f32_16x16x32_bf16 v[110:113], v[178:181], v[186:189], 0
	v_mfma_f32_16x16x32_bf16 v[102:105], v[168:171], v[194:197], 0
	v_mfma_f32_16x16x32_bf16 v[94:97], v[178:181], v[194:197], 0
	v_mfma_f32_16x16x32_bf16 v[86:89], v[168:171], v[202:205], 0
	v_mfma_f32_16x16x32_bf16 v[78:81], v[178:181], v[202:205], 0
	v_mfma_f32_16x16x32_bf16 v[70:73], v[168:171], v[210:213], 0
	v_mfma_f32_16x16x32_bf16 v[66:69], v[178:181], v[210:213], 0
	v_mfma_f32_16x16x32_bf16 v[118:121], v[172:175], v[190:193], v[118:121]
	v_mfma_f32_16x16x32_bf16 v[110:113], v[182:185], v[190:193], v[110:113]
	v_mfma_f32_16x16x32_bf16 v[102:105], v[172:175], v[198:201], v[102:105]
	v_mfma_f32_16x16x32_bf16 v[94:97], v[182:185], v[198:201], v[94:97]
	v_mfma_f32_16x16x32_bf16 v[86:89], v[172:175], v[206:209], v[86:89]
	v_mfma_f32_16x16x32_bf16 v[78:81], v[182:185], v[206:209], v[78:81]
	v_mfma_f32_16x16x32_bf16 v[70:73], v[172:175], v[214:217], v[70:73]
	v_mfma_f32_16x16x32_bf16 v[66:69], v[182:185], v[214:217], v[66:69]
	s_setprio 0
	s_barrier
	s_add_i32 s57, s47, s39
	v_lshl_add_u64 v[144:145], s[34:35], 0, v[132:133]
	s_mov_b32 m0, s57
	ds_read_b128 v[186:189], v150 offset:16384
	ds_read_b128 v[190:193], v150 offset:17408
	ds_read_b128 v[194:197], v150 offset:18432
	ds_read_b128 v[198:201], v150 offset:19456
	ds_read_b128 v[202:205], v150 offset:20480
	ds_read_b128 v[206:209], v150 offset:21504
	ds_read_b128 v[210:213], v150 offset:22528
	ds_read_b128 v[214:217], v150 offset:23552
	global_load_lds_dwordx4 v[144:145], off
	s_add_i32 m0, s57, 0x2000
	s_add_u32 s58, s34, 0x40000
	v_lshl_add_u64 v[218:219], s[34:35], 0, v[136:137]
	s_addc_u32 s59, s35, 0
	s_add_i32 s57, s48, s39
	global_load_lds_dwordx4 v[218:219], off
	v_lshl_add_u64 v[220:221], s[58:59], 0, v[132:133]
	s_mov_b32 m0, s57
	v_lshl_add_u64 v[222:223], s[2:3], 0, v[134:135]
	global_load_lds_dwordx4 v[220:221], off
	v_lshl_add_u64 v[220:221], s[58:59], 0, v[136:137]
	s_add_i32 m0, s57, 0x2000
	s_nop 0
	global_load_lds_dwordx4 v[220:221], off
	v_lshl_add_u64 v[220:221], s[2:3], 0, v[130:131]
	s_mov_b32 m0, s40
	s_nop 0
	global_load_lds_dwordx4 v[220:221], off
	s_mov_b32 m0, s29
	s_nop 0
	global_load_lds_dwordx4 v[222:223], off
	s_waitcnt vmcnt(8)
	s_waitcnt lgkmcnt(0)
	s_barrier
	s_setprio 1
	s_waitcnt lgkmcnt(0)
	v_mfma_f32_16x16x32_bf16 v[62:65], v[152:155], v[186:189], 0
	v_mfma_f32_16x16x32_bf16 v[58:61], v[160:163], v[186:189], 0
	v_mfma_f32_16x16x32_bf16 v[50:53], v[152:155], v[194:197], 0
	v_mfma_f32_16x16x32_bf16 v[42:45], v[160:163], v[194:197], 0
	v_mfma_f32_16x16x32_bf16 v[34:37], v[152:155], v[202:205], 0
	v_mfma_f32_16x16x32_bf16 v[26:29], v[160:163], v[202:205], 0
	v_mfma_f32_16x16x32_bf16 v[18:21], v[152:155], v[210:213], 0
	v_mfma_f32_16x16x32_bf16 v[10:13], v[160:163], v[210:213], 0
	v_mfma_f32_16x16x32_bf16 v[62:65], v[156:159], v[190:193], v[62:65]
	v_mfma_f32_16x16x32_bf16 v[58:61], v[164:167], v[190:193], v[58:61]
	v_mfma_f32_16x16x32_bf16 v[50:53], v[156:159], v[198:201], v[50:53]
	v_mfma_f32_16x16x32_bf16 v[42:45], v[164:167], v[198:201], v[42:45]
	v_mfma_f32_16x16x32_bf16 v[34:37], v[156:159], v[206:209], v[34:37]
	v_mfma_f32_16x16x32_bf16 v[26:29], v[164:167], v[206:209], v[26:29]
	v_mfma_f32_16x16x32_bf16 v[18:21], v[156:159], v[214:217], v[18:21]
	v_mfma_f32_16x16x32_bf16 v[10:13], v[164:167], v[214:217], v[10:13]
	s_setprio 0
	s_setprio 1
	v_mfma_f32_16x16x32_bf16 v[54:57], v[168:171], v[186:189], 0
	v_mfma_f32_16x16x32_bf16 v[46:49], v[178:181], v[186:189], 0
	v_mfma_f32_16x16x32_bf16 v[38:41], v[168:171], v[194:197], 0
	v_mfma_f32_16x16x32_bf16 v[30:33], v[178:181], v[194:197], 0
	v_mfma_f32_16x16x32_bf16 v[22:25], v[168:171], v[202:205], 0
	v_mfma_f32_16x16x32_bf16 v[14:17], v[178:181], v[202:205], 0
	v_mfma_f32_16x16x32_bf16 v[6:9], v[168:171], v[210:213], 0
	v_mfma_f32_16x16x32_bf16 v[2:5], v[178:181], v[210:213], 0
	v_mfma_f32_16x16x32_bf16 v[54:57], v[172:175], v[190:193], v[54:57]
	v_mfma_f32_16x16x32_bf16 v[46:49], v[182:185], v[190:193], v[46:49]
	v_mfma_f32_16x16x32_bf16 v[38:41], v[172:175], v[198:201], v[38:41]
	v_mfma_f32_16x16x32_bf16 v[30:33], v[182:185], v[198:201], v[30:33]
	v_mfma_f32_16x16x32_bf16 v[22:25], v[172:175], v[206:209], v[22:25]
	v_mfma_f32_16x16x32_bf16 v[14:17], v[182:185], v[206:209], v[14:17]
	v_mfma_f32_16x16x32_bf16 v[6:9], v[172:175], v[214:217], v[6:9]
	v_mfma_f32_16x16x32_bf16 v[2:5], v[182:185], v[214:217], v[2:5]
	s_setprio 0
	s_barrier
	s_add_i32 s57, 0, 0x18000
	v_add_u32_e32 v151, s57, v146
	s_add_i32 s58, 0, 0x1c000
	ds_read_b128 v[152:155], v151
	ds_read_b128 v[156:159], v151 offset:1024
	ds_read_b128 v[160:163], v151 offset:2048
	ds_read_b128 v[164:167], v151 offset:3072
	v_add_u32_e32 v151, s58, v146
	ds_read_b128 v[168:171], v151
	ds_read_b128 v[172:175], v151 offset:1024
	ds_read_b128 v[178:181], v151 offset:2048
	ds_read_b128 v[182:185], v151 offset:3072
	s_add_u32 s2, s2, 0x40000
	s_addc_u32 s3, s3, 0
	s_mov_b32 m0, s41
	v_lshl_add_u64 v[224:225], s[2:3], 0, v[130:131]
	ds_read_b128 v[186:189], v150 offset:32768
	ds_read_b128 v[190:193], v150 offset:33792
	ds_read_b128 v[194:197], v150 offset:34816
	ds_read_b128 v[198:201], v150 offset:35840
	ds_read_b128 v[202:205], v150 offset:36864
	ds_read_b128 v[206:209], v150 offset:37888
	ds_read_b128 v[210:213], v150 offset:38912
	ds_read_b128 v[214:217], v150 offset:39936
	global_load_lds_dwordx4 v[224:225], off
	v_lshl_add_u64 v[224:225], s[2:3], 0, v[134:135]
	s_mov_b32 m0, s42
	s_nop 0
	global_load_lds_dwordx4 v[224:225], off
	s_waitcnt vmcnt(8)
	s_waitcnt lgkmcnt(0)
	s_barrier
	s_setprio 1
	s_waitcnt lgkmcnt(0)
	v_mfma_f32_16x16x32_bf16 v[126:129], v[152:155], v[186:189], v[126:129]
	v_mfma_f32_16x16x32_bf16 v[122:125], v[160:163], v[186:189], v[122:125]
	v_mfma_f32_16x16x32_bf16 v[114:117], v[152:155], v[194:197], v[114:117]
	v_mfma_f32_16x16x32_bf16 v[106:109], v[160:163], v[194:197], v[106:109]
	v_mfma_f32_16x16x32_bf16 v[98:101], v[152:155], v[202:205], v[98:101]
	v_mfma_f32_16x16x32_bf16 v[90:93], v[160:163], v[202:205], v[90:93]
	v_mfma_f32_16x16x32_bf16 v[82:85], v[152:155], v[210:213], v[82:85]
	v_mfma_f32_16x16x32_bf16 v[74:77], v[160:163], v[210:213], v[74:77]
	v_mfma_f32_16x16x32_bf16 v[126:129], v[156:159], v[190:193], v[126:129]
	v_mfma_f32_16x16x32_bf16 v[122:125], v[164:167], v[190:193], v[122:125]
	v_mfma_f32_16x16x32_bf16 v[114:117], v[156:159], v[198:201], v[114:117]
	v_mfma_f32_16x16x32_bf16 v[106:109], v[164:167], v[198:201], v[106:109]
	v_mfma_f32_16x16x32_bf16 v[98:101], v[156:159], v[206:209], v[98:101]
	v_mfma_f32_16x16x32_bf16 v[90:93], v[164:167], v[206:209], v[90:93]
	v_mfma_f32_16x16x32_bf16 v[82:85], v[156:159], v[214:217], v[82:85]
	v_mfma_f32_16x16x32_bf16 v[74:77], v[164:167], v[214:217], v[74:77]
	s_setprio 0
	s_setprio 1
	v_mfma_f32_16x16x32_bf16 v[118:121], v[168:171], v[186:189], v[118:121]
	v_mfma_f32_16x16x32_bf16 v[110:113], v[178:181], v[186:189], v[110:113]
	v_mfma_f32_16x16x32_bf16 v[102:105], v[168:171], v[194:197], v[102:105]
	v_mfma_f32_16x16x32_bf16 v[94:97], v[178:181], v[194:197], v[94:97]
	v_mfma_f32_16x16x32_bf16 v[86:89], v[168:171], v[202:205], v[86:89]
	v_mfma_f32_16x16x32_bf16 v[78:81], v[178:181], v[202:205], v[78:81]
	v_mfma_f32_16x16x32_bf16 v[70:73], v[168:171], v[210:213], v[70:73]
	v_mfma_f32_16x16x32_bf16 v[66:69], v[178:181], v[210:213], v[66:69]
	v_mfma_f32_16x16x32_bf16 v[118:121], v[172:175], v[190:193], v[118:121]
	v_mfma_f32_16x16x32_bf16 v[110:113], v[182:185], v[190:193], v[110:113]
	v_mfma_f32_16x16x32_bf16 v[102:105], v[172:175], v[198:201], v[102:105]
	v_mfma_f32_16x16x32_bf16 v[94:97], v[182:185], v[198:201], v[94:97]
	v_mfma_f32_16x16x32_bf16 v[86:89], v[172:175], v[206:209], v[86:89]
	v_mfma_f32_16x16x32_bf16 v[78:81], v[182:185], v[206:209], v[78:81]
	v_mfma_f32_16x16x32_bf16 v[70:73], v[172:175], v[214:217], v[70:73]
	v_mfma_f32_16x16x32_bf16 v[66:69], v[182:185], v[214:217], v[66:69]
	s_setprio 0
	s_barrier
	s_add_i32 s2, s57, s39
	v_lshl_add_u64 v[144:145], v[144:145], 0, s[6:7]
	s_mov_b32 m0, s2
	ds_read_b128 v[186:189], v150 offset:49152
	ds_read_b128 v[190:193], v150 offset:50176
	ds_read_b128 v[194:197], v150 offset:51200
	ds_read_b128 v[198:201], v150 offset:52224
	ds_read_b128 v[202:205], v150 offset:53248
	ds_read_b128 v[206:209], v150 offset:54272
	ds_read_b128 v[210:213], v150 offset:55296
	ds_read_b128 v[214:217], v150 offset:56320
	global_load_lds_dwordx4 v[144:145], off
	s_add_i32 m0, s2, 0x2000
	s_add_u32 s2, s34, 0x40080
	v_lshl_add_u64 v[144:145], v[218:219], 0, s[6:7]
	s_addc_u32 s3, s35, 0
	s_add_i32 s34, s58, s39
	global_load_lds_dwordx4 v[144:145], off
	v_lshl_add_u64 v[144:145], s[2:3], 0, v[132:133]
	s_mov_b32 m0, s34
	s_nop 0
	global_load_lds_dwordx4 v[144:145], off
	v_lshl_add_u64 v[144:145], s[2:3], 0, v[136:137]
	s_add_i32 m0, s34, 0x2000
	s_nop 0
	global_load_lds_dwordx4 v[144:145], off
	v_lshl_add_u64 v[144:145], v[220:221], 0, s[6:7]
	s_mov_b32 m0, s44
	s_nop 0
	global_load_lds_dwordx4 v[144:145], off
	v_lshl_add_u64 v[144:145], v[222:223], 0, s[6:7]
	s_mov_b32 m0, s45
	s_nop 0
	global_load_lds_dwordx4 v[144:145], off
	s_waitcnt vmcnt(8)
	s_waitcnt lgkmcnt(0)
	s_barrier
	s_setprio 1
	s_waitcnt lgkmcnt(0)
	v_mfma_f32_16x16x32_bf16 v[62:65], v[152:155], v[186:189], v[62:65]
	v_mfma_f32_16x16x32_bf16 v[58:61], v[160:163], v[186:189], v[58:61]
	v_mfma_f32_16x16x32_bf16 v[50:53], v[152:155], v[194:197], v[50:53]
	v_mfma_f32_16x16x32_bf16 v[42:45], v[160:163], v[194:197], v[42:45]
	v_mfma_f32_16x16x32_bf16 v[34:37], v[152:155], v[202:205], v[34:37]
	v_mfma_f32_16x16x32_bf16 v[26:29], v[160:163], v[202:205], v[26:29]
	v_mfma_f32_16x16x32_bf16 v[18:21], v[152:155], v[210:213], v[18:21]
	v_mfma_f32_16x16x32_bf16 v[10:13], v[160:163], v[210:213], v[10:13]
	v_mfma_f32_16x16x32_bf16 v[62:65], v[156:159], v[190:193], v[62:65]
	v_mfma_f32_16x16x32_bf16 v[58:61], v[164:167], v[190:193], v[58:61]
	v_mfma_f32_16x16x32_bf16 v[50:53], v[156:159], v[198:201], v[50:53]
	v_mfma_f32_16x16x32_bf16 v[42:45], v[164:167], v[198:201], v[42:45]
	v_mfma_f32_16x16x32_bf16 v[34:37], v[156:159], v[206:209], v[34:37]
	v_mfma_f32_16x16x32_bf16 v[26:29], v[164:167], v[206:209], v[26:29]
	v_mfma_f32_16x16x32_bf16 v[18:21], v[156:159], v[214:217], v[18:21]
	v_mfma_f32_16x16x32_bf16 v[10:13], v[164:167], v[214:217], v[10:13]
	s_setprio 0
	s_setprio 1
	v_mfma_f32_16x16x32_bf16 v[54:57], v[168:171], v[186:189], v[54:57]
	v_mfma_f32_16x16x32_bf16 v[46:49], v[178:181], v[186:189], v[46:49]
	v_mfma_f32_16x16x32_bf16 v[38:41], v[168:171], v[194:197], v[38:41]
	v_mfma_f32_16x16x32_bf16 v[30:33], v[178:181], v[194:197], v[30:33]
	v_mfma_f32_16x16x32_bf16 v[22:25], v[168:171], v[202:205], v[22:25]
	v_mfma_f32_16x16x32_bf16 v[14:17], v[178:181], v[202:205], v[14:17]
	v_mfma_f32_16x16x32_bf16 v[6:9], v[168:171], v[210:213], v[6:9]
	v_mfma_f32_16x16x32_bf16 v[2:5], v[178:181], v[210:213], v[2:5]
	v_mfma_f32_16x16x32_bf16 v[54:57], v[172:175], v[190:193], v[54:57]
	v_mfma_f32_16x16x32_bf16 v[46:49], v[182:185], v[190:193], v[46:49]
	v_mfma_f32_16x16x32_bf16 v[38:41], v[172:175], v[198:201], v[38:41]
	v_mfma_f32_16x16x32_bf16 v[30:33], v[182:185], v[198:201], v[30:33]
	v_mfma_f32_16x16x32_bf16 v[22:25], v[172:175], v[206:209], v[22:25]
	v_mfma_f32_16x16x32_bf16 v[14:17], v[182:185], v[206:209], v[14:17]
	v_mfma_f32_16x16x32_bf16 v[6:9], v[172:175], v[214:217], v[6:9]
	v_mfma_f32_16x16x32_bf16 v[2:5], v[182:185], v[214:217], v[2:5]
	s_setprio 0
	s_barrier
	s_add_i32 s56, s56, 2
	s_add_u32 s30, s30, 0x100
	s_addc_u32 s31, s31, 0
	s_add_u32 s54, s54, 0x100
	s_addc_u32 s55, s55, 0
	s_cmp_gt_u32 s56, 13
	s_cbranch_scc0 .LBB0_1098
	s_branch .Lpk1098_exit

.LBB0_1178:
	s_lshl_b64 s[2:3], s[22:23], 1
	v_readlane_b32 s28, v253, 52
	v_readlane_b32 s29, v253, 53
	s_add_u32 s28, s28, s2
	s_addc_u32 s29, s29, s3
	s_and_b64 s[2:3], s[26:27], exec
	s_cselect_b32 s19, s29, s37
	s_cselect_b32 s21, s28, s36
	s_lshl_b64 s[2:3], s[24:25], 1
	s_add_u32 s30, s35, s2
	s_addc_u32 s31, s40, s3
	s_and_b64 s[2:3], s[26:27], exec
	s_cselect_b32 s57, s31, s39
	s_cselect_b32 s58, s30, s38
	s_add_u32 s36, s36, 0x40080
	s_addc_u32 s37, s37, 0
	s_add_u32 s59, s38, 0x100
	s_addc_u32 s60, s39, 0
	s_mov_b32 s61, -2
.Lpk1179_peel:
	ds_read_b128 v[144:147], v158
	ds_read_b128 v[164:167], v158 offset:1024
	ds_read_b128 v[168:171], v158 offset:2048
	ds_read_b128 v[172:175], v158 offset:3072
	ds_read_b128 v[178:181], v159
	ds_read_b128 v[182:185], v159 offset:1024
	ds_read_b128 v[186:189], v159 offset:2048
	ds_read_b128 v[190:193], v159 offset:3072
	s_add_u32 s2, s36, 0xfffc0080
	s_addc_u32 s3, s37, -1
	s_cmp_eq_u32 s61, 12
	s_cselect_b32 s3, s19, s3
	s_cselect_b32 s2, s21, s2
	s_cselect_b32 s39, s57, s60
	s_cselect_b32 s38, s58, s59
	v_lshl_add_u64 v[226:227], s[36:37], 0, v[138:139]
	s_add_i32 m0, s42, 0xc000
	ds_read_b128 v[194:197], v160
	ds_read_b128 v[198:201], v160 offset:1024
	ds_read_b128 v[202:205], v160 offset:2048
	ds_read_b128 v[206:209], v160 offset:3072
	ds_read_b128 v[210:213], v160 offset:4096
	ds_read_b128 v[214:217], v160 offset:5120
	ds_read_b128 v[218:221], v160 offset:6144
	ds_read_b128 v[222:225], v160 offset:7168
	global_load_lds_dwordx4 v[226:227], off
	v_lshl_add_u64 v[226:227], s[36:37], 0, v[140:141]
	s_add_i32 m0, s42, 0xe000
	s_nop 0
	global_load_lds_dwordx4 v[226:227], off
	s_waitcnt vmcnt(8)
	s_waitcnt lgkmcnt(0)
	s_barrier
	s_setprio 1
	s_waitcnt lgkmcnt(0)
	v_mfma_f32_16x16x32_bf16 v[126:129], v[144:147], v[194:197], 0
	v_mfma_f32_16x16x32_bf16 v[122:125], v[168:171], v[194:197], 0
	v_mfma_f32_16x16x32_bf16 v[114:117], v[144:147], v[202:205], 0
	v_mfma_f32_16x16x32_bf16 v[106:109], v[168:171], v[202:205], 0
	v_mfma_f32_16x16x32_bf16 v[98:101], v[144:147], v[210:213], 0
	v_mfma_f32_16x16x32_bf16 v[90:93], v[168:171], v[210:213], 0
	v_mfma_f32_16x16x32_bf16 v[82:85], v[144:147], v[218:221], 0
	v_mfma_f32_16x16x32_bf16 v[74:77], v[168:171], v[218:221], 0
	v_mfma_f32_16x16x32_bf16 v[126:129], v[164:167], v[198:201], v[126:129]
	v_mfma_f32_16x16x32_bf16 v[122:125], v[172:175], v[198:201], v[122:125]
	v_mfma_f32_16x16x32_bf16 v[114:117], v[164:167], v[206:209], v[114:117]
	v_mfma_f32_16x16x32_bf16 v[106:109], v[172:175], v[206:209], v[106:109]
	v_mfma_f32_16x16x32_bf16 v[98:101], v[164:167], v[214:217], v[98:101]
	v_mfma_f32_16x16x32_bf16 v[90:93], v[172:175], v[214:217], v[90:93]
	v_mfma_f32_16x16x32_bf16 v[82:85], v[164:167], v[222:225], v[82:85]
	v_mfma_f32_16x16x32_bf16 v[74:77], v[172:175], v[222:225], v[74:77]
	s_setprio 0
	s_setprio 1
	v_mfma_f32_16x16x32_bf16 v[118:121], v[178:181], v[194:197], 0
	v_mfma_f32_16x16x32_bf16 v[110:113], v[186:189], v[194:197], 0
	v_mfma_f32_16x16x32_bf16 v[102:105], v[178:181], v[202:205], 0
	v_mfma_f32_16x16x32_bf16 v[94:97], v[186:189], v[202:205], 0
	v_mfma_f32_16x16x32_bf16 v[86:89], v[178:181], v[210:213], 0
	v_mfma_f32_16x16x32_bf16 v[78:81], v[186:189], v[210:213], 0
	v_mfma_f32_16x16x32_bf16 v[70:73], v[178:181], v[218:221], 0
	v_mfma_f32_16x16x32_bf16 v[66:69], v[186:189], v[218:221], 0
	v_mfma_f32_16x16x32_bf16 v[118:121], v[182:185], v[198:201], v[118:121]
	v_mfma_f32_16x16x32_bf16 v[110:113], v[190:193], v[198:201], v[110:113]
	v_mfma_f32_16x16x32_bf16 v[102:105], v[182:185], v[206:209], v[102:105]
	v_mfma_f32_16x16x32_bf16 v[94:97], v[190:193], v[206:209], v[94:97]
	v_mfma_f32_16x16x32_bf16 v[86:89], v[182:185], v[214:217], v[86:89]
	v_mfma_f32_16x16x32_bf16 v[78:81], v[190:193], v[214:217], v[78:81]
	v_mfma_f32_16x16x32_bf16 v[70:73], v[182:185], v[222:225], v[70:73]
	v_mfma_f32_16x16x32_bf16 v[66:69], v[190:193], v[222:225], v[66:69]
	s_setprio 0
	s_barrier
	s_add_i32 s62, s51, s41
	v_lshl_add_u64 v[226:227], s[38:39], 0, v[132:133]
	s_mov_b32 m0, s62
	ds_read_b128 v[194:197], v160 offset:16384
	ds_read_b128 v[198:201], v160 offset:17408
	ds_read_b128 v[202:205], v160 offset:18432
	ds_read_b128 v[206:209], v160 offset:19456
	ds_read_b128 v[210:213], v160 offset:20480
	ds_read_b128 v[214:217], v160 offset:21504
	ds_read_b128 v[218:221], v160 offset:22528
	ds_read_b128 v[222:225], v160 offset:23552
	global_load_lds_dwordx4 v[226:227], off
	s_add_i32 m0, s62, 0x2000
	s_add_u32 s62, s38, 0x40000
	v_lshl_add_u64 v[228:229], s[38:39], 0, v[136:137]
	s_addc_u32 s63, s39, 0
	s_add_i32 s64, s52, s41
	global_load_lds_dwordx4 v[228:229], off
	v_lshl_add_u64 v[230:231], s[62:63], 0, v[132:133]
	s_mov_b32 m0, s64
	v_lshl_add_u64 v[232:233], s[2:3], 0, v[134:135]
	global_load_lds_dwordx4 v[230:231], off
	v_lshl_add_u64 v[230:231], s[62:63], 0, v[136:137]
	s_add_i32 m0, s64, 0x2000
	s_nop 0
	global_load_lds_dwordx4 v[230:231], off
	v_lshl_add_u64 v[230:231], s[2:3], 0, v[130:131]
	s_mov_b32 m0, s42
	s_nop 0
	global_load_lds_dwordx4 v[230:231], off
	s_mov_b32 m0, s43
	s_nop 0
	global_load_lds_dwordx4 v[232:233], off
	s_waitcnt vmcnt(8)
	s_waitcnt lgkmcnt(0)
	s_barrier
	s_setprio 1
	s_waitcnt lgkmcnt(0)
	v_mfma_f32_16x16x32_bf16 v[62:65], v[144:147], v[194:197], 0
	v_mfma_f32_16x16x32_bf16 v[58:61], v[168:171], v[194:197], 0
	v_mfma_f32_16x16x32_bf16 v[50:53], v[144:147], v[202:205], 0
	v_mfma_f32_16x16x32_bf16 v[42:45], v[168:171], v[202:205], 0
	v_mfma_f32_16x16x32_bf16 v[34:37], v[144:147], v[210:213], 0
	v_mfma_f32_16x16x32_bf16 v[26:29], v[168:171], v[210:213], 0
	v_mfma_f32_16x16x32_bf16 v[18:21], v[144:147], v[218:221], 0
	v_mfma_f32_16x16x32_bf16 v[10:13], v[168:171], v[218:221], 0
	v_mfma_f32_16x16x32_bf16 v[62:65], v[164:167], v[198:201], v[62:65]
	v_mfma_f32_16x16x32_bf16 v[58:61], v[172:175], v[198:201], v[58:61]
	v_mfma_f32_16x16x32_bf16 v[50:53], v[164:167], v[206:209], v[50:53]
	v_mfma_f32_16x16x32_bf16 v[42:45], v[172:175], v[206:209], v[42:45]
	v_mfma_f32_16x16x32_bf16 v[34:37], v[164:167], v[214:217], v[34:37]
	v_mfma_f32_16x16x32_bf16 v[26:29], v[172:175], v[214:217], v[26:29]
	v_mfma_f32_16x16x32_bf16 v[18:21], v[164:167], v[222:225], v[18:21]
	v_mfma_f32_16x16x32_bf16 v[10:13], v[172:175], v[222:225], v[10:13]
	s_setprio 0
	s_setprio 1
	v_mfma_f32_16x16x32_bf16 v[54:57], v[178:181], v[194:197], 0
	v_mfma_f32_16x16x32_bf16 v[46:49], v[186:189], v[194:197], 0
	v_mfma_f32_16x16x32_bf16 v[38:41], v[178:181], v[202:205], 0
	v_mfma_f32_16x16x32_bf16 v[30:33], v[186:189], v[202:205], 0
	v_mfma_f32_16x16x32_bf16 v[22:25], v[178:181], v[210:213], 0
	v_mfma_f32_16x16x32_bf16 v[14:17], v[186:189], v[210:213], 0
	v_mfma_f32_16x16x32_bf16 v[6:9], v[178:181], v[218:221], 0
	v_mfma_f32_16x16x32_bf16 v[2:5], v[186:189], v[218:221], 0
	v_mfma_f32_16x16x32_bf16 v[54:57], v[182:185], v[198:201], v[54:57]
	v_mfma_f32_16x16x32_bf16 v[46:49], v[190:193], v[198:201], v[46:49]
	v_mfma_f32_16x16x32_bf16 v[38:41], v[182:185], v[206:209], v[38:41]
	v_mfma_f32_16x16x32_bf16 v[30:33], v[190:193], v[206:209], v[30:33]
	v_mfma_f32_16x16x32_bf16 v[22:25], v[182:185], v[214:217], v[22:25]
	v_mfma_f32_16x16x32_bf16 v[14:17], v[190:193], v[214:217], v[14:17]
	v_mfma_f32_16x16x32_bf16 v[6:9], v[182:185], v[222:225], v[6:9]
	v_mfma_f32_16x16x32_bf16 v[2:5], v[190:193], v[222:225], v[2:5]
	s_setprio 0
	s_barrier
	s_add_i32 s62, 0, 0x18000
	v_add_u32_e32 v163, s62, v148
	s_add_i32 s63, 0, 0x1c000
	ds_read_b128 v[144:147], v163
	ds_read_b128 v[164:167], v163 offset:1024
	ds_read_b128 v[168:171], v163 offset:2048
	ds_read_b128 v[172:175], v163 offset:3072
	v_add_u32_e32 v163, s63, v148
	ds_read_b128 v[178:181], v163
	ds_read_b128 v[182:185], v163 offset:1024
	ds_read_b128 v[186:189], v163 offset:2048
	ds_read_b128 v[190:193], v163 offset:3072
	s_add_u32 s2, s2, 0x40000
	s_addc_u32 s3, s3, 0
	s_mov_b32 m0, s44
	v_lshl_add_u64 v[234:235], s[2:3], 0, v[130:131]
	ds_read_b128 v[194:197], v160 offset:32768
	ds_read_b128 v[198:201], v160 offset:33792
	ds_read_b128 v[202:205], v160 offset:34816
	ds_read_b128 v[206:209], v160 offset:35840
	ds_read_b128 v[210:213], v160 offset:36864
	ds_read_b128 v[214:217], v160 offset:37888
	ds_read_b128 v[218:221], v160 offset:38912
	ds_read_b128 v[222:225], v160 offset:39936
	global_load_lds_dwordx4 v[234:235], off
	v_lshl_add_u64 v[234:235], s[2:3], 0, v[134:135]
	s_mov_b32 m0, s45
	s_nop 0
	global_load_lds_dwordx4 v[234:235], off
	s_waitcnt vmcnt(8)
	s_waitcnt lgkmcnt(0)
	s_barrier
	s_setprio 1
	s_waitcnt lgkmcnt(0)
	v_mfma_f32_16x16x32_bf16 v[126:129], v[144:147], v[194:197], v[126:129]
	v_mfma_f32_16x16x32_bf16 v[122:125], v[168:171], v[194:197], v[122:125]
	v_mfma_f32_16x16x32_bf16 v[114:117], v[144:147], v[202:205], v[114:117]
	v_mfma_f32_16x16x32_bf16 v[106:109], v[168:171], v[202:205], v[106:109]
	v_mfma_f32_16x16x32_bf16 v[98:101], v[144:147], v[210:213], v[98:101]
	v_mfma_f32_16x16x32_bf16 v[90:93], v[168:171], v[210:213], v[90:93]
	v_mfma_f32_16x16x32_bf16 v[82:85], v[144:147], v[218:221], v[82:85]
	v_mfma_f32_16x16x32_bf16 v[74:77], v[168:171], v[218:221], v[74:77]
	v_mfma_f32_16x16x32_bf16 v[126:129], v[164:167], v[198:201], v[126:129]
	v_mfma_f32_16x16x32_bf16 v[122:125], v[172:175], v[198:201], v[122:125]
	v_mfma_f32_16x16x32_bf16 v[114:117], v[164:167], v[206:209], v[114:117]
	v_mfma_f32_16x16x32_bf16 v[106:109], v[172:175], v[206:209], v[106:109]
	v_mfma_f32_16x16x32_bf16 v[98:101], v[164:167], v[214:217], v[98:101]
	v_mfma_f32_16x16x32_bf16 v[90:93], v[172:175], v[214:217], v[90:93]
	v_mfma_f32_16x16x32_bf16 v[82:85], v[164:167], v[222:225], v[82:85]
	v_mfma_f32_16x16x32_bf16 v[74:77], v[172:175], v[222:225], v[74:77]
	s_setprio 0
	s_setprio 1
	v_mfma_f32_16x16x32_bf16 v[118:121], v[178:181], v[194:197], v[118:121]
	v_mfma_f32_16x16x32_bf16 v[110:113], v[186:189], v[194:197], v[110:113]
	v_mfma_f32_16x16x32_bf16 v[102:105], v[178:181], v[202:205], v[102:105]
	v_mfma_f32_16x16x32_bf16 v[94:97], v[186:189], v[202:205], v[94:97]
	v_mfma_f32_16x16x32_bf16 v[86:89], v[178:181], v[210:213], v[86:89]
	v_mfma_f32_16x16x32_bf16 v[78:81], v[186:189], v[210:213], v[78:81]
	v_mfma_f32_16x16x32_bf16 v[70:73], v[178:181], v[218:221], v[70:73]
	v_mfma_f32_16x16x32_bf16 v[66:69], v[186:189], v[218:221], v[66:69]
	v_mfma_f32_16x16x32_bf16 v[118:121], v[182:185], v[198:201], v[118:121]
	v_mfma_f32_16x16x32_bf16 v[110:113], v[190:193], v[198:201], v[110:113]
	v_mfma_f32_16x16x32_bf16 v[102:105], v[182:185], v[206:209], v[102:105]
	v_mfma_f32_16x16x32_bf16 v[94:97], v[190:193], v[206:209], v[94:97]
	v_mfma_f32_16x16x32_bf16 v[86:89], v[182:185], v[214:217], v[86:89]
	v_mfma_f32_16x16x32_bf16 v[78:81], v[190:193], v[214:217], v[78:81]
	v_mfma_f32_16x16x32_bf16 v[70:73], v[182:185], v[222:225], v[70:73]
	v_mfma_f32_16x16x32_bf16 v[66:69], v[190:193], v[222:225], v[66:69]
	s_setprio 0
	s_barrier
	s_add_i32 s2, s62, s41
	v_lshl_add_u64 v[226:227], v[226:227], 0, s[10:11]
	s_mov_b32 m0, s2
	ds_read_b128 v[194:197], v160 offset:49152
	ds_read_b128 v[198:201], v160 offset:50176
	ds_read_b128 v[202:205], v160 offset:51200
	ds_read_b128 v[206:209], v160 offset:52224
	ds_read_b128 v[210:213], v160 offset:53248
	ds_read_b128 v[214:217], v160 offset:54272
	ds_read_b128 v[218:221], v160 offset:55296
	ds_read_b128 v[222:225], v160 offset:56320
	global_load_lds_dwordx4 v[226:227], off
	s_add_i32 m0, s2, 0x2000
	s_add_u32 s2, s38, 0x40080
	v_lshl_add_u64 v[226:227], v[228:229], 0, s[10:11]
	s_addc_u32 s3, s39, 0
	s_add_i32 s38, s63, s41
	global_load_lds_dwordx4 v[226:227], off
	v_lshl_add_u64 v[226:227], s[2:3], 0, v[132:133]
	s_mov_b32 m0, s38
	s_nop 0
	global_load_lds_dwordx4 v[226:227], off
	v_lshl_add_u64 v[226:227], s[2:3], 0, v[136:137]
	s_add_i32 m0, s38, 0x2000
	s_nop 0
	global_load_lds_dwordx4 v[226:227], off
	v_lshl_add_u64 v[226:227], v[230:231], 0, s[10:11]
	s_mov_b32 m0, s47
	s_nop 0
	global_load_lds_dwordx4 v[226:227], off
	v_lshl_add_u64 v[226:227], v[232:233], 0, s[10:11]
	s_mov_b32 m0, s48
	s_nop 0
	global_load_lds_dwordx4 v[226:227], off
	s_waitcnt vmcnt(8)
	s_waitcnt lgkmcnt(0)
	s_barrier
	s_setprio 1
	s_waitcnt lgkmcnt(0)
	v_mfma_f32_16x16x32_bf16 v[62:65], v[144:147], v[194:197], v[62:65]
	v_mfma_f32_16x16x32_bf16 v[58:61], v[168:171], v[194:197], v[58:61]
	v_mfma_f32_16x16x32_bf16 v[50:53], v[144:147], v[202:205], v[50:53]
	v_mfma_f32_16x16x32_bf16 v[42:45], v[168:171], v[202:205], v[42:45]
	v_mfma_f32_16x16x32_bf16 v[34:37], v[144:147], v[210:213], v[34:37]
	v_mfma_f32_16x16x32_bf16 v[26:29], v[168:171], v[210:213], v[26:29]
	v_mfma_f32_16x16x32_bf16 v[18:21], v[144:147], v[218:221], v[18:21]
	v_mfma_f32_16x16x32_bf16 v[10:13], v[168:171], v[218:221], v[10:13]
	v_mfma_f32_16x16x32_bf16 v[62:65], v[164:167], v[198:201], v[62:65]
	v_mfma_f32_16x16x32_bf16 v[58:61], v[172:175], v[198:201], v[58:61]
	v_mfma_f32_16x16x32_bf16 v[50:53], v[164:167], v[206:209], v[50:53]
	v_mfma_f32_16x16x32_bf16 v[42:45], v[172:175], v[206:209], v[42:45]
	v_mfma_f32_16x16x32_bf16 v[34:37], v[164:167], v[214:217], v[34:37]
	v_mfma_f32_16x16x32_bf16 v[26:29], v[172:175], v[214:217], v[26:29]
	v_mfma_f32_16x16x32_bf16 v[18:21], v[164:167], v[222:225], v[18:21]
	v_mfma_f32_16x16x32_bf16 v[10:13], v[172:175], v[222:225], v[10:13]
	s_setprio 0
	s_setprio 1
	v_mfma_f32_16x16x32_bf16 v[54:57], v[178:181], v[194:197], v[54:57]
	v_mfma_f32_16x16x32_bf16 v[46:49], v[186:189], v[194:197], v[46:49]
	v_mfma_f32_16x16x32_bf16 v[38:41], v[178:181], v[202:205], v[38:41]
	v_mfma_f32_16x16x32_bf16 v[30:33], v[186:189], v[202:205], v[30:33]
	v_mfma_f32_16x16x32_bf16 v[22:25], v[178:181], v[210:213], v[22:25]
	v_mfma_f32_16x16x32_bf16 v[14:17], v[186:189], v[210:213], v[14:17]
	v_mfma_f32_16x16x32_bf16 v[6:9], v[178:181], v[218:221], v[6:9]
	v_mfma_f32_16x16x32_bf16 v[2:5], v[186:189], v[218:221], v[2:5]
	v_mfma_f32_16x16x32_bf16 v[54:57], v[182:185], v[198:201], v[54:57]
	v_mfma_f32_16x16x32_bf16 v[46:49], v[190:193], v[198:201], v[46:49]
	v_mfma_f32_16x16x32_bf16 v[38:41], v[182:185], v[206:209], v[38:41]
	v_mfma_f32_16x16x32_bf16 v[30:33], v[190:193], v[206:209], v[30:33]
	v_mfma_f32_16x16x32_bf16 v[22:25], v[182:185], v[214:217], v[22:25]
	v_mfma_f32_16x16x32_bf16 v[14:17], v[190:193], v[214:217], v[14:17]
	v_mfma_f32_16x16x32_bf16 v[6:9], v[182:185], v[222:225], v[6:9]
	v_mfma_f32_16x16x32_bf16 v[2:5], v[190:193], v[222:225], v[2:5]
	s_setprio 0
	s_barrier
	s_add_i32 s61, s61, 2
	s_add_u32 s36, s36, 0x100
	s_addc_u32 s37, s37, 0
	s_add_u32 s59, s59, 0x100
	s_addc_u32 s60, s60, 0
	s_cmp_gt_u32 s61, 13
	s_cbranch_scc0 .LBB0_1179
	s_branch .Lpk1179_exit

.Lpk1179_exit:
	s_and_b64 vcc, exec, s[12:13]
	s_cbranch_vccz .LBB0_1182
	s_barrier

.LBB0_1238:
	s_lshl_b64 s[2:3], s[22:23], 1
	s_add_u32 s28, s4, s2
	s_addc_u32 s29, s5, s3
	s_and_b64 s[2:3], s[26:27], exec
	s_cselect_b32 s19, s29, s37
	s_cselect_b32 s21, s28, s36
	s_lshl_b64 s[2:3], s[24:25], 1
	s_add_u32 s30, s41, s2
	s_addc_u32 s31, s42, s3
	s_and_b64 s[2:3], s[26:27], exec
	s_cselect_b32 s58, s31, s39
	s_cselect_b32 s59, s30, s38
	s_add_u32 s36, s36, 0x40080
	s_addc_u32 s37, s37, 0
	s_add_u32 s60, s38, 0x100
	s_addc_u32 s61, s39, 0
	s_mov_b32 s62, -2
.Lpk1239_peel:
	ds_read_b128 v[152:155], v148
	ds_read_b128 v[156:159], v148 offset:1024
	ds_read_b128 v[160:163], v148 offset:2048
	ds_read_b128 v[164:167], v148 offset:3072
	ds_read_b128 v[168:171], v149
	ds_read_b128 v[172:175], v149 offset:1024
	ds_read_b128 v[178:181], v149 offset:2048
	ds_read_b128 v[182:185], v149 offset:3072
	s_add_u32 s2, s36, 0xfffc0080
	s_addc_u32 s3, s37, -1
	s_cmp_eq_u32 s62, 12
	s_cselect_b32 s3, s19, s3
	s_cselect_b32 s2, s21, s2
	s_cselect_b32 s39, s58, s61
	s_cselect_b32 s38, s59, s60
	v_lshl_add_u64 v[144:145], s[36:37], 0, v[138:139]
	s_add_i32 m0, s44, 0xc000
	ds_read_b128 v[186:189], v150
	ds_read_b128 v[190:193], v150 offset:1024
	ds_read_b128 v[194:197], v150 offset:2048
	ds_read_b128 v[198:201], v150 offset:3072
	ds_read_b128 v[202:205], v150 offset:4096
	ds_read_b128 v[206:209], v150 offset:5120
	ds_read_b128 v[210:213], v150 offset:6144
	ds_read_b128 v[214:217], v150 offset:7168
	global_load_lds_dwordx4 v[144:145], off
	v_lshl_add_u64 v[144:145], s[36:37], 0, v[140:141]
	s_add_i32 m0, s44, 0xe000
	s_nop 0
	global_load_lds_dwordx4 v[144:145], off
	s_waitcnt vmcnt(8)
	s_waitcnt lgkmcnt(0)
	s_barrier
	s_setprio 1
	s_waitcnt lgkmcnt(0)
	v_mfma_f32_16x16x32_bf16 v[126:129], v[152:155], v[186:189], 0
	v_mfma_f32_16x16x32_bf16 v[122:125], v[160:163], v[186:189], 0
	v_mfma_f32_16x16x32_bf16 v[114:117], v[152:155], v[194:197], 0
	v_mfma_f32_16x16x32_bf16 v[106:109], v[160:163], v[194:197], 0
	v_mfma_f32_16x16x32_bf16 v[98:101], v[152:155], v[202:205], 0
	v_mfma_f32_16x16x32_bf16 v[90:93], v[160:163], v[202:205], 0
	v_mfma_f32_16x16x32_bf16 v[82:85], v[152:155], v[210:213], 0
	v_mfma_f32_16x16x32_bf16 v[74:77], v[160:163], v[210:213], 0
	v_mfma_f32_16x16x32_bf16 v[126:129], v[156:159], v[190:193], v[126:129]
	v_mfma_f32_16x16x32_bf16 v[122:125], v[164:167], v[190:193], v[122:125]
	v_mfma_f32_16x16x32_bf16 v[114:117], v[156:159], v[198:201], v[114:117]
	v_mfma_f32_16x16x32_bf16 v[106:109], v[164:167], v[198:201], v[106:109]
	v_mfma_f32_16x16x32_bf16 v[98:101], v[156:159], v[206:209], v[98:101]
	v_mfma_f32_16x16x32_bf16 v[90:93], v[164:167], v[206:209], v[90:93]
	v_mfma_f32_16x16x32_bf16 v[82:85], v[156:159], v[214:217], v[82:85]
	v_mfma_f32_16x16x32_bf16 v[74:77], v[164:167], v[214:217], v[74:77]
	s_setprio 0
	s_setprio 1
	v_mfma_f32_16x16x32_bf16 v[118:121], v[168:171], v[186:189], 0
	v_mfma_f32_16x16x32_bf16 v[110:113], v[178:181], v[186:189], 0
	v_mfma_f32_16x16x32_bf16 v[102:105], v[168:171], v[194:197], 0
	v_mfma_f32_16x16x32_bf16 v[94:97], v[178:181], v[194:197], 0
	v_mfma_f32_16x16x32_bf16 v[86:89], v[168:171], v[202:205], 0
	v_mfma_f32_16x16x32_bf16 v[78:81], v[178:181], v[202:205], 0
	v_mfma_f32_16x16x32_bf16 v[70:73], v[168:171], v[210:213], 0
	v_mfma_f32_16x16x32_bf16 v[66:69], v[178:181], v[210:213], 0
	v_mfma_f32_16x16x32_bf16 v[118:121], v[172:175], v[190:193], v[118:121]
	v_mfma_f32_16x16x32_bf16 v[110:113], v[182:185], v[190:193], v[110:113]
	v_mfma_f32_16x16x32_bf16 v[102:105], v[172:175], v[198:201], v[102:105]
	v_mfma_f32_16x16x32_bf16 v[94:97], v[182:185], v[198:201], v[94:97]
	v_mfma_f32_16x16x32_bf16 v[86:89], v[172:175], v[206:209], v[86:89]
	v_mfma_f32_16x16x32_bf16 v[78:81], v[182:185], v[206:209], v[78:81]
	v_mfma_f32_16x16x32_bf16 v[70:73], v[172:175], v[214:217], v[70:73]
	v_mfma_f32_16x16x32_bf16 v[66:69], v[182:185], v[214:217], v[66:69]
	s_setprio 0
	s_barrier
	s_add_i32 s63, s51, s43
	v_lshl_add_u64 v[144:145], s[38:39], 0, v[132:133]
	s_mov_b32 m0, s63
	ds_read_b128 v[186:189], v150 offset:16384
	ds_read_b128 v[190:193], v150 offset:17408
	ds_read_b128 v[194:197], v150 offset:18432
	ds_read_b128 v[198:201], v150 offset:19456
	ds_read_b128 v[202:205], v150 offset:20480
	ds_read_b128 v[206:209], v150 offset:21504
	ds_read_b128 v[210:213], v150 offset:22528
	ds_read_b128 v[214:217], v150 offset:23552
	global_load_lds_dwordx4 v[144:145], off
	s_add_i32 m0, s63, 0x2000
	s_add_u32 s64, s38, 0x40000
	v_lshl_add_u64 v[218:219], s[38:39], 0, v[136:137]
	s_addc_u32 s65, s39, 0
	s_add_i32 s63, s52, s43
	global_load_lds_dwordx4 v[218:219], off
	v_lshl_add_u64 v[220:221], s[64:65], 0, v[132:133]
	s_mov_b32 m0, s63
	v_lshl_add_u64 v[222:223], s[2:3], 0, v[134:135]
	global_load_lds_dwordx4 v[220:221], off
	v_lshl_add_u64 v[220:221], s[64:65], 0, v[136:137]
	s_add_i32 m0, s63, 0x2000
	s_nop 0
	global_load_lds_dwordx4 v[220:221], off
	v_lshl_add_u64 v[220:221], s[2:3], 0, v[130:131]
	s_mov_b32 m0, s44
	s_nop 0
	global_load_lds_dwordx4 v[220:221], off
	s_mov_b32 m0, s35
	s_nop 0
	global_load_lds_dwordx4 v[222:223], off
	s_waitcnt vmcnt(8)
	s_waitcnt lgkmcnt(0)
	s_barrier
	s_setprio 1
	s_waitcnt lgkmcnt(0)
	v_mfma_f32_16x16x32_bf16 v[62:65], v[152:155], v[186:189], 0
	v_mfma_f32_16x16x32_bf16 v[58:61], v[160:163], v[186:189], 0
	v_mfma_f32_16x16x32_bf16 v[50:53], v[152:155], v[194:197], 0
	v_mfma_f32_16x16x32_bf16 v[42:45], v[160:163], v[194:197], 0
	v_mfma_f32_16x16x32_bf16 v[34:37], v[152:155], v[202:205], 0
	v_mfma_f32_16x16x32_bf16 v[26:29], v[160:163], v[202:205], 0
	v_mfma_f32_16x16x32_bf16 v[18:21], v[152:155], v[210:213], 0
	v_mfma_f32_16x16x32_bf16 v[10:13], v[160:163], v[210:213], 0
	v_mfma_f32_16x16x32_bf16 v[62:65], v[156:159], v[190:193], v[62:65]
	v_mfma_f32_16x16x32_bf16 v[58:61], v[164:167], v[190:193], v[58:61]
	v_mfma_f32_16x16x32_bf16 v[50:53], v[156:159], v[198:201], v[50:53]
	v_mfma_f32_16x16x32_bf16 v[42:45], v[164:167], v[198:201], v[42:45]
	v_mfma_f32_16x16x32_bf16 v[34:37], v[156:159], v[206:209], v[34:37]
	v_mfma_f32_16x16x32_bf16 v[26:29], v[164:167], v[206:209], v[26:29]
	v_mfma_f32_16x16x32_bf16 v[18:21], v[156:159], v[214:217], v[18:21]
	v_mfma_f32_16x16x32_bf16 v[10:13], v[164:167], v[214:217], v[10:13]
	s_setprio 0
	s_setprio 1
	v_mfma_f32_16x16x32_bf16 v[54:57], v[168:171], v[186:189], 0
	v_mfma_f32_16x16x32_bf16 v[46:49], v[178:181], v[186:189], 0
	v_mfma_f32_16x16x32_bf16 v[38:41], v[168:171], v[194:197], 0
	v_mfma_f32_16x16x32_bf16 v[30:33], v[178:181], v[194:197], 0
	v_mfma_f32_16x16x32_bf16 v[22:25], v[168:171], v[202:205], 0
	v_mfma_f32_16x16x32_bf16 v[14:17], v[178:181], v[202:205], 0
	v_mfma_f32_16x16x32_bf16 v[6:9], v[168:171], v[210:213], 0
	v_mfma_f32_16x16x32_bf16 v[2:5], v[178:181], v[210:213], 0
	v_mfma_f32_16x16x32_bf16 v[54:57], v[172:175], v[190:193], v[54:57]
	v_mfma_f32_16x16x32_bf16 v[46:49], v[182:185], v[190:193], v[46:49]
	v_mfma_f32_16x16x32_bf16 v[38:41], v[172:175], v[198:201], v[38:41]
	v_mfma_f32_16x16x32_bf16 v[30:33], v[182:185], v[198:201], v[30:33]
	v_mfma_f32_16x16x32_bf16 v[22:25], v[172:175], v[206:209], v[22:25]
	v_mfma_f32_16x16x32_bf16 v[14:17], v[182:185], v[206:209], v[14:17]
	v_mfma_f32_16x16x32_bf16 v[6:9], v[172:175], v[214:217], v[6:9]
	v_mfma_f32_16x16x32_bf16 v[2:5], v[182:185], v[214:217], v[2:5]
	s_setprio 0
	s_barrier
	s_add_i32 s63, 0, 0x18000
	v_add_u32_e32 v151, s63, v146
	s_add_i32 s64, 0, 0x1c000
	ds_read_b128 v[152:155], v151
	ds_read_b128 v[156:159], v151 offset:1024
	ds_read_b128 v[160:163], v151 offset:2048
	ds_read_b128 v[164:167], v151 offset:3072
	v_add_u32_e32 v151, s64, v146
	ds_read_b128 v[168:171], v151
	ds_read_b128 v[172:175], v151 offset:1024
	ds_read_b128 v[178:181], v151 offset:2048
	ds_read_b128 v[182:185], v151 offset:3072
	s_add_u32 s2, s2, 0x40000
	s_addc_u32 s3, s3, 0
	s_mov_b32 m0, s45
	v_lshl_add_u64 v[224:225], s[2:3], 0, v[130:131]
	ds_read_b128 v[186:189], v150 offset:32768
	ds_read_b128 v[190:193], v150 offset:33792
	ds_read_b128 v[194:197], v150 offset:34816
	ds_read_b128 v[198:201], v150 offset:35840
	ds_read_b128 v[202:205], v150 offset:36864
	ds_read_b128 v[206:209], v150 offset:37888
	ds_read_b128 v[210:213], v150 offset:38912
	ds_read_b128 v[214:217], v150 offset:39936
	global_load_lds_dwordx4 v[224:225], off
	v_lshl_add_u64 v[224:225], s[2:3], 0, v[134:135]
	s_mov_b32 m0, s46
	s_nop 0
	global_load_lds_dwordx4 v[224:225], off
	s_waitcnt vmcnt(8)
	s_waitcnt lgkmcnt(0)
	s_barrier
	s_setprio 1
	s_waitcnt lgkmcnt(0)
	v_mfma_f32_16x16x32_bf16 v[126:129], v[152:155], v[186:189], v[126:129]
	v_mfma_f32_16x16x32_bf16 v[122:125], v[160:163], v[186:189], v[122:125]
	v_mfma_f32_16x16x32_bf16 v[114:117], v[152:155], v[194:197], v[114:117]
	v_mfma_f32_16x16x32_bf16 v[106:109], v[160:163], v[194:197], v[106:109]
	v_mfma_f32_16x16x32_bf16 v[98:101], v[152:155], v[202:205], v[98:101]
	v_mfma_f32_16x16x32_bf16 v[90:93], v[160:163], v[202:205], v[90:93]
	v_mfma_f32_16x16x32_bf16 v[82:85], v[152:155], v[210:213], v[82:85]
	v_mfma_f32_16x16x32_bf16 v[74:77], v[160:163], v[210:213], v[74:77]
	v_mfma_f32_16x16x32_bf16 v[126:129], v[156:159], v[190:193], v[126:129]
	v_mfma_f32_16x16x32_bf16 v[122:125], v[164:167], v[190:193], v[122:125]
	v_mfma_f32_16x16x32_bf16 v[114:117], v[156:159], v[198:201], v[114:117]
	v_mfma_f32_16x16x32_bf16 v[106:109], v[164:167], v[198:201], v[106:109]
	v_mfma_f32_16x16x32_bf16 v[98:101], v[156:159], v[206:209], v[98:101]
	v_mfma_f32_16x16x32_bf16 v[90:93], v[164:167], v[206:209], v[90:93]
	v_mfma_f32_16x16x32_bf16 v[82:85], v[156:159], v[214:217], v[82:85]
	v_mfma_f32_16x16x32_bf16 v[74:77], v[164:167], v[214:217], v[74:77]
	s_setprio 0
	s_setprio 1
	v_mfma_f32_16x16x32_bf16 v[118:121], v[168:171], v[186:189], v[118:121]
	v_mfma_f32_16x16x32_bf16 v[110:113], v[178:181], v[186:189], v[110:113]
	v_mfma_f32_16x16x32_bf16 v[102:105], v[168:171], v[194:197], v[102:105]
	v_mfma_f32_16x16x32_bf16 v[94:97], v[178:181], v[194:197], v[94:97]
	v_mfma_f32_16x16x32_bf16 v[86:89], v[168:171], v[202:205], v[86:89]
	v_mfma_f32_16x16x32_bf16 v[78:81], v[178:181], v[202:205], v[78:81]
	v_mfma_f32_16x16x32_bf16 v[70:73], v[168:171], v[210:213], v[70:73]
	v_mfma_f32_16x16x32_bf16 v[66:69], v[178:181], v[210:213], v[66:69]
	v_mfma_f32_16x16x32_bf16 v[118:121], v[172:175], v[190:193], v[118:121]
	v_mfma_f32_16x16x32_bf16 v[110:113], v[182:185], v[190:193], v[110:113]
	v_mfma_f32_16x16x32_bf16 v[102:105], v[172:175], v[198:201], v[102:105]
	v_mfma_f32_16x16x32_bf16 v[94:97], v[182:185], v[198:201], v[94:97]
	v_mfma_f32_16x16x32_bf16 v[86:89], v[172:175], v[206:209], v[86:89]
	v_mfma_f32_16x16x32_bf16 v[78:81], v[182:185], v[206:209], v[78:81]
	v_mfma_f32_16x16x32_bf16 v[70:73], v[172:175], v[214:217], v[70:73]
	v_mfma_f32_16x16x32_bf16 v[66:69], v[182:185], v[214:217], v[66:69]
	s_setprio 0
	s_barrier
	s_add_i32 s2, s63, s43
	v_lshl_add_u64 v[144:145], v[144:145], 0, s[8:9]
	s_mov_b32 m0, s2
	ds_read_b128 v[186:189], v150 offset:49152
	ds_read_b128 v[190:193], v150 offset:50176
	ds_read_b128 v[194:197], v150 offset:51200
	ds_read_b128 v[198:201], v150 offset:52224
	ds_read_b128 v[202:205], v150 offset:53248
	ds_read_b128 v[206:209], v150 offset:54272
	ds_read_b128 v[210:213], v150 offset:55296
	ds_read_b128 v[214:217], v150 offset:56320
	global_load_lds_dwordx4 v[144:145], off
	s_add_i32 m0, s2, 0x2000
	s_add_u32 s2, s38, 0x40080
	v_lshl_add_u64 v[144:145], v[218:219], 0, s[8:9]
	s_addc_u32 s3, s39, 0
	s_add_i32 s38, s64, s43
	global_load_lds_dwordx4 v[144:145], off
	v_lshl_add_u64 v[144:145], s[2:3], 0, v[132:133]
	s_mov_b32 m0, s38
	s_nop 0
	global_load_lds_dwordx4 v[144:145], off
	v_lshl_add_u64 v[144:145], s[2:3], 0, v[136:137]
	s_add_i32 m0, s38, 0x2000
	s_nop 0
	global_load_lds_dwordx4 v[144:145], off
	v_lshl_add_u64 v[144:145], v[220:221], 0, s[8:9]
	s_mov_b32 m0, s48
	s_nop 0
	global_load_lds_dwordx4 v[144:145], off
	v_lshl_add_u64 v[144:145], v[222:223], 0, s[8:9]
	s_mov_b32 m0, s49
	s_nop 0
	global_load_lds_dwordx4 v[144:145], off
	s_waitcnt vmcnt(8)
	s_waitcnt lgkmcnt(0)
	s_barrier
	s_setprio 1
	s_waitcnt lgkmcnt(0)
	v_mfma_f32_16x16x32_bf16 v[62:65], v[152:155], v[186:189], v[62:65]
	v_mfma_f32_16x16x32_bf16 v[58:61], v[160:163], v[186:189], v[58:61]
	v_mfma_f32_16x16x32_bf16 v[50:53], v[152:155], v[194:197], v[50:53]
	v_mfma_f32_16x16x32_bf16 v[42:45], v[160:163], v[194:197], v[42:45]
	v_mfma_f32_16x16x32_bf16 v[34:37], v[152:155], v[202:205], v[34:37]
	v_mfma_f32_16x16x32_bf16 v[26:29], v[160:163], v[202:205], v[26:29]
	v_mfma_f32_16x16x32_bf16 v[18:21], v[152:155], v[210:213], v[18:21]
	v_mfma_f32_16x16x32_bf16 v[10:13], v[160:163], v[210:213], v[10:13]
	v_mfma_f32_16x16x32_bf16 v[62:65], v[156:159], v[190:193], v[62:65]
	v_mfma_f32_16x16x32_bf16 v[58:61], v[164:167], v[190:193], v[58:61]
	v_mfma_f32_16x16x32_bf16 v[50:53], v[156:159], v[198:201], v[50:53]
	v_mfma_f32_16x16x32_bf16 v[42:45], v[164:167], v[198:201], v[42:45]
	v_mfma_f32_16x16x32_bf16 v[34:37], v[156:159], v[206:209], v[34:37]
	v_mfma_f32_16x16x32_bf16 v[26:29], v[164:167], v[206:209], v[26:29]
	v_mfma_f32_16x16x32_bf16 v[18:21], v[156:159], v[214:217], v[18:21]
	v_mfma_f32_16x16x32_bf16 v[10:13], v[164:167], v[214:217], v[10:13]
	s_setprio 0
	s_setprio 1
	v_mfma_f32_16x16x32_bf16 v[54:57], v[168:171], v[186:189], v[54:57]
	v_mfma_f32_16x16x32_bf16 v[46:49], v[178:181], v[186:189], v[46:49]
	v_mfma_f32_16x16x32_bf16 v[38:41], v[168:171], v[194:197], v[38:41]
	v_mfma_f32_16x16x32_bf16 v[30:33], v[178:181], v[194:197], v[30:33]
	v_mfma_f32_16x16x32_bf16 v[22:25], v[168:171], v[202:205], v[22:25]
	v_mfma_f32_16x16x32_bf16 v[14:17], v[178:181], v[202:205], v[14:17]
	v_mfma_f32_16x16x32_bf16 v[6:9], v[168:171], v[210:213], v[6:9]
	v_mfma_f32_16x16x32_bf16 v[2:5], v[178:181], v[210:213], v[2:5]
	v_mfma_f32_16x16x32_bf16 v[54:57], v[172:175], v[190:193], v[54:57]
	v_mfma_f32_16x16x32_bf16 v[46:49], v[182:185], v[190:193], v[46:49]
	v_mfma_f32_16x16x32_bf16 v[38:41], v[172:175], v[198:201], v[38:41]
	v_mfma_f32_16x16x32_bf16 v[30:33], v[182:185], v[198:201], v[30:33]
	v_mfma_f32_16x16x32_bf16 v[22:25], v[172:175], v[206:209], v[22:25]
	v_mfma_f32_16x16x32_bf16 v[14:17], v[182:185], v[206:209], v[14:17]
	v_mfma_f32_16x16x32_bf16 v[6:9], v[172:175], v[214:217], v[6:9]
	v_mfma_f32_16x16x32_bf16 v[2:5], v[182:185], v[214:217], v[2:5]
	s_setprio 0
	s_barrier
	s_add_i32 s62, s62, 2
	s_add_u32 s36, s36, 0x100
	s_addc_u32 s37, s37, 0
	s_add_u32 s60, s60, 0x100
	s_addc_u32 s61, s61, 0
	s_cmp_gt_u32 s62, 13
	s_cbranch_scc0 .LBB0_1239
	s_branch .Lpk1239_exit

.Lpk1239_exit:
	s_and_b64 vcc, exec, s[10:11]
	s_cbranch_vccz .LBB0_1242
	s_barrier

.LBB0_1302:
	s_lshl_b64 s[2:3], s[14:15], 1
	v_readlane_b32 s20, v253, 52
	v_readlane_b32 s21, v253, 53
	s_add_u32 s20, s20, s2
	s_addc_u32 s21, s21, s3
	s_and_b64 s[2:3], s[18:19], exec
	s_cselect_b32 s11, s21, s27
	s_cselect_b32 s13, s20, s26
	s_lshl_b64 s[2:3], s[16:17], 1
	s_add_u32 s22, s48, s2
	s_addc_u32 s23, s49, s3
	s_and_b64 s[2:3], s[18:19], exec
	s_cselect_b32 s47, s23, s29
	s_cselect_b32 s52, s22, s28
	s_add_u32 s26, s26, 0x40080
	s_addc_u32 s27, s27, 0
	s_add_u32 s53, s28, 0x100
	s_addc_u32 s54, s29, 0
	s_mov_b32 s55, -2
.Lpk1303_peel:
	ds_read_b128 v[166:169], v139
	ds_read_b128 v[170:173], v139 offset:1024
	ds_read_b128 v[178:181], v139 offset:2048
	ds_read_b128 v[182:185], v139 offset:3072
	ds_read_b128 v[186:189], v163
	ds_read_b128 v[190:193], v163 offset:1024
	ds_read_b128 v[194:197], v163 offset:2048
	ds_read_b128 v[198:201], v163 offset:3072
	s_add_u32 s2, s26, 0xfffc0080
	s_addc_u32 s3, s27, -1
	s_cmp_eq_u32 s55, 12
	s_cselect_b32 s3, s11, s3
	s_cselect_b32 s2, s13, s2
	s_cselect_b32 s29, s47, s54
	s_cselect_b32 s28, s52, s53
	v_lshl_add_u64 v[148:149], s[26:27], 0, v[142:143]
	s_add_i32 m0, s34, 0xc000
	ds_read_b128 v[202:205], v164
	ds_read_b128 v[206:209], v164 offset:1024
	ds_read_b128 v[210:213], v164 offset:2048
	ds_read_b128 v[214:217], v164 offset:3072
	ds_read_b128 v[218:221], v164 offset:4096
	ds_read_b128 v[222:225], v164 offset:5120
	ds_read_b128 v[226:229], v164 offset:6144
	ds_read_b128 v[230:233], v164 offset:7168
	global_load_lds_dwordx4 v[148:149], off
	v_lshl_add_u64 v[148:149], s[26:27], 0, v[144:145]
	s_add_i32 m0, s34, 0xe000
	s_nop 0
	global_load_lds_dwordx4 v[148:149], off
	s_waitcnt vmcnt(8)
	s_waitcnt lgkmcnt(0)
	s_barrier
	s_setprio 1
	s_waitcnt lgkmcnt(0)
	v_mfma_f32_16x16x32_bf16 v[126:129], v[166:169], v[202:205], 0
	v_mfma_f32_16x16x32_bf16 v[122:125], v[178:181], v[202:205], 0
	v_mfma_f32_16x16x32_bf16 v[110:113], v[166:169], v[210:213], 0
	v_mfma_f32_16x16x32_bf16 v[106:109], v[178:181], v[210:213], 0
	v_mfma_f32_16x16x32_bf16 v[94:97], v[166:169], v[218:221], 0
	v_mfma_f32_16x16x32_bf16 v[90:93], v[178:181], v[218:221], 0
	v_mfma_f32_16x16x32_bf16 v[78:81], v[166:169], v[226:229], 0
	v_mfma_f32_16x16x32_bf16 v[74:77], v[178:181], v[226:229], 0
	v_mfma_f32_16x16x32_bf16 v[126:129], v[170:173], v[206:209], v[126:129]
	v_mfma_f32_16x16x32_bf16 v[122:125], v[182:185], v[206:209], v[122:125]
	v_mfma_f32_16x16x32_bf16 v[110:113], v[170:173], v[214:217], v[110:113]
	v_mfma_f32_16x16x32_bf16 v[106:109], v[182:185], v[214:217], v[106:109]
	v_mfma_f32_16x16x32_bf16 v[94:97], v[170:173], v[222:225], v[94:97]
	v_mfma_f32_16x16x32_bf16 v[90:93], v[182:185], v[222:225], v[90:93]
	v_mfma_f32_16x16x32_bf16 v[78:81], v[170:173], v[230:233], v[78:81]
	v_mfma_f32_16x16x32_bf16 v[74:77], v[182:185], v[230:233], v[74:77]
	s_setprio 0
	s_setprio 1
	v_mfma_f32_16x16x32_bf16 v[118:121], v[186:189], v[202:205], 0
	v_mfma_f32_16x16x32_bf16 v[114:117], v[194:197], v[202:205], 0
	v_mfma_f32_16x16x32_bf16 v[102:105], v[186:189], v[210:213], 0
	v_mfma_f32_16x16x32_bf16 v[98:101], v[194:197], v[210:213], 0
	v_mfma_f32_16x16x32_bf16 v[86:89], v[186:189], v[218:221], 0
	v_mfma_f32_16x16x32_bf16 v[82:85], v[194:197], v[218:221], 0
	v_mfma_f32_16x16x32_bf16 v[70:73], v[186:189], v[226:229], 0
	v_mfma_f32_16x16x32_bf16 v[66:69], v[194:197], v[226:229], 0
	v_mfma_f32_16x16x32_bf16 v[118:121], v[190:193], v[206:209], v[118:121]
	v_mfma_f32_16x16x32_bf16 v[114:117], v[198:201], v[206:209], v[114:117]
	v_mfma_f32_16x16x32_bf16 v[102:105], v[190:193], v[214:217], v[102:105]
	v_mfma_f32_16x16x32_bf16 v[98:101], v[198:201], v[214:217], v[98:101]
	v_mfma_f32_16x16x32_bf16 v[86:89], v[190:193], v[222:225], v[86:89]
	v_mfma_f32_16x16x32_bf16 v[82:85], v[198:201], v[222:225], v[82:85]
	v_mfma_f32_16x16x32_bf16 v[70:73], v[190:193], v[230:233], v[70:73]
	v_mfma_f32_16x16x32_bf16 v[66:69], v[198:201], v[230:233], v[66:69]
	s_setprio 0
	s_barrier
	s_add_i32 s56, s42, s30
	v_lshl_add_u64 v[148:149], s[28:29], 0, v[132:133]
	s_mov_b32 m0, s56
	ds_read_b128 v[202:205], v164 offset:16384
	ds_read_b128 v[206:209], v164 offset:17408
	ds_read_b128 v[210:213], v164 offset:18432
	ds_read_b128 v[214:217], v164 offset:19456
	ds_read_b128 v[218:221], v164 offset:20480
	ds_read_b128 v[222:225], v164 offset:21504
	ds_read_b128 v[226:229], v164 offset:22528
	ds_read_b128 v[230:233], v164 offset:23552
	global_load_lds_dwordx4 v[148:149], off
	s_add_i32 m0, s56, 0x2000
	s_add_u32 s56, s28, 0x40000
	v_lshl_add_u64 v[174:175], s[28:29], 0, v[136:137]
	s_addc_u32 s57, s29, 0
	s_add_i32 s58, s43, s30
	global_load_lds_dwordx4 v[174:175], off
	v_lshl_add_u64 v[234:235], s[56:57], 0, v[132:133]
	s_mov_b32 m0, s58
	v_lshl_add_u64 v[236:237], s[2:3], 0, v[134:135]
	global_load_lds_dwordx4 v[234:235], off
	v_lshl_add_u64 v[234:235], s[56:57], 0, v[136:137]
	s_add_i32 m0, s58, 0x2000
	s_nop 0
	global_load_lds_dwordx4 v[234:235], off
	v_lshl_add_u64 v[234:235], s[2:3], 0, v[130:131]
	s_mov_b32 m0, s34
	s_nop 0
	global_load_lds_dwordx4 v[234:235], off
	s_mov_b32 m0, s25
	s_nop 0
	global_load_lds_dwordx4 v[236:237], off
	s_waitcnt vmcnt(8)
	s_waitcnt lgkmcnt(0)
	s_barrier
	s_setprio 1
	s_waitcnt lgkmcnt(0)
	v_mfma_f32_16x16x32_bf16 v[62:65], v[166:169], v[202:205], 0
	v_mfma_f32_16x16x32_bf16 v[58:61], v[178:181], v[202:205], 0
	v_mfma_f32_16x16x32_bf16 v[46:49], v[166:169], v[210:213], 0
	v_mfma_f32_16x16x32_bf16 v[42:45], v[178:181], v[210:213], 0
	v_mfma_f32_16x16x32_bf16 v[30:33], v[166:169], v[218:221], 0
	v_mfma_f32_16x16x32_bf16 v[26:29], v[178:181], v[218:221], 0
	v_mfma_f32_16x16x32_bf16 v[14:17], v[166:169], v[226:229], 0
	v_mfma_f32_16x16x32_bf16 v[10:13], v[178:181], v[226:229], 0
	v_mfma_f32_16x16x32_bf16 v[62:65], v[170:173], v[206:209], v[62:65]
	v_mfma_f32_16x16x32_bf16 v[58:61], v[182:185], v[206:209], v[58:61]
	v_mfma_f32_16x16x32_bf16 v[46:49], v[170:173], v[214:217], v[46:49]
	v_mfma_f32_16x16x32_bf16 v[42:45], v[182:185], v[214:217], v[42:45]
	v_mfma_f32_16x16x32_bf16 v[30:33], v[170:173], v[222:225], v[30:33]
	v_mfma_f32_16x16x32_bf16 v[26:29], v[182:185], v[222:225], v[26:29]
	v_mfma_f32_16x16x32_bf16 v[14:17], v[170:173], v[230:233], v[14:17]
	v_mfma_f32_16x16x32_bf16 v[10:13], v[182:185], v[230:233], v[10:13]
	s_setprio 0
	s_setprio 1
	v_mfma_f32_16x16x32_bf16 v[54:57], v[186:189], v[202:205], 0
	v_mfma_f32_16x16x32_bf16 v[50:53], v[194:197], v[202:205], 0
	v_mfma_f32_16x16x32_bf16 v[38:41], v[186:189], v[210:213], 0
	v_mfma_f32_16x16x32_bf16 v[34:37], v[194:197], v[210:213], 0
	v_mfma_f32_16x16x32_bf16 v[22:25], v[186:189], v[218:221], 0
	v_mfma_f32_16x16x32_bf16 v[18:21], v[194:197], v[218:221], 0
	v_mfma_f32_16x16x32_bf16 v[6:9], v[186:189], v[226:229], 0
	v_mfma_f32_16x16x32_bf16 v[2:5], v[194:197], v[226:229], 0
	v_mfma_f32_16x16x32_bf16 v[54:57], v[190:193], v[206:209], v[54:57]
	v_mfma_f32_16x16x32_bf16 v[50:53], v[198:201], v[206:209], v[50:53]
	v_mfma_f32_16x16x32_bf16 v[38:41], v[190:193], v[214:217], v[38:41]
	v_mfma_f32_16x16x32_bf16 v[34:37], v[198:201], v[214:217], v[34:37]
	v_mfma_f32_16x16x32_bf16 v[22:25], v[190:193], v[222:225], v[22:25]
	v_mfma_f32_16x16x32_bf16 v[18:21], v[198:201], v[222:225], v[18:21]
	v_mfma_f32_16x16x32_bf16 v[6:9], v[190:193], v[230:233], v[6:9]
	v_mfma_f32_16x16x32_bf16 v[2:5], v[198:201], v[230:233], v[2:5]
	s_setprio 0
	s_barrier
	s_add_i32 s56, 0, 0x18000
	v_add_u32_e32 v165, s56, v162
	s_add_i32 s57, 0, 0x1c000
	ds_read_b128 v[166:169], v165
	ds_read_b128 v[170:173], v165 offset:1024
	ds_read_b128 v[178:181], v165 offset:2048
	ds_read_b128 v[182:185], v165 offset:3072
	v_add_u32_e32 v165, s57, v162
	ds_read_b128 v[186:189], v165
	ds_read_b128 v[190:193], v165 offset:1024
	ds_read_b128 v[194:197], v165 offset:2048
	ds_read_b128 v[198:201], v165 offset:3072
	s_add_u32 s2, s2, 0x40000
	s_addc_u32 s3, s3, 0
	s_mov_b32 m0, s35
	v_lshl_add_u64 v[238:239], s[2:3], 0, v[130:131]
	ds_read_b128 v[202:205], v164 offset:32768
	ds_read_b128 v[206:209], v164 offset:33792
	ds_read_b128 v[210:213], v164 offset:34816
	ds_read_b128 v[214:217], v164 offset:35840
	ds_read_b128 v[218:221], v164 offset:36864
	ds_read_b128 v[222:225], v164 offset:37888
	ds_read_b128 v[226:229], v164 offset:38912
	ds_read_b128 v[230:233], v164 offset:39936
	global_load_lds_dwordx4 v[238:239], off
	v_lshl_add_u64 v[238:239], s[2:3], 0, v[134:135]
	s_mov_b32 m0, s36
	s_nop 0
	global_load_lds_dwordx4 v[238:239], off
	s_waitcnt vmcnt(8)
	s_waitcnt lgkmcnt(0)
	s_barrier
	s_setprio 1
	s_waitcnt lgkmcnt(0)
	v_mfma_f32_16x16x32_bf16 v[126:129], v[166:169], v[202:205], v[126:129]
	v_mfma_f32_16x16x32_bf16 v[122:125], v[178:181], v[202:205], v[122:125]
	v_mfma_f32_16x16x32_bf16 v[110:113], v[166:169], v[210:213], v[110:113]
	v_mfma_f32_16x16x32_bf16 v[106:109], v[178:181], v[210:213], v[106:109]
	v_mfma_f32_16x16x32_bf16 v[94:97], v[166:169], v[218:221], v[94:97]
	v_mfma_f32_16x16x32_bf16 v[90:93], v[178:181], v[218:221], v[90:93]
	v_mfma_f32_16x16x32_bf16 v[78:81], v[166:169], v[226:229], v[78:81]
	v_mfma_f32_16x16x32_bf16 v[74:77], v[178:181], v[226:229], v[74:77]
	v_mfma_f32_16x16x32_bf16 v[126:129], v[170:173], v[206:209], v[126:129]
	v_mfma_f32_16x16x32_bf16 v[122:125], v[182:185], v[206:209], v[122:125]
	v_mfma_f32_16x16x32_bf16 v[110:113], v[170:173], v[214:217], v[110:113]
	v_mfma_f32_16x16x32_bf16 v[106:109], v[182:185], v[214:217], v[106:109]
	v_mfma_f32_16x16x32_bf16 v[94:97], v[170:173], v[222:225], v[94:97]
	v_mfma_f32_16x16x32_bf16 v[90:93], v[182:185], v[222:225], v[90:93]
	v_mfma_f32_16x16x32_bf16 v[78:81], v[170:173], v[230:233], v[78:81]
	v_mfma_f32_16x16x32_bf16 v[74:77], v[182:185], v[230:233], v[74:77]
	s_setprio 0
	s_setprio 1
	v_mfma_f32_16x16x32_bf16 v[118:121], v[186:189], v[202:205], v[118:121]
	v_mfma_f32_16x16x32_bf16 v[114:117], v[194:197], v[202:205], v[114:117]
	v_mfma_f32_16x16x32_bf16 v[102:105], v[186:189], v[210:213], v[102:105]
	v_mfma_f32_16x16x32_bf16 v[98:101], v[194:197], v[210:213], v[98:101]
	v_mfma_f32_16x16x32_bf16 v[86:89], v[186:189], v[218:221], v[86:89]
	v_mfma_f32_16x16x32_bf16 v[82:85], v[194:197], v[218:221], v[82:85]
	v_mfma_f32_16x16x32_bf16 v[70:73], v[186:189], v[226:229], v[70:73]
	v_mfma_f32_16x16x32_bf16 v[66:69], v[194:197], v[226:229], v[66:69]
	v_mfma_f32_16x16x32_bf16 v[118:121], v[190:193], v[206:209], v[118:121]
	v_mfma_f32_16x16x32_bf16 v[114:117], v[198:201], v[206:209], v[114:117]
	v_mfma_f32_16x16x32_bf16 v[102:105], v[190:193], v[214:217], v[102:105]
	v_mfma_f32_16x16x32_bf16 v[98:101], v[198:201], v[214:217], v[98:101]
	v_mfma_f32_16x16x32_bf16 v[86:89], v[190:193], v[222:225], v[86:89]
	v_mfma_f32_16x16x32_bf16 v[82:85], v[198:201], v[222:225], v[82:85]
	v_mfma_f32_16x16x32_bf16 v[70:73], v[190:193], v[230:233], v[70:73]
	v_mfma_f32_16x16x32_bf16 v[66:69], v[198:201], v[230:233], v[66:69]
	s_setprio 0
	s_barrier
	s_add_i32 s2, s56, s30
	v_lshl_add_u64 v[148:149], v[148:149], 0, s[6:7]
	s_mov_b32 m0, s2
	ds_read_b128 v[202:205], v164 offset:49152
	ds_read_b128 v[206:209], v164 offset:50176
	ds_read_b128 v[210:213], v164 offset:51200
	ds_read_b128 v[214:217], v164 offset:52224
	ds_read_b128 v[218:221], v164 offset:53248
	ds_read_b128 v[222:225], v164 offset:54272
	ds_read_b128 v[226:229], v164 offset:55296
	ds_read_b128 v[230:233], v164 offset:56320
	global_load_lds_dwordx4 v[148:149], off
	s_add_i32 m0, s2, 0x2000
	s_add_u32 s2, s28, 0x40080
	v_lshl_add_u64 v[148:149], v[174:175], 0, s[6:7]
	s_addc_u32 s3, s29, 0
	s_add_i32 s28, s57, s30
	global_load_lds_dwordx4 v[148:149], off
	v_lshl_add_u64 v[148:149], s[2:3], 0, v[132:133]
	s_mov_b32 m0, s28
	s_nop 0
	global_load_lds_dwordx4 v[148:149], off
	v_lshl_add_u64 v[148:149], s[2:3], 0, v[136:137]
	s_add_i32 m0, s28, 0x2000
	s_nop 0
	global_load_lds_dwordx4 v[148:149], off
	v_lshl_add_u64 v[148:149], v[234:235], 0, s[6:7]
	s_mov_b32 m0, s39
	s_nop 0
	global_load_lds_dwordx4 v[148:149], off
	v_lshl_add_u64 v[148:149], v[236:237], 0, s[6:7]
	s_mov_b32 m0, s40
	s_nop 0
	global_load_lds_dwordx4 v[148:149], off
	s_waitcnt vmcnt(8)
	s_waitcnt lgkmcnt(0)
	s_barrier
	s_setprio 1
	s_waitcnt lgkmcnt(0)
	v_mfma_f32_16x16x32_bf16 v[62:65], v[166:169], v[202:205], v[62:65]
	v_mfma_f32_16x16x32_bf16 v[58:61], v[178:181], v[202:205], v[58:61]
	v_mfma_f32_16x16x32_bf16 v[46:49], v[166:169], v[210:213], v[46:49]
	v_mfma_f32_16x16x32_bf16 v[42:45], v[178:181], v[210:213], v[42:45]
	v_mfma_f32_16x16x32_bf16 v[30:33], v[166:169], v[218:221], v[30:33]
	v_mfma_f32_16x16x32_bf16 v[26:29], v[178:181], v[218:221], v[26:29]
	v_mfma_f32_16x16x32_bf16 v[14:17], v[166:169], v[226:229], v[14:17]
	v_mfma_f32_16x16x32_bf16 v[10:13], v[178:181], v[226:229], v[10:13]
	v_mfma_f32_16x16x32_bf16 v[62:65], v[170:173], v[206:209], v[62:65]
	v_mfma_f32_16x16x32_bf16 v[58:61], v[182:185], v[206:209], v[58:61]
	v_mfma_f32_16x16x32_bf16 v[46:49], v[170:173], v[214:217], v[46:49]
	v_mfma_f32_16x16x32_bf16 v[42:45], v[182:185], v[214:217], v[42:45]
	v_mfma_f32_16x16x32_bf16 v[30:33], v[170:173], v[222:225], v[30:33]
	v_mfma_f32_16x16x32_bf16 v[26:29], v[182:185], v[222:225], v[26:29]
	v_mfma_f32_16x16x32_bf16 v[14:17], v[170:173], v[230:233], v[14:17]
	v_mfma_f32_16x16x32_bf16 v[10:13], v[182:185], v[230:233], v[10:13]
	s_setprio 0
	s_setprio 1
	v_mfma_f32_16x16x32_bf16 v[54:57], v[186:189], v[202:205], v[54:57]
	v_mfma_f32_16x16x32_bf16 v[50:53], v[194:197], v[202:205], v[50:53]
	v_mfma_f32_16x16x32_bf16 v[38:41], v[186:189], v[210:213], v[38:41]
	v_mfma_f32_16x16x32_bf16 v[34:37], v[194:197], v[210:213], v[34:37]
	v_mfma_f32_16x16x32_bf16 v[22:25], v[186:189], v[218:221], v[22:25]
	v_mfma_f32_16x16x32_bf16 v[18:21], v[194:197], v[218:221], v[18:21]
	v_mfma_f32_16x16x32_bf16 v[6:9], v[186:189], v[226:229], v[6:9]
	v_mfma_f32_16x16x32_bf16 v[2:5], v[194:197], v[226:229], v[2:5]
	v_mfma_f32_16x16x32_bf16 v[54:57], v[190:193], v[206:209], v[54:57]
	v_mfma_f32_16x16x32_bf16 v[50:53], v[198:201], v[206:209], v[50:53]
	v_mfma_f32_16x16x32_bf16 v[38:41], v[190:193], v[214:217], v[38:41]
	v_mfma_f32_16x16x32_bf16 v[34:37], v[198:201], v[214:217], v[34:37]
	v_mfma_f32_16x16x32_bf16 v[22:25], v[190:193], v[222:225], v[22:25]
	v_mfma_f32_16x16x32_bf16 v[18:21], v[198:201], v[222:225], v[18:21]
	v_mfma_f32_16x16x32_bf16 v[6:9], v[190:193], v[230:233], v[6:9]
	v_mfma_f32_16x16x32_bf16 v[2:5], v[198:201], v[230:233], v[2:5]
	s_setprio 0
	s_barrier
	s_add_i32 s55, s55, 2
	s_add_u32 s26, s26, 0x100
	s_addc_u32 s27, s27, 0
	s_add_u32 s53, s53, 0x100
	s_addc_u32 s54, s54, 0
	s_cmp_gt_u32 s55, 13
	s_cbranch_scc0 .LBB0_1303
	s_branch .Lpk1303_exit

.LBB0_1399:
	s_lshl_b64 s[2:3], s[14:15], 1
	v_readlane_b32 s20, v253, 52
	v_readlane_b32 s21, v253, 53
	s_add_u32 s20, s20, s2
	s_addc_u32 s21, s21, s3
	s_and_b64 s[2:3], s[18:19], exec
	s_cselect_b32 s11, s21, s29
	s_cselect_b32 s13, s20, s28
	s_lshl_b64 s[2:3], s[16:17], 1
	s_add_u32 s22, s48, s2
	s_addc_u32 s23, s49, s3
	s_and_b64 s[2:3], s[18:19], exec
	s_cselect_b32 s47, s23, s31
	s_cselect_b32 s52, s22, s30
	s_add_u32 s28, s28, 0x40080
	s_addc_u32 s29, s29, 0
	s_add_u32 s53, s30, 0x100
	s_addc_u32 s54, s31, 0
	s_mov_b32 s55, -2
.Lpk1400_peel:
	ds_read_b128 v[152:155], v1
	ds_read_b128 v[156:159], v1 offset:1024
	ds_read_b128 v[160:163], v1 offset:2048
	ds_read_b128 v[164:167], v1 offset:3072
	ds_read_b128 v[168:171], v149
	ds_read_b128 v[172:175], v149 offset:1024
	ds_read_b128 v[178:181], v149 offset:2048
	ds_read_b128 v[182:185], v149 offset:3072
	s_add_u32 s2, s28, 0xfffc0080
	s_addc_u32 s3, s29, -1
	s_cmp_eq_u32 s55, 12
	s_cselect_b32 s3, s11, s3
	s_cselect_b32 s2, s13, s2
	s_cselect_b32 s31, s47, s54
	s_cselect_b32 s30, s52, s53
	v_lshl_add_u64 v[146:147], s[28:29], 0, v[140:141]
	s_add_i32 m0, s25, 0xc000
	ds_read_b128 v[186:189], v150
	ds_read_b128 v[190:193], v150 offset:1024
	ds_read_b128 v[194:197], v150 offset:2048
	ds_read_b128 v[198:201], v150 offset:3072
	ds_read_b128 v[202:205], v150 offset:4096
	ds_read_b128 v[206:209], v150 offset:5120
	ds_read_b128 v[210:213], v150 offset:6144
	ds_read_b128 v[214:217], v150 offset:7168
	global_load_lds_dwordx4 v[146:147], off
	v_lshl_add_u64 v[146:147], s[28:29], 0, v[142:143]
	s_add_i32 m0, s25, 0xe000
	s_nop 0
	global_load_lds_dwordx4 v[146:147], off
	s_waitcnt vmcnt(8)
	s_waitcnt lgkmcnt(0)
	s_barrier
	s_setprio 1
	s_waitcnt lgkmcnt(0)
	v_mfma_f32_16x16x32_bf16 v[126:129], v[152:155], v[186:189], 0
	v_mfma_f32_16x16x32_bf16 v[122:125], v[160:163], v[186:189], 0
	v_mfma_f32_16x16x32_bf16 v[110:113], v[152:155], v[194:197], 0
	v_mfma_f32_16x16x32_bf16 v[106:109], v[160:163], v[194:197], 0
	v_mfma_f32_16x16x32_bf16 v[94:97], v[152:155], v[202:205], 0
	v_mfma_f32_16x16x32_bf16 v[90:93], v[160:163], v[202:205], 0
	v_mfma_f32_16x16x32_bf16 v[78:81], v[152:155], v[210:213], 0
	v_mfma_f32_16x16x32_bf16 v[74:77], v[160:163], v[210:213], 0
	v_mfma_f32_16x16x32_bf16 v[126:129], v[156:159], v[190:193], v[126:129]
	v_mfma_f32_16x16x32_bf16 v[122:125], v[164:167], v[190:193], v[122:125]
	v_mfma_f32_16x16x32_bf16 v[110:113], v[156:159], v[198:201], v[110:113]
	v_mfma_f32_16x16x32_bf16 v[106:109], v[164:167], v[198:201], v[106:109]
	v_mfma_f32_16x16x32_bf16 v[94:97], v[156:159], v[206:209], v[94:97]
	v_mfma_f32_16x16x32_bf16 v[90:93], v[164:167], v[206:209], v[90:93]
	v_mfma_f32_16x16x32_bf16 v[78:81], v[156:159], v[214:217], v[78:81]
	v_mfma_f32_16x16x32_bf16 v[74:77], v[164:167], v[214:217], v[74:77]
	s_setprio 0
	s_setprio 1
	v_mfma_f32_16x16x32_bf16 v[118:121], v[168:171], v[186:189], 0
	v_mfma_f32_16x16x32_bf16 v[114:117], v[178:181], v[186:189], 0
	v_mfma_f32_16x16x32_bf16 v[102:105], v[168:171], v[194:197], 0
	v_mfma_f32_16x16x32_bf16 v[98:101], v[178:181], v[194:197], 0
	v_mfma_f32_16x16x32_bf16 v[86:89], v[168:171], v[202:205], 0
	v_mfma_f32_16x16x32_bf16 v[82:85], v[178:181], v[202:205], 0
	v_mfma_f32_16x16x32_bf16 v[70:73], v[168:171], v[210:213], 0
	v_mfma_f32_16x16x32_bf16 v[66:69], v[178:181], v[210:213], 0
	v_mfma_f32_16x16x32_bf16 v[118:121], v[172:175], v[190:193], v[118:121]
	v_mfma_f32_16x16x32_bf16 v[114:117], v[182:185], v[190:193], v[114:117]
	v_mfma_f32_16x16x32_bf16 v[102:105], v[172:175], v[198:201], v[102:105]
	v_mfma_f32_16x16x32_bf16 v[98:101], v[182:185], v[198:201], v[98:101]
	v_mfma_f32_16x16x32_bf16 v[86:89], v[172:175], v[206:209], v[86:89]
	v_mfma_f32_16x16x32_bf16 v[82:85], v[182:185], v[206:209], v[82:85]
	v_mfma_f32_16x16x32_bf16 v[70:73], v[172:175], v[214:217], v[70:73]
	v_mfma_f32_16x16x32_bf16 v[66:69], v[182:185], v[214:217], v[66:69]
	s_setprio 0
	s_barrier
	s_add_i32 s56, s43, s34
	v_lshl_add_u64 v[146:147], s[30:31], 0, v[132:133]
	s_mov_b32 m0, s56
	ds_read_b128 v[186:189], v150 offset:16384
	ds_read_b128 v[190:193], v150 offset:17408
	ds_read_b128 v[194:197], v150 offset:18432
	ds_read_b128 v[198:201], v150 offset:19456
	ds_read_b128 v[202:205], v150 offset:20480
	ds_read_b128 v[206:209], v150 offset:21504
	ds_read_b128 v[210:213], v150 offset:22528
	ds_read_b128 v[214:217], v150 offset:23552
	global_load_lds_dwordx4 v[146:147], off
	s_add_i32 m0, s56, 0x2000
	s_add_u32 s56, s30, 0x40000
	v_lshl_add_u64 v[218:219], s[30:31], 0, v[136:137]
	s_addc_u32 s57, s31, 0
	s_add_i32 s58, s44, s34
	global_load_lds_dwordx4 v[218:219], off
	v_lshl_add_u64 v[220:221], s[56:57], 0, v[132:133]
	s_mov_b32 m0, s58
	v_lshl_add_u64 v[222:223], s[2:3], 0, v[134:135]
	global_load_lds_dwordx4 v[220:221], off
	v_lshl_add_u64 v[220:221], s[56:57], 0, v[136:137]
	s_add_i32 m0, s58, 0x2000
	s_nop 0
	global_load_lds_dwordx4 v[220:221], off
	v_lshl_add_u64 v[220:221], s[2:3], 0, v[130:131]
	s_mov_b32 m0, s25
	s_nop 0
	global_load_lds_dwordx4 v[220:221], off
	s_mov_b32 m0, s27
	s_nop 0
	global_load_lds_dwordx4 v[222:223], off
	s_waitcnt vmcnt(8)
	s_waitcnt lgkmcnt(0)
	s_barrier
	s_setprio 1
	s_waitcnt lgkmcnt(0)
	v_mfma_f32_16x16x32_bf16 v[62:65], v[152:155], v[186:189], 0
	v_mfma_f32_16x16x32_bf16 v[58:61], v[160:163], v[186:189], 0
	v_mfma_f32_16x16x32_bf16 v[46:49], v[152:155], v[194:197], 0
	v_mfma_f32_16x16x32_bf16 v[42:45], v[160:163], v[194:197], 0
	v_mfma_f32_16x16x32_bf16 v[30:33], v[152:155], v[202:205], 0
	v_mfma_f32_16x16x32_bf16 v[26:29], v[160:163], v[202:205], 0
	v_mfma_f32_16x16x32_bf16 v[14:17], v[152:155], v[210:213], 0
	v_mfma_f32_16x16x32_bf16 v[10:13], v[160:163], v[210:213], 0
	v_mfma_f32_16x16x32_bf16 v[62:65], v[156:159], v[190:193], v[62:65]
	v_mfma_f32_16x16x32_bf16 v[58:61], v[164:167], v[190:193], v[58:61]
	v_mfma_f32_16x16x32_bf16 v[46:49], v[156:159], v[198:201], v[46:49]
	v_mfma_f32_16x16x32_bf16 v[42:45], v[164:167], v[198:201], v[42:45]
	v_mfma_f32_16x16x32_bf16 v[30:33], v[156:159], v[206:209], v[30:33]
	v_mfma_f32_16x16x32_bf16 v[26:29], v[164:167], v[206:209], v[26:29]
	v_mfma_f32_16x16x32_bf16 v[14:17], v[156:159], v[214:217], v[14:17]
	v_mfma_f32_16x16x32_bf16 v[10:13], v[164:167], v[214:217], v[10:13]
	s_setprio 0
	s_setprio 1
	v_mfma_f32_16x16x32_bf16 v[54:57], v[168:171], v[186:189], 0
	v_mfma_f32_16x16x32_bf16 v[50:53], v[178:181], v[186:189], 0
	v_mfma_f32_16x16x32_bf16 v[38:41], v[168:171], v[194:197], 0
	v_mfma_f32_16x16x32_bf16 v[34:37], v[178:181], v[194:197], 0
	v_mfma_f32_16x16x32_bf16 v[22:25], v[168:171], v[202:205], 0
	v_mfma_f32_16x16x32_bf16 v[18:21], v[178:181], v[202:205], 0
	v_mfma_f32_16x16x32_bf16 v[6:9], v[168:171], v[210:213], 0
	v_mfma_f32_16x16x32_bf16 v[2:5], v[178:181], v[210:213], 0
	v_mfma_f32_16x16x32_bf16 v[54:57], v[172:175], v[190:193], v[54:57]
	v_mfma_f32_16x16x32_bf16 v[50:53], v[182:185], v[190:193], v[50:53]
	v_mfma_f32_16x16x32_bf16 v[38:41], v[172:175], v[198:201], v[38:41]
	v_mfma_f32_16x16x32_bf16 v[34:37], v[182:185], v[198:201], v[34:37]
	v_mfma_f32_16x16x32_bf16 v[22:25], v[172:175], v[206:209], v[22:25]
	v_mfma_f32_16x16x32_bf16 v[18:21], v[182:185], v[206:209], v[18:21]
	v_mfma_f32_16x16x32_bf16 v[6:9], v[172:175], v[214:217], v[6:9]
	v_mfma_f32_16x16x32_bf16 v[2:5], v[182:185], v[214:217], v[2:5]
	s_setprio 0
	s_barrier
	s_add_i32 s56, 0, 0x18000
	v_add_u32_e32 v151, s56, v148
	s_add_i32 s57, 0, 0x1c000
	ds_read_b128 v[152:155], v151
	ds_read_b128 v[156:159], v151 offset:1024
	ds_read_b128 v[160:163], v151 offset:2048
	ds_read_b128 v[164:167], v151 offset:3072
	v_add_u32_e32 v151, s57, v148
	ds_read_b128 v[168:171], v151
	ds_read_b128 v[172:175], v151 offset:1024
	ds_read_b128 v[178:181], v151 offset:2048
	ds_read_b128 v[182:185], v151 offset:3072
	s_add_u32 s2, s2, 0x40000
	s_addc_u32 s3, s3, 0
	s_mov_b32 m0, s36
	v_lshl_add_u64 v[224:225], s[2:3], 0, v[130:131]
	ds_read_b128 v[186:189], v150 offset:32768
	ds_read_b128 v[190:193], v150 offset:33792
	ds_read_b128 v[194:197], v150 offset:34816
	ds_read_b128 v[198:201], v150 offset:35840
	ds_read_b128 v[202:205], v150 offset:36864
	ds_read_b128 v[206:209], v150 offset:37888
	ds_read_b128 v[210:213], v150 offset:38912
	ds_read_b128 v[214:217], v150 offset:39936
	global_load_lds_dwordx4 v[224:225], off
	v_lshl_add_u64 v[224:225], s[2:3], 0, v[134:135]
	s_mov_b32 m0, s37
	s_nop 0
	global_load_lds_dwordx4 v[224:225], off
	s_waitcnt vmcnt(8)
	s_waitcnt lgkmcnt(0)
	s_barrier
	s_setprio 1
	s_waitcnt lgkmcnt(0)
	v_mfma_f32_16x16x32_bf16 v[126:129], v[152:155], v[186:189], v[126:129]
	v_mfma_f32_16x16x32_bf16 v[122:125], v[160:163], v[186:189], v[122:125]
	v_mfma_f32_16x16x32_bf16 v[110:113], v[152:155], v[194:197], v[110:113]
	v_mfma_f32_16x16x32_bf16 v[106:109], v[160:163], v[194:197], v[106:109]
	v_mfma_f32_16x16x32_bf16 v[94:97], v[152:155], v[202:205], v[94:97]
	v_mfma_f32_16x16x32_bf16 v[90:93], v[160:163], v[202:205], v[90:93]
	v_mfma_f32_16x16x32_bf16 v[78:81], v[152:155], v[210:213], v[78:81]
	v_mfma_f32_16x16x32_bf16 v[74:77], v[160:163], v[210:213], v[74:77]
	v_mfma_f32_16x16x32_bf16 v[126:129], v[156:159], v[190:193], v[126:129]
	v_mfma_f32_16x16x32_bf16 v[122:125], v[164:167], v[190:193], v[122:125]
	v_mfma_f32_16x16x32_bf16 v[110:113], v[156:159], v[198:201], v[110:113]
	v_mfma_f32_16x16x32_bf16 v[106:109], v[164:167], v[198:201], v[106:109]
	v_mfma_f32_16x16x32_bf16 v[94:97], v[156:159], v[206:209], v[94:97]
	v_mfma_f32_16x16x32_bf16 v[90:93], v[164:167], v[206:209], v[90:93]
	v_mfma_f32_16x16x32_bf16 v[78:81], v[156:159], v[214:217], v[78:81]
	v_mfma_f32_16x16x32_bf16 v[74:77], v[164:167], v[214:217], v[74:77]
	s_setprio 0
	s_setprio 1
	v_mfma_f32_16x16x32_bf16 v[118:121], v[168:171], v[186:189], v[118:121]
	v_mfma_f32_16x16x32_bf16 v[114:117], v[178:181], v[186:189], v[114:117]
	v_mfma_f32_16x16x32_bf16 v[102:105], v[168:171], v[194:197], v[102:105]
	v_mfma_f32_16x16x32_bf16 v[98:101], v[178:181], v[194:197], v[98:101]
	v_mfma_f32_16x16x32_bf16 v[86:89], v[168:171], v[202:205], v[86:89]
	v_mfma_f32_16x16x32_bf16 v[82:85], v[178:181], v[202:205], v[82:85]
	v_mfma_f32_16x16x32_bf16 v[70:73], v[168:171], v[210:213], v[70:73]
	v_mfma_f32_16x16x32_bf16 v[66:69], v[178:181], v[210:213], v[66:69]
	v_mfma_f32_16x16x32_bf16 v[118:121], v[172:175], v[190:193], v[118:121]
	v_mfma_f32_16x16x32_bf16 v[114:117], v[182:185], v[190:193], v[114:117]
	v_mfma_f32_16x16x32_bf16 v[102:105], v[172:175], v[198:201], v[102:105]
	v_mfma_f32_16x16x32_bf16 v[98:101], v[182:185], v[198:201], v[98:101]
	v_mfma_f32_16x16x32_bf16 v[86:89], v[172:175], v[206:209], v[86:89]
	v_mfma_f32_16x16x32_bf16 v[82:85], v[182:185], v[206:209], v[82:85]
	v_mfma_f32_16x16x32_bf16 v[70:73], v[172:175], v[214:217], v[70:73]
	v_mfma_f32_16x16x32_bf16 v[66:69], v[182:185], v[214:217], v[66:69]
	s_setprio 0
	s_barrier
	s_add_i32 s2, s56, s34
	v_lshl_add_u64 v[146:147], v[146:147], 0, s[6:7]
	s_mov_b32 m0, s2
	ds_read_b128 v[186:189], v150 offset:49152
	ds_read_b128 v[190:193], v150 offset:50176
	ds_read_b128 v[194:197], v150 offset:51200
	ds_read_b128 v[198:201], v150 offset:52224
	ds_read_b128 v[202:205], v150 offset:53248
	ds_read_b128 v[206:209], v150 offset:54272
	ds_read_b128 v[210:213], v150 offset:55296
	ds_read_b128 v[214:217], v150 offset:56320
	global_load_lds_dwordx4 v[146:147], off
	s_add_i32 m0, s2, 0x2000
	s_add_u32 s2, s30, 0x40080
	v_lshl_add_u64 v[146:147], v[218:219], 0, s[6:7]
	s_addc_u32 s3, s31, 0
	s_add_i32 s30, s57, s34
	global_load_lds_dwordx4 v[146:147], off
	v_lshl_add_u64 v[146:147], s[2:3], 0, v[132:133]
	s_mov_b32 m0, s30
	s_nop 0
	global_load_lds_dwordx4 v[146:147], off
	v_lshl_add_u64 v[146:147], s[2:3], 0, v[136:137]
	s_add_i32 m0, s30, 0x2000
	s_nop 0
	global_load_lds_dwordx4 v[146:147], off
	v_lshl_add_u64 v[146:147], v[220:221], 0, s[6:7]
	s_mov_b32 m0, s40
	s_nop 0
	global_load_lds_dwordx4 v[146:147], off
	v_lshl_add_u64 v[146:147], v[222:223], 0, s[6:7]
	s_mov_b32 m0, s41
	s_nop 0
	global_load_lds_dwordx4 v[146:147], off
	s_waitcnt vmcnt(8)
	s_waitcnt lgkmcnt(0)
	s_barrier
	s_setprio 1
	s_waitcnt lgkmcnt(0)
	v_mfma_f32_16x16x32_bf16 v[62:65], v[152:155], v[186:189], v[62:65]
	v_mfma_f32_16x16x32_bf16 v[58:61], v[160:163], v[186:189], v[58:61]
	v_mfma_f32_16x16x32_bf16 v[46:49], v[152:155], v[194:197], v[46:49]
	v_mfma_f32_16x16x32_bf16 v[42:45], v[160:163], v[194:197], v[42:45]
	v_mfma_f32_16x16x32_bf16 v[30:33], v[152:155], v[202:205], v[30:33]
	v_mfma_f32_16x16x32_bf16 v[26:29], v[160:163], v[202:205], v[26:29]
	v_mfma_f32_16x16x32_bf16 v[14:17], v[152:155], v[210:213], v[14:17]
	v_mfma_f32_16x16x32_bf16 v[10:13], v[160:163], v[210:213], v[10:13]
	v_mfma_f32_16x16x32_bf16 v[62:65], v[156:159], v[190:193], v[62:65]
	v_mfma_f32_16x16x32_bf16 v[58:61], v[164:167], v[190:193], v[58:61]
	v_mfma_f32_16x16x32_bf16 v[46:49], v[156:159], v[198:201], v[46:49]
	v_mfma_f32_16x16x32_bf16 v[42:45], v[164:167], v[198:201], v[42:45]
	v_mfma_f32_16x16x32_bf16 v[30:33], v[156:159], v[206:209], v[30:33]
	v_mfma_f32_16x16x32_bf16 v[26:29], v[164:167], v[206:209], v[26:29]
	v_mfma_f32_16x16x32_bf16 v[14:17], v[156:159], v[214:217], v[14:17]
	v_mfma_f32_16x16x32_bf16 v[10:13], v[164:167], v[214:217], v[10:13]
	s_setprio 0
	s_setprio 1
	v_mfma_f32_16x16x32_bf16 v[54:57], v[168:171], v[186:189], v[54:57]
	v_mfma_f32_16x16x32_bf16 v[50:53], v[178:181], v[186:189], v[50:53]
	v_mfma_f32_16x16x32_bf16 v[38:41], v[168:171], v[194:197], v[38:41]
	v_mfma_f32_16x16x32_bf16 v[34:37], v[178:181], v[194:197], v[34:37]
	v_mfma_f32_16x16x32_bf16 v[22:25], v[168:171], v[202:205], v[22:25]
	v_mfma_f32_16x16x32_bf16 v[18:21], v[178:181], v[202:205], v[18:21]
	v_mfma_f32_16x16x32_bf16 v[6:9], v[168:171], v[210:213], v[6:9]
	v_mfma_f32_16x16x32_bf16 v[2:5], v[178:181], v[210:213], v[2:5]
	v_mfma_f32_16x16x32_bf16 v[54:57], v[172:175], v[190:193], v[54:57]
	v_mfma_f32_16x16x32_bf16 v[50:53], v[182:185], v[190:193], v[50:53]
	v_mfma_f32_16x16x32_bf16 v[38:41], v[172:175], v[198:201], v[38:41]
	v_mfma_f32_16x16x32_bf16 v[34:37], v[182:185], v[198:201], v[34:37]
	v_mfma_f32_16x16x32_bf16 v[22:25], v[172:175], v[206:209], v[22:25]
	v_mfma_f32_16x16x32_bf16 v[18:21], v[182:185], v[206:209], v[18:21]
	v_mfma_f32_16x16x32_bf16 v[6:9], v[172:175], v[214:217], v[6:9]
	v_mfma_f32_16x16x32_bf16 v[2:5], v[182:185], v[214:217], v[2:5]
	s_setprio 0
	s_barrier
	s_add_i32 s55, s55, 2
	s_add_u32 s28, s28, 0x100
	s_addc_u32 s29, s29, 0
	s_add_u32 s53, s53, 0x100
	s_addc_u32 s54, s54, 0
	s_cmp_gt_u32 s55, 13
	s_cbranch_scc0 .LBB0_1400
	s_branch .Lpk1400_exit

.LBB0_1443:
	s_lshl_b64 s[2:3], s[16:17], 1
	v_readlane_b32 s22, v253, 54
	s_add_u32 s22, s22, s2
	v_readlane_b32 s2, v253, 7
	s_addc_u32 s23, s2, s3
	s_and_b64 s[2:3], s[20:21], exec
	s_cselect_b32 s56, s23, s27
	s_cselect_b32 s57, s22, s26
	s_lshl_b64 s[2:3], s[18:19], 1
	s_add_u32 s24, s36, s2
	s_addc_u32 s25, s37, s3
	s_and_b64 s[2:3], s[20:21], exec
	s_cselect_b32 s58, s25, s29
	s_cselect_b32 s59, s24, s28
	s_add_u32 s26, s26, 0xc000
	s_addc_u32 s27, s27, 0
	s_add_u32 s60, s28, 0x10000
	s_addc_u32 s61, s29, 0
	s_mov_b32 s62, -2
.Lpk1444_peel:
	ds_read_b128 v[152:155], v148
	ds_read_b128 v[156:159], v148 offset:1024
	ds_read_b128 v[160:163], v148 offset:2048
	ds_read_b128 v[164:167], v148 offset:3072
	ds_read_b128 v[168:171], v149
	ds_read_b128 v[172:175], v149 offset:1024
	ds_read_b128 v[178:181], v149 offset:2048
	ds_read_b128 v[182:185], v149 offset:3072
	s_add_u32 s2, s26, 0x4000
	s_addc_u32 s3, s27, 0
	s_cmp_eq_u32 s62, 40
	s_cselect_b32 s2, s57, s2
	s_cselect_b32 s3, s56, s3
	s_cselect_b32 s31, s58, s61
	s_cselect_b32 s30, s59, s60
	s_add_u32 s28, s2, 0x8000
	s_addc_u32 s29, s3, 0
	v_lshl_add_u64 v[144:145], s[26:27], 0, v[138:139]
	s_add_i32 m0, s39, 0xc000
	ds_read_b128 v[186:189], v150
	ds_read_b128 v[190:193], v150 offset:1024
	ds_read_b128 v[194:197], v150 offset:2048
	ds_read_b128 v[198:201], v150 offset:3072
	ds_read_b128 v[202:205], v150 offset:4096
	ds_read_b128 v[206:209], v150 offset:5120
	ds_read_b128 v[210:213], v150 offset:6144
	ds_read_b128 v[214:217], v150 offset:7168
	global_load_lds_dwordx4 v[144:145], off
	v_lshl_add_u64 v[144:145], s[26:27], 0, v[140:141]
	s_add_i32 m0, s39, 0xe000
	s_nop 0
	global_load_lds_dwordx4 v[144:145], off
	s_waitcnt vmcnt(8)
	s_waitcnt lgkmcnt(0)
	s_barrier
	s_setprio 1
	s_waitcnt lgkmcnt(0)
	v_mfma_f32_16x16x32_bf16 v[126:129], v[152:155], v[186:189], 0
	v_mfma_f32_16x16x32_bf16 v[122:125], v[160:163], v[186:189], 0
	v_mfma_f32_16x16x32_bf16 v[114:117], v[152:155], v[194:197], 0
	v_mfma_f32_16x16x32_bf16 v[106:109], v[160:163], v[194:197], 0
	v_mfma_f32_16x16x32_bf16 v[98:101], v[152:155], v[202:205], 0
	v_mfma_f32_16x16x32_bf16 v[90:93], v[160:163], v[202:205], 0
	v_mfma_f32_16x16x32_bf16 v[82:85], v[152:155], v[210:213], 0
	v_mfma_f32_16x16x32_bf16 v[74:77], v[160:163], v[210:213], 0
	v_mfma_f32_16x16x32_bf16 v[126:129], v[156:159], v[190:193], v[126:129]
	v_mfma_f32_16x16x32_bf16 v[122:125], v[164:167], v[190:193], v[122:125]
	v_mfma_f32_16x16x32_bf16 v[114:117], v[156:159], v[198:201], v[114:117]
	v_mfma_f32_16x16x32_bf16 v[106:109], v[164:167], v[198:201], v[106:109]
	v_mfma_f32_16x16x32_bf16 v[98:101], v[156:159], v[206:209], v[98:101]
	v_mfma_f32_16x16x32_bf16 v[90:93], v[164:167], v[206:209], v[90:93]
	v_mfma_f32_16x16x32_bf16 v[82:85], v[156:159], v[214:217], v[82:85]
	v_mfma_f32_16x16x32_bf16 v[74:77], v[164:167], v[214:217], v[74:77]
	s_setprio 0
	s_setprio 1
	v_mfma_f32_16x16x32_bf16 v[118:121], v[168:171], v[186:189], 0
	v_mfma_f32_16x16x32_bf16 v[110:113], v[178:181], v[186:189], 0
	v_mfma_f32_16x16x32_bf16 v[102:105], v[168:171], v[194:197], 0
	v_mfma_f32_16x16x32_bf16 v[94:97], v[178:181], v[194:197], 0
	v_mfma_f32_16x16x32_bf16 v[86:89], v[168:171], v[202:205], 0
	v_mfma_f32_16x16x32_bf16 v[78:81], v[178:181], v[202:205], 0
	v_mfma_f32_16x16x32_bf16 v[70:73], v[168:171], v[210:213], 0
	v_mfma_f32_16x16x32_bf16 v[66:69], v[178:181], v[210:213], 0
	v_mfma_f32_16x16x32_bf16 v[118:121], v[172:175], v[190:193], v[118:121]
	v_mfma_f32_16x16x32_bf16 v[110:113], v[182:185], v[190:193], v[110:113]
	v_mfma_f32_16x16x32_bf16 v[102:105], v[172:175], v[198:201], v[102:105]
	v_mfma_f32_16x16x32_bf16 v[94:97], v[182:185], v[198:201], v[94:97]
	v_mfma_f32_16x16x32_bf16 v[86:89], v[172:175], v[206:209], v[86:89]
	v_mfma_f32_16x16x32_bf16 v[78:81], v[182:185], v[206:209], v[78:81]
	v_mfma_f32_16x16x32_bf16 v[70:73], v[172:175], v[214:217], v[70:73]
	v_mfma_f32_16x16x32_bf16 v[66:69], v[182:185], v[214:217], v[66:69]
	s_setprio 0
	s_barrier
	s_add_i32 s63, s46, s38
	v_lshl_add_u64 v[144:145], s[30:31], 0, v[132:133]
	s_mov_b32 m0, s63
	ds_read_b128 v[186:189], v150 offset:16384
	ds_read_b128 v[190:193], v150 offset:17408
	ds_read_b128 v[194:197], v150 offset:18432
	ds_read_b128 v[198:201], v150 offset:19456
	ds_read_b128 v[202:205], v150 offset:20480
	ds_read_b128 v[206:209], v150 offset:21504
	ds_read_b128 v[210:213], v150 offset:22528
	ds_read_b128 v[214:217], v150 offset:23552
	global_load_lds_dwordx4 v[144:145], off
	s_add_i32 m0, s63, 0x2000
	s_add_u32 s64, s30, 0x4000
	v_lshl_add_u64 v[144:145], s[30:31], 0, v[136:137]
	s_addc_u32 s65, s31, 0
	s_add_i32 s63, s47, s38
	global_load_lds_dwordx4 v[144:145], off
	v_lshl_add_u64 v[144:145], s[64:65], 0, v[132:133]
	s_mov_b32 m0, s63
	s_nop 0
	global_load_lds_dwordx4 v[144:145], off
	v_lshl_add_u64 v[144:145], s[64:65], 0, v[136:137]
	s_add_i32 m0, s63, 0x2000
	s_nop 0
	global_load_lds_dwordx4 v[144:145], off
	v_lshl_add_u64 v[144:145], s[2:3], 0, v[130:131]
	s_mov_b32 m0, s39
	s_nop 0
	global_load_lds_dwordx4 v[144:145], off
	v_lshl_add_u64 v[144:145], s[2:3], 0, v[134:135]
	s_mov_b32 m0, s40
	s_nop 0
	global_load_lds_dwordx4 v[144:145], off
	s_waitcnt vmcnt(8)
	s_waitcnt lgkmcnt(0)
	s_barrier
	s_setprio 1
	s_waitcnt lgkmcnt(0)
	v_mfma_f32_16x16x32_bf16 v[62:65], v[152:155], v[186:189], 0
	v_mfma_f32_16x16x32_bf16 v[58:61], v[160:163], v[186:189], 0
	v_mfma_f32_16x16x32_bf16 v[50:53], v[152:155], v[194:197], 0
	v_mfma_f32_16x16x32_bf16 v[42:45], v[160:163], v[194:197], 0
	v_mfma_f32_16x16x32_bf16 v[34:37], v[152:155], v[202:205], 0
	v_mfma_f32_16x16x32_bf16 v[26:29], v[160:163], v[202:205], 0
	v_mfma_f32_16x16x32_bf16 v[18:21], v[152:155], v[210:213], 0
	v_mfma_f32_16x16x32_bf16 v[10:13], v[160:163], v[210:213], 0
	v_mfma_f32_16x16x32_bf16 v[62:65], v[156:159], v[190:193], v[62:65]
	v_mfma_f32_16x16x32_bf16 v[58:61], v[164:167], v[190:193], v[58:61]
	v_mfma_f32_16x16x32_bf16 v[50:53], v[156:159], v[198:201], v[50:53]
	v_mfma_f32_16x16x32_bf16 v[42:45], v[164:167], v[198:201], v[42:45]
	v_mfma_f32_16x16x32_bf16 v[34:37], v[156:159], v[206:209], v[34:37]
	v_mfma_f32_16x16x32_bf16 v[26:29], v[164:167], v[206:209], v[26:29]
	v_mfma_f32_16x16x32_bf16 v[18:21], v[156:159], v[214:217], v[18:21]
	v_mfma_f32_16x16x32_bf16 v[10:13], v[164:167], v[214:217], v[10:13]
	s_setprio 0
	s_setprio 1
	v_mfma_f32_16x16x32_bf16 v[54:57], v[168:171], v[186:189], 0
	v_mfma_f32_16x16x32_bf16 v[46:49], v[178:181], v[186:189], 0
	v_mfma_f32_16x16x32_bf16 v[38:41], v[168:171], v[194:197], 0
	v_mfma_f32_16x16x32_bf16 v[30:33], v[178:181], v[194:197], 0
	v_mfma_f32_16x16x32_bf16 v[22:25], v[168:171], v[202:205], 0
	v_mfma_f32_16x16x32_bf16 v[14:17], v[178:181], v[202:205], 0
	v_mfma_f32_16x16x32_bf16 v[6:9], v[168:171], v[210:213], 0
	v_mfma_f32_16x16x32_bf16 v[2:5], v[178:181], v[210:213], 0
	v_mfma_f32_16x16x32_bf16 v[54:57], v[172:175], v[190:193], v[54:57]
	v_mfma_f32_16x16x32_bf16 v[46:49], v[182:185], v[190:193], v[46:49]
	v_mfma_f32_16x16x32_bf16 v[38:41], v[172:175], v[198:201], v[38:41]
	v_mfma_f32_16x16x32_bf16 v[30:33], v[182:185], v[198:201], v[30:33]
	v_mfma_f32_16x16x32_bf16 v[22:25], v[172:175], v[206:209], v[22:25]
	v_mfma_f32_16x16x32_bf16 v[14:17], v[182:185], v[206:209], v[14:17]
	v_mfma_f32_16x16x32_bf16 v[6:9], v[172:175], v[214:217], v[6:9]
	v_mfma_f32_16x16x32_bf16 v[2:5], v[182:185], v[214:217], v[2:5]
	s_setprio 0
	s_barrier
	s_add_i32 s63, 0, 0x18000
	v_add_u32_e32 v144, s63, v146
	s_add_i32 s64, 0, 0x1c000
	ds_read_b128 v[152:155], v144
	ds_read_b128 v[156:159], v144 offset:1024
	ds_read_b128 v[160:163], v144 offset:2048
	ds_read_b128 v[164:167], v144 offset:3072
	v_add_u32_e32 v144, s64, v146
	ds_read_b128 v[168:171], v144
	ds_read_b128 v[172:175], v144 offset:1024
	ds_read_b128 v[178:181], v144 offset:2048
	ds_read_b128 v[182:185], v144 offset:3072
	s_add_u32 s2, s2, 0x4000
	s_addc_u32 s3, s3, 0
	s_mov_b32 m0, s41
	v_lshl_add_u64 v[144:145], s[2:3], 0, v[130:131]
	ds_read_b128 v[186:189], v150 offset:32768
	ds_read_b128 v[190:193], v150 offset:33792
	ds_read_b128 v[194:197], v150 offset:34816
	ds_read_b128 v[198:201], v150 offset:35840
	ds_read_b128 v[202:205], v150 offset:36864
	ds_read_b128 v[206:209], v150 offset:37888
	ds_read_b128 v[210:213], v150 offset:38912
	ds_read_b128 v[214:217], v150 offset:39936
	global_load_lds_dwordx4 v[144:145], off
	v_lshl_add_u64 v[144:145], s[2:3], 0, v[134:135]
	s_mov_b32 m0, s42
	s_nop 0
	global_load_lds_dwordx4 v[144:145], off
	s_waitcnt vmcnt(8)
	s_waitcnt lgkmcnt(0)
	s_barrier
	s_setprio 1
	s_waitcnt lgkmcnt(0)
	v_mfma_f32_16x16x32_bf16 v[126:129], v[152:155], v[186:189], v[126:129]
	v_mfma_f32_16x16x32_bf16 v[122:125], v[160:163], v[186:189], v[122:125]
	v_mfma_f32_16x16x32_bf16 v[114:117], v[152:155], v[194:197], v[114:117]
	v_mfma_f32_16x16x32_bf16 v[106:109], v[160:163], v[194:197], v[106:109]
	v_mfma_f32_16x16x32_bf16 v[98:101], v[152:155], v[202:205], v[98:101]
	v_mfma_f32_16x16x32_bf16 v[90:93], v[160:163], v[202:205], v[90:93]
	v_mfma_f32_16x16x32_bf16 v[82:85], v[152:155], v[210:213], v[82:85]
	v_mfma_f32_16x16x32_bf16 v[74:77], v[160:163], v[210:213], v[74:77]
	v_mfma_f32_16x16x32_bf16 v[126:129], v[156:159], v[190:193], v[126:129]
	v_mfma_f32_16x16x32_bf16 v[122:125], v[164:167], v[190:193], v[122:125]
	v_mfma_f32_16x16x32_bf16 v[114:117], v[156:159], v[198:201], v[114:117]
	v_mfma_f32_16x16x32_bf16 v[106:109], v[164:167], v[198:201], v[106:109]
	v_mfma_f32_16x16x32_bf16 v[98:101], v[156:159], v[206:209], v[98:101]
	v_mfma_f32_16x16x32_bf16 v[90:93], v[164:167], v[206:209], v[90:93]
	v_mfma_f32_16x16x32_bf16 v[82:85], v[156:159], v[214:217], v[82:85]
	v_mfma_f32_16x16x32_bf16 v[74:77], v[164:167], v[214:217], v[74:77]
	s_setprio 0
	s_setprio 1
	v_mfma_f32_16x16x32_bf16 v[118:121], v[168:171], v[186:189], v[118:121]
	v_mfma_f32_16x16x32_bf16 v[110:113], v[178:181], v[186:189], v[110:113]
	v_mfma_f32_16x16x32_bf16 v[102:105], v[168:171], v[194:197], v[102:105]
	v_mfma_f32_16x16x32_bf16 v[94:97], v[178:181], v[194:197], v[94:97]
	v_mfma_f32_16x16x32_bf16 v[86:89], v[168:171], v[202:205], v[86:89]
	v_mfma_f32_16x16x32_bf16 v[78:81], v[178:181], v[202:205], v[78:81]
	v_mfma_f32_16x16x32_bf16 v[70:73], v[168:171], v[210:213], v[70:73]
	v_mfma_f32_16x16x32_bf16 v[66:69], v[178:181], v[210:213], v[66:69]
	v_mfma_f32_16x16x32_bf16 v[118:121], v[172:175], v[190:193], v[118:121]
	v_mfma_f32_16x16x32_bf16 v[110:113], v[182:185], v[190:193], v[110:113]
	v_mfma_f32_16x16x32_bf16 v[102:105], v[172:175], v[198:201], v[102:105]
	v_mfma_f32_16x16x32_bf16 v[94:97], v[182:185], v[198:201], v[94:97]
	v_mfma_f32_16x16x32_bf16 v[86:89], v[172:175], v[206:209], v[86:89]
	v_mfma_f32_16x16x32_bf16 v[78:81], v[182:185], v[206:209], v[78:81]
	v_mfma_f32_16x16x32_bf16 v[70:73], v[172:175], v[214:217], v[70:73]
	v_mfma_f32_16x16x32_bf16 v[66:69], v[182:185], v[214:217], v[66:69]
	s_setprio 0
	s_barrier
	s_add_u32 s2, s30, 0x8000
	s_addc_u32 s3, s31, 0
	s_add_i32 s63, s63, s38
	v_lshl_add_u64 v[144:145], s[2:3], 0, v[132:133]
	s_mov_b32 m0, s63
	ds_read_b128 v[186:189], v150 offset:49152
	ds_read_b128 v[190:193], v150 offset:50176
	ds_read_b128 v[194:197], v150 offset:51200
	ds_read_b128 v[198:201], v150 offset:52224
	ds_read_b128 v[202:205], v150 offset:53248
	ds_read_b128 v[206:209], v150 offset:54272
	ds_read_b128 v[210:213], v150 offset:55296
	ds_read_b128 v[214:217], v150 offset:56320
	global_load_lds_dwordx4 v[144:145], off
	s_add_i32 m0, s63, 0x2000
	v_lshl_add_u64 v[144:145], s[2:3], 0, v[136:137]
	s_add_u32 s2, s30, 0xc000
	s_addc_u32 s3, s31, 0
	s_add_i32 s30, s64, s38
	global_load_lds_dwordx4 v[144:145], off
	v_lshl_add_u64 v[144:145], s[2:3], 0, v[132:133]
	s_mov_b32 m0, s30
	s_nop 0
	global_load_lds_dwordx4 v[144:145], off
	v_lshl_add_u64 v[144:145], s[2:3], 0, v[136:137]
	s_add_i32 m0, s30, 0x2000
	s_nop 0
	global_load_lds_dwordx4 v[144:145], off
	v_lshl_add_u64 v[144:145], s[28:29], 0, v[130:131]
	s_mov_b32 m0, s44
	s_nop 0
	global_load_lds_dwordx4 v[144:145], off
	v_lshl_add_u64 v[144:145], s[28:29], 0, v[134:135]
	s_mov_b32 m0, s45
	s_nop 0
	global_load_lds_dwordx4 v[144:145], off
	s_waitcnt vmcnt(8)
	s_waitcnt lgkmcnt(0)
	s_barrier
	s_setprio 1
	s_waitcnt lgkmcnt(0)
	v_mfma_f32_16x16x32_bf16 v[62:65], v[152:155], v[186:189], v[62:65]
	v_mfma_f32_16x16x32_bf16 v[58:61], v[160:163], v[186:189], v[58:61]
	v_mfma_f32_16x16x32_bf16 v[50:53], v[152:155], v[194:197], v[50:53]
	v_mfma_f32_16x16x32_bf16 v[42:45], v[160:163], v[194:197], v[42:45]
	v_mfma_f32_16x16x32_bf16 v[34:37], v[152:155], v[202:205], v[34:37]
	v_mfma_f32_16x16x32_bf16 v[26:29], v[160:163], v[202:205], v[26:29]
	v_mfma_f32_16x16x32_bf16 v[18:21], v[152:155], v[210:213], v[18:21]
	v_mfma_f32_16x16x32_bf16 v[10:13], v[160:163], v[210:213], v[10:13]
	v_mfma_f32_16x16x32_bf16 v[62:65], v[156:159], v[190:193], v[62:65]
	v_mfma_f32_16x16x32_bf16 v[58:61], v[164:167], v[190:193], v[58:61]
	v_mfma_f32_16x16x32_bf16 v[50:53], v[156:159], v[198:201], v[50:53]
	v_mfma_f32_16x16x32_bf16 v[42:45], v[164:167], v[198:201], v[42:45]
	v_mfma_f32_16x16x32_bf16 v[34:37], v[156:159], v[206:209], v[34:37]
	v_mfma_f32_16x16x32_bf16 v[26:29], v[164:167], v[206:209], v[26:29]
	v_mfma_f32_16x16x32_bf16 v[18:21], v[156:159], v[214:217], v[18:21]
	v_mfma_f32_16x16x32_bf16 v[10:13], v[164:167], v[214:217], v[10:13]
	s_setprio 0
	s_setprio 1
	v_mfma_f32_16x16x32_bf16 v[54:57], v[168:171], v[186:189], v[54:57]
	v_mfma_f32_16x16x32_bf16 v[46:49], v[178:181], v[186:189], v[46:49]
	v_mfma_f32_16x16x32_bf16 v[38:41], v[168:171], v[194:197], v[38:41]
	v_mfma_f32_16x16x32_bf16 v[30:33], v[178:181], v[194:197], v[30:33]
	v_mfma_f32_16x16x32_bf16 v[22:25], v[168:171], v[202:205], v[22:25]
	v_mfma_f32_16x16x32_bf16 v[14:17], v[178:181], v[202:205], v[14:17]
	v_mfma_f32_16x16x32_bf16 v[6:9], v[168:171], v[210:213], v[6:9]
	v_mfma_f32_16x16x32_bf16 v[2:5], v[178:181], v[210:213], v[2:5]
	v_mfma_f32_16x16x32_bf16 v[54:57], v[172:175], v[190:193], v[54:57]
	v_mfma_f32_16x16x32_bf16 v[46:49], v[182:185], v[190:193], v[46:49]
	v_mfma_f32_16x16x32_bf16 v[38:41], v[172:175], v[198:201], v[38:41]
	v_mfma_f32_16x16x32_bf16 v[30:33], v[182:185], v[198:201], v[30:33]
	v_mfma_f32_16x16x32_bf16 v[22:25], v[172:175], v[206:209], v[22:25]
	v_mfma_f32_16x16x32_bf16 v[14:17], v[182:185], v[206:209], v[14:17]
	v_mfma_f32_16x16x32_bf16 v[6:9], v[172:175], v[214:217], v[6:9]
	v_mfma_f32_16x16x32_bf16 v[2:5], v[182:185], v[214:217], v[2:5]
	s_setprio 0
	s_barrier
	s_add_i32 s62, s62, 2
	s_add_u32 s26, s26, 0x10000
	s_addc_u32 s27, s27, 0
	s_add_u32 s60, s60, 0x10000
	s_addc_u32 s61, s61, 0
	s_cmp_gt_u32 s62, 41
	s_cbranch_scc0 .LBB0_1444
	s_branch .Lpk1444_exit
